# GEMM K-loops: LDS-DMA with scalar base + per-lane 32-bit offsets (no per-step VALU address math; 16 VALU fewer per K-step per wave)
# speedup vs baseline: 1.0079x; 1.0079x over previous
.LBB0_303:
	s_mul_hi_i32 s5, s68, 0x2aaaaaab
	s_lshr_b32 s2, s5, 31
	s_add_i32 s5, s5, s2
	s_lshl_b32 s69, s5, 8
	s_waitcnt lgkmcnt(0)
	v_add_u32_e32 v0, s69, v189
	v_min_i32_e32 v0, 0x7fff, v0
	v_ashrrev_i32_e32 v1, 31, v0
	v_lshlrev_b64 v[0:1], 11, v[0:1]
	s_mul_i32 s2, s5, 0x600
	v_lshl_add_u64 v[172:173], v[168:169], 0, v[0:1]
	v_subrev_u32_e32 v0, s2, v200
	v_ashrrev_i32_e32 v1, 31, v0
	v_lshlrev_b64 v[0:1], 11, v[0:1]
	v_lshl_add_u64 v[180:181], v[170:171], 0, v[0:1]
	v_subrev_u32_e32 v0, s2, v201
	v_ashrrev_i32_e32 v1, 31, v0
	v_lshlrev_b64 v[0:1], 11, v[0:1]
	v_lshl_add_u64 v[182:183], v[170:171], 0, v[0:1]
	v_subrev_u32_e32 v0, s2, v202
	v_ashrrev_i32_e32 v1, 31, v0
	v_add_u32_e32 v2, s69, v190
	v_add_u32_e32 v4, s69, v163
	v_add_u32_e32 v6, s69, v192
	v_lshlrev_b64 v[0:1], 11, v[0:1]
	v_min_i32_e32 v2, 0x7fff, v2
	v_min_i32_e32 v4, 0x7fff, v4
	v_min_i32_e32 v6, 0x7fff, v6
	v_lshl_add_u64 v[184:185], v[170:171], 0, v[0:1]
	v_subrev_u32_e32 v0, s2, v203
	v_ashrrev_i32_e32 v3, 31, v2
	v_ashrrev_i32_e32 v5, 31, v4
	v_ashrrev_i32_e32 v7, 31, v6
	v_ashrrev_i32_e32 v1, 31, v0
	v_lshlrev_b64 v[2:3], 11, v[2:3]
	v_lshlrev_b64 v[4:5], 11, v[4:5]
	v_lshlrev_b64 v[6:7], 11, v[6:7]
	v_lshlrev_b64 v[0:1], 11, v[0:1]
	s_mov_b32 s4, s68
	v_lshl_add_u64 v[174:175], v[168:169], 0, v[2:3]
	v_lshl_add_u64 v[176:177], v[168:169], 0, v[4:5]
	v_lshl_add_u64 v[178:179], v[168:169], 0, v[6:7]
	v_lshl_add_u64 v[186:187], v[170:171], 0, v[0:1]
	s_mov_b64 s[2:3], 0
	s_mov_b32 s6, s25
	v_mov_b32_e32 v0, v161
	v_mov_b32_e32 v1, v161
	v_mov_b32_e32 v2, v161
	v_mov_b32_e32 v3, v161
	v_mov_b32_e32 v4, v161
	v_mov_b32_e32 v5, v161
	v_mov_b32_e32 v6, v161
	v_mov_b32_e32 v7, v161
	v_mov_b32_e32 v8, v161
	v_mov_b32_e32 v9, v161
	v_mov_b32_e32 v10, v161
	v_mov_b32_e32 v11, v161
	v_mov_b32_e32 v12, v161
	v_mov_b32_e32 v13, v161
	v_mov_b32_e32 v14, v161
	v_mov_b32_e32 v15, v161
	v_mov_b32_e32 v16, v161
	v_mov_b32_e32 v17, v161
	v_mov_b32_e32 v18, v161
	v_mov_b32_e32 v19, v161
	v_mov_b32_e32 v20, v161
	v_mov_b32_e32 v21, v161
	v_mov_b32_e32 v22, v161
	v_mov_b32_e32 v23, v161
	v_mov_b32_e32 v24, v161
	v_mov_b32_e32 v25, v161
	v_mov_b32_e32 v26, v161
	v_mov_b32_e32 v27, v161
	v_mov_b32_e32 v28, v161
	v_mov_b32_e32 v29, v161
	v_mov_b32_e32 v30, v161
	v_mov_b32_e32 v31, v161
	v_mov_b32_e32 v32, v161
	v_mov_b32_e32 v33, v161
	v_mov_b32_e32 v34, v161
	v_mov_b32_e32 v35, v161
	v_mov_b32_e32 v36, v161
	v_mov_b32_e32 v37, v161
	v_mov_b32_e32 v38, v161
	v_mov_b32_e32 v39, v161
	v_mov_b32_e32 v40, v161
	v_mov_b32_e32 v41, v161
	v_mov_b32_e32 v42, v161
	v_mov_b32_e32 v43, v161
	v_mov_b32_e32 v44, v161
	v_mov_b32_e32 v45, v161
	v_mov_b32_e32 v46, v161
	v_mov_b32_e32 v47, v161
	v_mov_b32_e32 v48, v161
	v_mov_b32_e32 v49, v161
	v_mov_b32_e32 v50, v161
	v_mov_b32_e32 v51, v161
	v_mov_b32_e32 v52, v161
	v_mov_b32_e32 v53, v161
	v_mov_b32_e32 v54, v161
	v_mov_b32_e32 v55, v161
	v_mov_b32_e32 v56, v161
	v_mov_b32_e32 v57, v161
	v_mov_b32_e32 v58, v161
	v_mov_b32_e32 v59, v161
	v_mov_b32_e32 v60, v161
	v_mov_b32_e32 v61, v161
	v_mov_b32_e32 v62, v161
	v_mov_b32_e32 v63, v161
	v_mov_b32_e32 v64, v161
	v_mov_b32_e32 v65, v161
	v_mov_b32_e32 v66, v161
	v_mov_b32_e32 v67, v161
	v_mov_b32_e32 v68, v161
	v_mov_b32_e32 v69, v161
	v_mov_b32_e32 v70, v161
	v_mov_b32_e32 v71, v161
	v_mov_b32_e32 v72, v161
	v_mov_b32_e32 v73, v161
	v_mov_b32_e32 v74, v161
	v_mov_b32_e32 v75, v161
	v_mov_b32_e32 v76, v161
	v_mov_b32_e32 v77, v161
	v_mov_b32_e32 v78, v161
	v_mov_b32_e32 v79, v161
	v_mov_b32_e32 v80, v161
	v_mov_b32_e32 v81, v161
	v_mov_b32_e32 v82, v161
	v_mov_b32_e32 v83, v161
	v_mov_b32_e32 v84, v161
	v_mov_b32_e32 v85, v161
	v_mov_b32_e32 v86, v161
	v_mov_b32_e32 v87, v161
	v_mov_b32_e32 v88, v161
	v_mov_b32_e32 v89, v161
	v_mov_b32_e32 v90, v161
	v_mov_b32_e32 v91, v161
	v_mov_b32_e32 v92, v161
	v_mov_b32_e32 v93, v161
	v_mov_b32_e32 v94, v161
	v_mov_b32_e32 v95, v161
	v_mov_b32_e32 v96, v161
	v_mov_b32_e32 v97, v161
	v_mov_b32_e32 v98, v161
	v_mov_b32_e32 v99, v161
	v_mov_b32_e32 v100, v161
	v_mov_b32_e32 v101, v161
	v_mov_b32_e32 v102, v161
	v_mov_b32_e32 v103, v161
	v_mov_b32_e32 v104, v161
	v_mov_b32_e32 v105, v161
	v_mov_b32_e32 v106, v161
	v_mov_b32_e32 v107, v161
	v_mov_b32_e32 v108, v161
	v_mov_b32_e32 v109, v161
	v_mov_b32_e32 v110, v161
	v_mov_b32_e32 v111, v161
	v_mov_b32_e32 v112, v161
	v_mov_b32_e32 v113, v161
	v_mov_b32_e32 v114, v161
	v_mov_b32_e32 v115, v161
	v_mov_b32_e32 v116, v161
	v_mov_b32_e32 v117, v161
	v_mov_b32_e32 v118, v161
	v_mov_b32_e32 v119, v161
	v_mov_b32_e32 v120, v161
	v_mov_b32_e32 v121, v161
	v_mov_b32_e32 v122, v161
	v_mov_b32_e32 v123, v161
	v_mov_b32_e32 v124, v161
	v_mov_b32_e32 v125, v161
	v_mov_b32_e32 v126, v161
	v_mov_b32_e32 v127, v161
	v_mbcnt_hi_u32_b32 v128, -1, v210
	s_and_b32 s90, s70, 0x40
	v_and_b32_e32 v159, 48, v128
	v_or_b32_e32 v159, s90, v159
	v_and_b32_e32 v129, 31, v128
	v_lshrrev_b32_e32 v130, 5, v128
	v_bfe_u32 v131, v128, 1, 3
	v_lshlrev_b32_e32 v132, 7, v129
	s_lshr_b32 s91, s70, 7
	s_lshl_b32 s91, s91, 13
	s_lshl_b32 s90, s90, 8
	s_add_u32 s90, s90, 0x8000
	s_lshl_b32 s88, s70, 4
	s_mov_b32 s89, 0x10000
	s_lshl_b32 s92, s22, 4
	s_and_b32 s92, s92, 0x780
	s_mov_b32 s93, 0
	s_load_dwordx2 s[96:97], s[0:1], 0x158
	s_load_dwordx2 s[98:99], s[0:1], 0xc0
	s_waitcnt lgkmcnt(0)
	v_subrev_u32_e32 v152, s96, v172
	v_xor_b32_e32 v152, v159, v152
	v_subrev_u32_e32 v153, s98, v180
	v_xor_b32_e32 v153, v159, v153
	v_subrev_u32_e32 v154, s96, v174
	v_xor_b32_e32 v154, v159, v154
	v_subrev_u32_e32 v155, s98, v182
	v_xor_b32_e32 v155, v159, v155
	v_subrev_u32_e32 v156, s96, v176
	v_xor_b32_e32 v156, v159, v156
	v_subrev_u32_e32 v157, s98, v184
	v_xor_b32_e32 v157, v159, v157
	v_subrev_u32_e32 v158, s96, v178
	v_xor_b32_e32 v158, v159, v158
	v_subrev_u32_e32 v160, s98, v186
	v_xor_b32_e32 v160, v159, v160
	v_xor_b32_e32 v133, v130, v131
	v_lshl_add_u32 v133, v133, 4, v132
	v_add_u32_e32 v232, s91, v133
	v_add_u32_e32 v236, s90, v133
	v_or_b32_e32 v133, 2, v130
	v_xor_b32_e32 v133, v133, v131
	v_lshl_add_u32 v133, v133, 4, v132
	v_add_u32_e32 v233, s91, v133
	v_add_u32_e32 v237, s90, v133
	v_or_b32_e32 v133, 4, v130
	v_xor_b32_e32 v133, v133, v131
	v_lshl_add_u32 v133, v133, 4, v132
	v_add_u32_e32 v234, s91, v133
	v_add_u32_e32 v238, s90, v133
	v_or_b32_e32 v133, 6, v130
	v_xor_b32_e32 v133, v133, v131
	v_lshl_add_u32 v133, v133, 4, v132
	v_add_u32_e32 v235, s91, v133
	v_add_u32_e32 v239, s90, v133
	s_barrier
	ds_read_b128 v[206:209], v232
	ds_read_b128 v[216:219], v236
	ds_read_b128 v[212:215], v232 offset:4096
	ds_read_b128 v[220:223], v236 offset:4096
	ds_read_b128 v[224:227], v236 offset:8192
	ds_read_b128 v[228:231], v236 offset:12288
	s_add_u32 s94, s2, s92
	s_add_u32 s94, s94, 0x80
	s_and_b32 s94, s94, 0x780
	s_sub_u32 s94, s94, 0x80
	s_subb_u32 s95, 0, 0
	s_add_u32 s100, s96, s94
	s_addc_u32 s101, s97, s95
	s_add_u32 s94, s98, s94
	s_addc_u32 s95, s99, s95
	s_add_u32 s90, s88, s89
	s_add_u32 m0, s90, 0
	s_nop 0
	global_load_lds_dwordx4 v152, s[100:101]
	s_add_u32 m0, s90, 32768
	s_nop 0
	global_load_lds_dwordx4 v153, s[94:95]
	s_add_u32 m0, s90, 8192
	s_nop 0
	global_load_lds_dwordx4 v154, s[100:101]
	s_add_u32 m0, s90, 40960
	s_nop 0
	global_load_lds_dwordx4 v155, s[94:95]
	s_add_u32 m0, s90, 16384
	s_nop 0
	global_load_lds_dwordx4 v156, s[100:101]
	s_add_u32 m0, s90, 49152
	s_nop 0
	global_load_lds_dwordx4 v157, s[94:95]
	s_add_u32 m0, s90, 24576
	s_nop 0
	global_load_lds_dwordx4 v158, s[100:101]
	s_add_u32 m0, s90, 57344
	s_nop 0
	global_load_lds_dwordx4 v160, s[94:95]
	s_xor_b32 s89, s89, 0x10000
.Lgk0_loop:
	ds_read_b128 v[128:131], v233
	ds_read_b128 v[136:139], v237
	ds_read_b128 v[132:135], v233 offset:4096
	ds_read_b128 v[140:143], v237 offset:4096
	ds_read_b128 v[144:147], v237 offset:8192
	ds_read_b128 v[148:151], v237 offset:12288
	s_waitcnt lgkmcnt(6)
	v_mfma_f32_32x32x16_bf16 v[112:127], v[206:209], v[216:219], v[112:127]
	v_mfma_f32_32x32x16_bf16 v[48:63], v[212:215], v[216:219], v[48:63]
	v_mfma_f32_32x32x16_bf16 v[96:111], v[206:209], v[220:223], v[96:111]
	v_mfma_f32_32x32x16_bf16 v[32:47], v[212:215], v[220:223], v[32:47]
	v_mfma_f32_32x32x16_bf16 v[80:95], v[206:209], v[224:227], v[80:95]
	v_mfma_f32_32x32x16_bf16 v[16:31], v[212:215], v[224:227], v[16:31]
	v_mfma_f32_32x32x16_bf16 v[64:79], v[206:209], v[228:231], v[64:79]
	v_mfma_f32_32x32x16_bf16 v[0:15], v[212:215], v[228:231], v[0:15]
	ds_read_b128 v[206:209], v234
	ds_read_b128 v[216:219], v238
	ds_read_b128 v[212:215], v234 offset:4096
	ds_read_b128 v[220:223], v238 offset:4096
	ds_read_b128 v[224:227], v238 offset:8192
	ds_read_b128 v[228:231], v238 offset:12288
	s_waitcnt lgkmcnt(6)
	v_mfma_f32_32x32x16_bf16 v[112:127], v[128:131], v[136:139], v[112:127]
	v_mfma_f32_32x32x16_bf16 v[48:63], v[132:135], v[136:139], v[48:63]
	v_mfma_f32_32x32x16_bf16 v[96:111], v[128:131], v[140:143], v[96:111]
	v_mfma_f32_32x32x16_bf16 v[32:47], v[132:135], v[140:143], v[32:47]
	v_mfma_f32_32x32x16_bf16 v[80:95], v[128:131], v[144:147], v[80:95]
	v_mfma_f32_32x32x16_bf16 v[16:31], v[132:135], v[144:147], v[16:31]
	v_mfma_f32_32x32x16_bf16 v[64:79], v[128:131], v[148:151], v[64:79]
	v_mfma_f32_32x32x16_bf16 v[0:15], v[132:135], v[148:151], v[0:15]
	ds_read_b128 v[128:131], v235
	ds_read_b128 v[136:139], v239
	ds_read_b128 v[132:135], v235 offset:4096
	ds_read_b128 v[140:143], v239 offset:4096
	ds_read_b128 v[144:147], v239 offset:8192
	ds_read_b128 v[148:151], v239 offset:12288
	s_waitcnt lgkmcnt(6)
	v_mfma_f32_32x32x16_bf16 v[112:127], v[206:209], v[216:219], v[112:127]
	v_mfma_f32_32x32x16_bf16 v[48:63], v[212:215], v[216:219], v[48:63]
	v_mfma_f32_32x32x16_bf16 v[96:111], v[206:209], v[220:223], v[96:111]
	v_mfma_f32_32x32x16_bf16 v[32:47], v[212:215], v[220:223], v[32:47]
	v_mfma_f32_32x32x16_bf16 v[80:95], v[206:209], v[224:227], v[80:95]
	v_mfma_f32_32x32x16_bf16 v[16:31], v[212:215], v[224:227], v[16:31]
	v_mfma_f32_32x32x16_bf16 v[64:79], v[206:209], v[228:231], v[64:79]
	v_mfma_f32_32x32x16_bf16 v[0:15], v[212:215], v[228:231], v[0:15]
	s_waitcnt vmcnt(0) lgkmcnt(0)
	s_barrier
	v_xor_b32_e32 v232, 0x10000, v232
	v_xor_b32_e32 v236, 0x10000, v236
	ds_read_b128 v[206:209], v232
	ds_read_b128 v[216:219], v236
	ds_read_b128 v[212:215], v232 offset:4096
	ds_read_b128 v[220:223], v236 offset:4096
	ds_read_b128 v[224:227], v236 offset:8192
	ds_read_b128 v[228:231], v236 offset:12288
	s_cmpk_eq_i32 s2, 0x700
	s_cbranch_scc1 .Lgk0_nodma
	s_add_u32 s94, s2, s92
	s_add_u32 s94, s94, 0x100
	s_and_b32 s94, s94, 0x780
	s_sub_u32 s94, s94, 0x80
	s_subb_u32 s95, 0, 0
	s_add_u32 s100, s96, s94
	s_addc_u32 s101, s97, s95
	s_add_u32 s94, s98, s94
	s_addc_u32 s95, s99, s95
	s_add_u32 s90, s88, s89
	v_mfma_f32_32x32x16_bf16 v[112:127], v[128:131], v[136:139], v[112:127]
	v_xor_b32_e32 v233, 0x10000, v233
	v_xor_b32_e32 v237, 0x10000, v237
	s_add_u32 m0, s90, 0
	s_nop 0
	global_load_lds_dwordx4 v152, s[100:101]
	v_mfma_f32_32x32x16_bf16 v[48:63], v[132:135], v[136:139], v[48:63]
	v_xor_b32_e32 v234, 0x10000, v234
	v_xor_b32_e32 v238, 0x10000, v238
	s_add_u32 m0, s90, 32768
	s_nop 0
	global_load_lds_dwordx4 v153, s[94:95]
	v_mfma_f32_32x32x16_bf16 v[96:111], v[128:131], v[140:143], v[96:111]
	v_xor_b32_e32 v235, 0x10000, v235
	v_xor_b32_e32 v239, 0x10000, v239
	s_add_u32 m0, s90, 8192
	s_nop 0
	global_load_lds_dwordx4 v154, s[100:101]
	v_mfma_f32_32x32x16_bf16 v[32:47], v[132:135], v[140:143], v[32:47]
	s_add_u32 m0, s90, 40960
	s_nop 0
	global_load_lds_dwordx4 v155, s[94:95]
	v_mfma_f32_32x32x16_bf16 v[80:95], v[128:131], v[144:147], v[80:95]
	s_add_u32 m0, s90, 16384
	s_nop 0
	global_load_lds_dwordx4 v156, s[100:101]
	v_mfma_f32_32x32x16_bf16 v[16:31], v[132:135], v[144:147], v[16:31]
	s_add_u32 m0, s90, 49152
	s_nop 0
	global_load_lds_dwordx4 v157, s[94:95]
	v_mfma_f32_32x32x16_bf16 v[64:79], v[128:131], v[148:151], v[64:79]
	s_add_u32 m0, s90, 24576
	s_nop 0
	global_load_lds_dwordx4 v158, s[100:101]
	v_mfma_f32_32x32x16_bf16 v[0:15], v[132:135], v[148:151], v[0:15]
	s_add_u32 m0, s90, 57344
	s_nop 0
	global_load_lds_dwordx4 v160, s[94:95]
	s_branch .Lgk0_join

.LBB0_307:
	ds_read_b128 v[128:131], v233
	ds_read_b128 v[136:139], v237
	ds_read_b128 v[132:135], v233 offset:4096
	ds_read_b128 v[140:143], v237 offset:4096
	ds_read_b128 v[144:147], v237 offset:8192
	ds_read_b128 v[148:151], v237 offset:12288
	s_waitcnt lgkmcnt(6)
	v_mfma_f32_32x32x16_bf16 v[112:127], v[206:209], v[216:219], v[112:127]
	v_mfma_f32_32x32x16_bf16 v[48:63], v[212:215], v[216:219], v[48:63]
	v_mfma_f32_32x32x16_bf16 v[96:111], v[206:209], v[220:223], v[96:111]
	v_mfma_f32_32x32x16_bf16 v[32:47], v[212:215], v[220:223], v[32:47]
	v_mfma_f32_32x32x16_bf16 v[80:95], v[206:209], v[224:227], v[80:95]
	v_mfma_f32_32x32x16_bf16 v[16:31], v[212:215], v[224:227], v[16:31]
	v_mfma_f32_32x32x16_bf16 v[64:79], v[206:209], v[228:231], v[64:79]
	v_mfma_f32_32x32x16_bf16 v[0:15], v[212:215], v[228:231], v[0:15]
	ds_read_b128 v[206:209], v234
	ds_read_b128 v[216:219], v238
	ds_read_b128 v[212:215], v234 offset:4096
	ds_read_b128 v[220:223], v238 offset:4096
	ds_read_b128 v[224:227], v238 offset:8192
	ds_read_b128 v[228:231], v238 offset:12288
	s_waitcnt lgkmcnt(6)
	v_mfma_f32_32x32x16_bf16 v[112:127], v[128:131], v[136:139], v[112:127]
	v_mfma_f32_32x32x16_bf16 v[48:63], v[132:135], v[136:139], v[48:63]
	v_mfma_f32_32x32x16_bf16 v[96:111], v[128:131], v[140:143], v[96:111]
	v_mfma_f32_32x32x16_bf16 v[32:47], v[132:135], v[140:143], v[32:47]
	v_mfma_f32_32x32x16_bf16 v[80:95], v[128:131], v[144:147], v[80:95]
	v_mfma_f32_32x32x16_bf16 v[16:31], v[132:135], v[144:147], v[16:31]
	v_mfma_f32_32x32x16_bf16 v[64:79], v[128:131], v[148:151], v[64:79]
	v_mfma_f32_32x32x16_bf16 v[0:15], v[132:135], v[148:151], v[0:15]
	ds_read_b128 v[128:131], v235
	ds_read_b128 v[136:139], v239
	ds_read_b128 v[132:135], v235 offset:4096
	ds_read_b128 v[140:143], v239 offset:4096
	ds_read_b128 v[144:147], v239 offset:8192
	ds_read_b128 v[148:151], v239 offset:12288
	s_waitcnt lgkmcnt(6)
	v_mfma_f32_32x32x16_bf16 v[112:127], v[206:209], v[216:219], v[112:127]
	v_mfma_f32_32x32x16_bf16 v[48:63], v[212:215], v[216:219], v[48:63]
	v_mfma_f32_32x32x16_bf16 v[96:111], v[206:209], v[220:223], v[96:111]
	v_mfma_f32_32x32x16_bf16 v[32:47], v[212:215], v[220:223], v[32:47]
	v_mfma_f32_32x32x16_bf16 v[80:95], v[206:209], v[224:227], v[80:95]
	v_mfma_f32_32x32x16_bf16 v[16:31], v[212:215], v[224:227], v[16:31]
	v_mfma_f32_32x32x16_bf16 v[64:79], v[206:209], v[228:231], v[64:79]
	v_mfma_f32_32x32x16_bf16 v[0:15], v[212:215], v[228:231], v[0:15]
	s_waitcnt vmcnt(0) lgkmcnt(0)
	s_barrier
	v_xor_b32_e32 v232, 0x10000, v232
	v_xor_b32_e32 v236, 0x10000, v236
	v_mfma_f32_32x32x16_bf16 v[112:127], v[128:131], v[136:139], v[112:127]
	v_xor_b32_e32 v233, 0x10000, v233
	v_xor_b32_e32 v237, 0x10000, v237
	v_mfma_f32_32x32x16_bf16 v[48:63], v[132:135], v[136:139], v[48:63]
	v_xor_b32_e32 v234, 0x10000, v234
	v_xor_b32_e32 v238, 0x10000, v238
	v_mfma_f32_32x32x16_bf16 v[96:111], v[128:131], v[140:143], v[96:111]
	v_xor_b32_e32 v235, 0x10000, v235
	v_xor_b32_e32 v239, 0x10000, v239
	v_mfma_f32_32x32x16_bf16 v[32:47], v[132:135], v[140:143], v[32:47]
	v_mfma_f32_32x32x16_bf16 v[80:95], v[128:131], v[144:147], v[80:95]
	v_mfma_f32_32x32x16_bf16 v[16:31], v[132:135], v[144:147], v[16:31]
	v_mfma_f32_32x32x16_bf16 v[64:79], v[128:131], v[148:151], v[64:79]
	v_mfma_f32_32x32x16_bf16 v[0:15], v[132:135], v[148:151], v[0:15]
	v_mbcnt_hi_u32_b32 v229, -1, v210
	v_and_b32_e32 v230, 31, v229
	v_lshrrev_b32_e32 v231, 5, v229
	v_lshlrev_b32_e32 v160, 3, v230
	v_lshlrev_b32_e32 v226, 2, v231
	s_lshr_b32 s90, s70, 6
	s_mul_i32 s91, s90, 0x1200
	s_add_u32 s91, s91, 0x12000
	v_mul_u32_u24_e32 v232, 0x240, v231
	v_lshl_add_u32 v232, v230, 1, v232
	v_add_u32_e32 v224, s91, v232
	v_lshrrev_b32_e32 v227, 3, v229
	v_and_b32_e32 v233, 7, v229
	v_lshlrev_b32_e32 v228, 4, v233
	v_mul_u32_u24_e32 v232, 0x90, v227
	v_add3_u32 v225, v232, v228, s91
	s_mul_i32 s92, s5, 6
	s_sub_u32 s93, s4, s92
	s_lshl_b32 s93, s93, 8
	s_lshl_b32 s92, s5, 8
	s_lshr_b32 s94, s90, 1
	s_lshl_b32 s94, s94, 6
	s_add_u32 s92, s92, s94
	s_and_b32 s94, s90, 1
	s_lshl_b32 s94, s94, 7
	s_add_u32 s93, s93, s94

.Lep0_00_mP:
	v_cvt_pk_bf16_f32 v229, v112, v96
	ds_write_b16 v224, v229
	ds_write_b16_d16_hi v224, v229 offset:64
	v_cvt_pk_bf16_f32 v230, v113, v97
	ds_write_b16 v224, v230 offset:144
	ds_write_b16_d16_hi v224, v230 offset:208
	v_cvt_pk_bf16_f32 v231, v114, v98
	ds_write_b16 v224, v231 offset:288
	ds_write_b16_d16_hi v224, v231 offset:352
	v_cvt_pk_bf16_f32 v232, v115, v99
	ds_write_b16 v224, v232 offset:432
	ds_write_b16_d16_hi v224, v232 offset:496
	v_cvt_pk_bf16_f32 v229, v116, v100
	ds_write_b16 v224, v229 offset:1152
	ds_write_b16_d16_hi v224, v229 offset:1216
	v_cvt_pk_bf16_f32 v230, v117, v101
	ds_write_b16 v224, v230 offset:1296
	ds_write_b16_d16_hi v224, v230 offset:1360
	v_cvt_pk_bf16_f32 v231, v118, v102
	ds_write_b16 v224, v231 offset:1440
	ds_write_b16_d16_hi v224, v231 offset:1504
	v_cvt_pk_bf16_f32 v232, v119, v103
	ds_write_b16 v224, v232 offset:1584
	ds_write_b16_d16_hi v224, v232 offset:1648
	v_cvt_pk_bf16_f32 v229, v120, v104
	ds_write_b16 v224, v229 offset:2304
	ds_write_b16_d16_hi v224, v229 offset:2368
	v_cvt_pk_bf16_f32 v230, v121, v105
	ds_write_b16 v224, v230 offset:2448
	ds_write_b16_d16_hi v224, v230 offset:2512
	v_cvt_pk_bf16_f32 v231, v122, v106
	ds_write_b16 v224, v231 offset:2592
	ds_write_b16_d16_hi v224, v231 offset:2656
	v_cvt_pk_bf16_f32 v232, v123, v107
	ds_write_b16 v224, v232 offset:2736
	ds_write_b16_d16_hi v224, v232 offset:2800
	v_cvt_pk_bf16_f32 v229, v124, v108
	ds_write_b16 v224, v229 offset:3456
	ds_write_b16_d16_hi v224, v229 offset:3520
	v_cvt_pk_bf16_f32 v230, v125, v109
	ds_write_b16 v224, v230 offset:3600
	ds_write_b16_d16_hi v224, v230 offset:3664
	v_cvt_pk_bf16_f32 v231, v126, v110
	ds_write_b16 v224, v231 offset:3744
	ds_write_b16_d16_hi v224, v231 offset:3808
	v_cvt_pk_bf16_f32 v232, v127, v111
	ds_write_b16 v224, v232 offset:3888
	ds_write_b16_d16_hi v224, v232 offset:3952
	s_branch .Lep0_00_stq
.Lep0_00_mR:
	s_load_dwordx2 s[98:99], s[0:1], 0x148
	v_add_u32_e32 v229, s94, v226
	v_lshlrev_b32_e32 v229, 8, v229
	v_add_u32_e32 v236, v229, v160
	v_mov_b32_e32 v237, 0
	s_waitcnt lgkmcnt(0)
	v_lshl_add_u64 v[236:237], s[98:99], 0, v[236:237]
	global_load_dwordx2 v[128:129], v[236:237], off
	global_load_dwordx2 v[130:131], v[236:237], off offset:256
	global_load_dwordx2 v[132:133], v[236:237], off offset:512
	global_load_dwordx2 v[134:135], v[236:237], off offset:768
	global_load_dwordx2 v[136:137], v[236:237], off offset:2048
	global_load_dwordx2 v[138:139], v[236:237], off offset:2304
	global_load_dwordx2 v[140:141], v[236:237], off offset:2560
	global_load_dwordx2 v[142:143], v[236:237], off offset:2816
	v_add_co_u32_e32 v238, vcc, 0x1000, v236
	s_nop 1
	v_addc_co_u32_e32 v239, vcc, 0, v237, vcc
	global_load_dwordx2 v[144:145], v[238:239], off
	global_load_dwordx2 v[146:147], v[238:239], off offset:256
	global_load_dwordx2 v[148:149], v[238:239], off offset:512
	global_load_dwordx2 v[150:151], v[238:239], off offset:768
	global_load_dwordx2 v[152:153], v[238:239], off offset:2048
	global_load_dwordx2 v[154:155], v[238:239], off offset:2304
	global_load_dwordx2 v[156:157], v[238:239], off offset:2560
	global_load_dwordx2 v[158:159], v[238:239], off offset:2816
	s_waitcnt vmcnt(15)
	v_mul_f32_e32 v229, v96, v129
	v_mul_f32_e32 v230, v112, v129
	v_fma_f32 v229, v112, v128, -v229
	v_fma_f32 v230, v96, v128, v230
	v_mul_f32_e32 v229, s88, v229
	v_mul_f32_e32 v230, s88, v230
	v_cvt_pk_bf16_f32 v229, v229, v230
	ds_write_b16 v224, v229
	ds_write_b16_d16_hi v224, v229 offset:64
	s_waitcnt vmcnt(14)
	v_mul_f32_e32 v229, v97, v131
	v_mul_f32_e32 v230, v113, v131
	v_fma_f32 v229, v113, v130, -v229
	v_fma_f32 v230, v97, v130, v230
	v_mul_f32_e32 v229, s88, v229
	v_mul_f32_e32 v230, s88, v230
	v_cvt_pk_bf16_f32 v229, v229, v230
	ds_write_b16 v224, v229 offset:144
	ds_write_b16_d16_hi v224, v229 offset:208
	s_waitcnt vmcnt(13)
	v_mul_f32_e32 v229, v98, v133
	v_mul_f32_e32 v230, v114, v133
	v_fma_f32 v229, v114, v132, -v229
	v_fma_f32 v230, v98, v132, v230
	v_mul_f32_e32 v229, s88, v229
	v_mul_f32_e32 v230, s88, v230
	v_cvt_pk_bf16_f32 v229, v229, v230
	ds_write_b16 v224, v229 offset:288
	ds_write_b16_d16_hi v224, v229 offset:352
	s_waitcnt vmcnt(12)
	v_mul_f32_e32 v229, v99, v135
	v_mul_f32_e32 v230, v115, v135
	v_fma_f32 v229, v115, v134, -v229
	v_fma_f32 v230, v99, v134, v230
	v_mul_f32_e32 v229, s88, v229
	v_mul_f32_e32 v230, s88, v230
	v_cvt_pk_bf16_f32 v229, v229, v230
	ds_write_b16 v224, v229 offset:432
	ds_write_b16_d16_hi v224, v229 offset:496
	s_waitcnt vmcnt(11)
	v_mul_f32_e32 v229, v100, v137
	v_mul_f32_e32 v230, v116, v137
	v_fma_f32 v229, v116, v136, -v229
	v_fma_f32 v230, v100, v136, v230
	v_mul_f32_e32 v229, s88, v229
	v_mul_f32_e32 v230, s88, v230
	v_cvt_pk_bf16_f32 v229, v229, v230
	ds_write_b16 v224, v229 offset:1152
	ds_write_b16_d16_hi v224, v229 offset:1216
	s_waitcnt vmcnt(10)
	v_mul_f32_e32 v229, v101, v139
	v_mul_f32_e32 v230, v117, v139
	v_fma_f32 v229, v117, v138, -v229
	v_fma_f32 v230, v101, v138, v230
	v_mul_f32_e32 v229, s88, v229
	v_mul_f32_e32 v230, s88, v230
	v_cvt_pk_bf16_f32 v229, v229, v230
	ds_write_b16 v224, v229 offset:1296
	ds_write_b16_d16_hi v224, v229 offset:1360
	s_waitcnt vmcnt(9)
	v_mul_f32_e32 v229, v102, v141
	v_mul_f32_e32 v230, v118, v141
	v_fma_f32 v229, v118, v140, -v229
	v_fma_f32 v230, v102, v140, v230
	v_mul_f32_e32 v229, s88, v229
	v_mul_f32_e32 v230, s88, v230
	v_cvt_pk_bf16_f32 v229, v229, v230
	ds_write_b16 v224, v229 offset:1440
	ds_write_b16_d16_hi v224, v229 offset:1504
	s_waitcnt vmcnt(8)
	v_mul_f32_e32 v229, v103, v143
	v_mul_f32_e32 v230, v119, v143
	v_fma_f32 v229, v119, v142, -v229
	v_fma_f32 v230, v103, v142, v230
	v_mul_f32_e32 v229, s88, v229
	v_mul_f32_e32 v230, s88, v230
	v_cvt_pk_bf16_f32 v229, v229, v230
	ds_write_b16 v224, v229 offset:1584
	ds_write_b16_d16_hi v224, v229 offset:1648
	s_waitcnt vmcnt(7)
	v_mul_f32_e32 v229, v104, v145
	v_mul_f32_e32 v230, v120, v145
	v_fma_f32 v229, v120, v144, -v229
	v_fma_f32 v230, v104, v144, v230
	v_mul_f32_e32 v229, s88, v229
	v_mul_f32_e32 v230, s88, v230
	v_cvt_pk_bf16_f32 v229, v229, v230
	ds_write_b16 v224, v229 offset:2304
	ds_write_b16_d16_hi v224, v229 offset:2368
	s_waitcnt vmcnt(6)
	v_mul_f32_e32 v229, v105, v147
	v_mul_f32_e32 v230, v121, v147
	v_fma_f32 v229, v121, v146, -v229
	v_fma_f32 v230, v105, v146, v230
	v_mul_f32_e32 v229, s88, v229
	v_mul_f32_e32 v230, s88, v230
	v_cvt_pk_bf16_f32 v229, v229, v230
	ds_write_b16 v224, v229 offset:2448
	ds_write_b16_d16_hi v224, v229 offset:2512
	s_waitcnt vmcnt(5)
	v_mul_f32_e32 v229, v106, v149
	v_mul_f32_e32 v230, v122, v149
	v_fma_f32 v229, v122, v148, -v229
	v_fma_f32 v230, v106, v148, v230
	v_mul_f32_e32 v229, s88, v229
	v_mul_f32_e32 v230, s88, v230
	v_cvt_pk_bf16_f32 v229, v229, v230
	ds_write_b16 v224, v229 offset:2592
	ds_write_b16_d16_hi v224, v229 offset:2656
	s_waitcnt vmcnt(4)
	v_mul_f32_e32 v229, v107, v151
	v_mul_f32_e32 v230, v123, v151
	v_fma_f32 v229, v123, v150, -v229
	v_fma_f32 v230, v107, v150, v230
	v_mul_f32_e32 v229, s88, v229
	v_mul_f32_e32 v230, s88, v230
	v_cvt_pk_bf16_f32 v229, v229, v230
	ds_write_b16 v224, v229 offset:2736
	ds_write_b16_d16_hi v224, v229 offset:2800
	s_waitcnt vmcnt(3)
	v_mul_f32_e32 v229, v108, v153
	v_mul_f32_e32 v230, v124, v153
	v_fma_f32 v229, v124, v152, -v229
	v_fma_f32 v230, v108, v152, v230
	v_mul_f32_e32 v229, s88, v229
	v_mul_f32_e32 v230, s88, v230
	v_cvt_pk_bf16_f32 v229, v229, v230
	ds_write_b16 v224, v229 offset:3456
	ds_write_b16_d16_hi v224, v229 offset:3520
	s_waitcnt vmcnt(2)
	v_mul_f32_e32 v229, v109, v155
	v_mul_f32_e32 v230, v125, v155
	v_fma_f32 v229, v125, v154, -v229
	v_fma_f32 v230, v109, v154, v230
	v_mul_f32_e32 v229, s88, v229
	v_mul_f32_e32 v230, s88, v230
	v_cvt_pk_bf16_f32 v229, v229, v230
	ds_write_b16 v224, v229 offset:3600
	ds_write_b16_d16_hi v224, v229 offset:3664
	s_waitcnt vmcnt(1)
	v_mul_f32_e32 v229, v110, v157
	v_mul_f32_e32 v230, v126, v157
	v_fma_f32 v229, v126, v156, -v229
	v_fma_f32 v230, v110, v156, v230
	v_mul_f32_e32 v229, s88, v229
	v_mul_f32_e32 v230, s88, v230
	v_cvt_pk_bf16_f32 v229, v229, v230
	ds_write_b16 v224, v229 offset:3744
	ds_write_b16_d16_hi v224, v229 offset:3808
	s_waitcnt vmcnt(0)
	v_mul_f32_e32 v229, v111, v159
	v_mul_f32_e32 v230, v127, v159
	v_fma_f32 v229, v127, v158, -v229
	v_fma_f32 v230, v111, v158, v230
	v_mul_f32_e32 v229, s88, v229
	v_mul_f32_e32 v230, s88, v230
	v_cvt_pk_bf16_f32 v229, v229, v230
	ds_write_b16 v224, v229 offset:3888
	ds_write_b16_d16_hi v224, v229 offset:3952
	s_branch .Lep0_00_stb
.Lep0_00_mS:
	v_mul_f32_e32 v229, 0xbfb8aa3b, v112
	v_mul_f32_e32 v230, 0xbfb8aa3b, v96
	v_exp_f32_e32 v229, v229
	v_exp_f32_e32 v230, v230
	v_add_f32_e32 v229, 1.0, v229
	v_add_f32_e32 v230, 1.0, v230
	v_rcp_f32_e32 v229, v229
	v_rcp_f32_e32 v230, v230
	v_mul_f32_e32 v229, v112, v229
	v_mul_f32_e32 v230, v96, v230
	v_cvt_pk_bf16_f32 v229, v229, v230
	ds_write_b16 v224, v229
	ds_write_b16_d16_hi v224, v229 offset:64
	v_mul_f32_e32 v231, 0xbfb8aa3b, v113
	v_mul_f32_e32 v232, 0xbfb8aa3b, v97
	v_exp_f32_e32 v231, v231
	v_exp_f32_e32 v232, v232
	v_add_f32_e32 v231, 1.0, v231
	v_add_f32_e32 v232, 1.0, v232
	v_rcp_f32_e32 v231, v231
	v_rcp_f32_e32 v232, v232
	v_mul_f32_e32 v231, v113, v231
	v_mul_f32_e32 v232, v97, v232
	v_cvt_pk_bf16_f32 v231, v231, v232
	ds_write_b16 v224, v231 offset:144
	ds_write_b16_d16_hi v224, v231 offset:208
	v_mul_f32_e32 v229, 0xbfb8aa3b, v114
	v_mul_f32_e32 v230, 0xbfb8aa3b, v98
	v_exp_f32_e32 v229, v229
	v_exp_f32_e32 v230, v230
	v_add_f32_e32 v229, 1.0, v229
	v_add_f32_e32 v230, 1.0, v230
	v_rcp_f32_e32 v229, v229
	v_rcp_f32_e32 v230, v230
	v_mul_f32_e32 v229, v114, v229
	v_mul_f32_e32 v230, v98, v230
	v_cvt_pk_bf16_f32 v229, v229, v230
	ds_write_b16 v224, v229 offset:288
	ds_write_b16_d16_hi v224, v229 offset:352
	v_mul_f32_e32 v231, 0xbfb8aa3b, v115
	v_mul_f32_e32 v232, 0xbfb8aa3b, v99
	v_exp_f32_e32 v231, v231
	v_exp_f32_e32 v232, v232
	v_add_f32_e32 v231, 1.0, v231
	v_add_f32_e32 v232, 1.0, v232
	v_rcp_f32_e32 v231, v231
	v_rcp_f32_e32 v232, v232
	v_mul_f32_e32 v231, v115, v231
	v_mul_f32_e32 v232, v99, v232
	v_cvt_pk_bf16_f32 v231, v231, v232
	ds_write_b16 v224, v231 offset:432
	ds_write_b16_d16_hi v224, v231 offset:496
	v_mul_f32_e32 v229, 0xbfb8aa3b, v116
	v_mul_f32_e32 v230, 0xbfb8aa3b, v100
	v_exp_f32_e32 v229, v229
	v_exp_f32_e32 v230, v230
	v_add_f32_e32 v229, 1.0, v229
	v_add_f32_e32 v230, 1.0, v230
	v_rcp_f32_e32 v229, v229
	v_rcp_f32_e32 v230, v230
	v_mul_f32_e32 v229, v116, v229
	v_mul_f32_e32 v230, v100, v230
	v_cvt_pk_bf16_f32 v229, v229, v230
	ds_write_b16 v224, v229 offset:1152
	ds_write_b16_d16_hi v224, v229 offset:1216
	v_mul_f32_e32 v231, 0xbfb8aa3b, v117
	v_mul_f32_e32 v232, 0xbfb8aa3b, v101
	v_exp_f32_e32 v231, v231
	v_exp_f32_e32 v232, v232
	v_add_f32_e32 v231, 1.0, v231
	v_add_f32_e32 v232, 1.0, v232
	v_rcp_f32_e32 v231, v231
	v_rcp_f32_e32 v232, v232
	v_mul_f32_e32 v231, v117, v231
	v_mul_f32_e32 v232, v101, v232
	v_cvt_pk_bf16_f32 v231, v231, v232
	ds_write_b16 v224, v231 offset:1296
	ds_write_b16_d16_hi v224, v231 offset:1360
	v_mul_f32_e32 v229, 0xbfb8aa3b, v118
	v_mul_f32_e32 v230, 0xbfb8aa3b, v102
	v_exp_f32_e32 v229, v229
	v_exp_f32_e32 v230, v230
	v_add_f32_e32 v229, 1.0, v229
	v_add_f32_e32 v230, 1.0, v230
	v_rcp_f32_e32 v229, v229
	v_rcp_f32_e32 v230, v230
	v_mul_f32_e32 v229, v118, v229
	v_mul_f32_e32 v230, v102, v230
	v_cvt_pk_bf16_f32 v229, v229, v230
	ds_write_b16 v224, v229 offset:1440
	ds_write_b16_d16_hi v224, v229 offset:1504
	v_mul_f32_e32 v231, 0xbfb8aa3b, v119
	v_mul_f32_e32 v232, 0xbfb8aa3b, v103
	v_exp_f32_e32 v231, v231
	v_exp_f32_e32 v232, v232
	v_add_f32_e32 v231, 1.0, v231
	v_add_f32_e32 v232, 1.0, v232
	v_rcp_f32_e32 v231, v231
	v_rcp_f32_e32 v232, v232
	v_mul_f32_e32 v231, v119, v231
	v_mul_f32_e32 v232, v103, v232
	v_cvt_pk_bf16_f32 v231, v231, v232
	ds_write_b16 v224, v231 offset:1584
	ds_write_b16_d16_hi v224, v231 offset:1648
	v_mul_f32_e32 v229, 0xbfb8aa3b, v120
	v_mul_f32_e32 v230, 0xbfb8aa3b, v104
	v_exp_f32_e32 v229, v229
	v_exp_f32_e32 v230, v230
	v_add_f32_e32 v229, 1.0, v229
	v_add_f32_e32 v230, 1.0, v230
	v_rcp_f32_e32 v229, v229
	v_rcp_f32_e32 v230, v230
	v_mul_f32_e32 v229, v120, v229
	v_mul_f32_e32 v230, v104, v230
	v_cvt_pk_bf16_f32 v229, v229, v230
	ds_write_b16 v224, v229 offset:2304
	ds_write_b16_d16_hi v224, v229 offset:2368
	v_mul_f32_e32 v231, 0xbfb8aa3b, v121
	v_mul_f32_e32 v232, 0xbfb8aa3b, v105
	v_exp_f32_e32 v231, v231
	v_exp_f32_e32 v232, v232
	v_add_f32_e32 v231, 1.0, v231
	v_add_f32_e32 v232, 1.0, v232
	v_rcp_f32_e32 v231, v231
	v_rcp_f32_e32 v232, v232
	v_mul_f32_e32 v231, v121, v231
	v_mul_f32_e32 v232, v105, v232
	v_cvt_pk_bf16_f32 v231, v231, v232
	ds_write_b16 v224, v231 offset:2448
	ds_write_b16_d16_hi v224, v231 offset:2512
	v_mul_f32_e32 v229, 0xbfb8aa3b, v122
	v_mul_f32_e32 v230, 0xbfb8aa3b, v106
	v_exp_f32_e32 v229, v229
	v_exp_f32_e32 v230, v230
	v_add_f32_e32 v229, 1.0, v229
	v_add_f32_e32 v230, 1.0, v230
	v_rcp_f32_e32 v229, v229
	v_rcp_f32_e32 v230, v230
	v_mul_f32_e32 v229, v122, v229
	v_mul_f32_e32 v230, v106, v230
	v_cvt_pk_bf16_f32 v229, v229, v230
	ds_write_b16 v224, v229 offset:2592
	ds_write_b16_d16_hi v224, v229 offset:2656
	v_mul_f32_e32 v231, 0xbfb8aa3b, v123
	v_mul_f32_e32 v232, 0xbfb8aa3b, v107
	v_exp_f32_e32 v231, v231
	v_exp_f32_e32 v232, v232
	v_add_f32_e32 v231, 1.0, v231
	v_add_f32_e32 v232, 1.0, v232
	v_rcp_f32_e32 v231, v231
	v_rcp_f32_e32 v232, v232
	v_mul_f32_e32 v231, v123, v231
	v_mul_f32_e32 v232, v107, v232
	v_cvt_pk_bf16_f32 v231, v231, v232
	ds_write_b16 v224, v231 offset:2736
	ds_write_b16_d16_hi v224, v231 offset:2800
	v_mul_f32_e32 v229, 0xbfb8aa3b, v124
	v_mul_f32_e32 v230, 0xbfb8aa3b, v108
	v_exp_f32_e32 v229, v229
	v_exp_f32_e32 v230, v230
	v_add_f32_e32 v229, 1.0, v229
	v_add_f32_e32 v230, 1.0, v230
	v_rcp_f32_e32 v229, v229
	v_rcp_f32_e32 v230, v230
	v_mul_f32_e32 v229, v124, v229
	v_mul_f32_e32 v230, v108, v230
	v_cvt_pk_bf16_f32 v229, v229, v230
	ds_write_b16 v224, v229 offset:3456
	ds_write_b16_d16_hi v224, v229 offset:3520
	v_mul_f32_e32 v231, 0xbfb8aa3b, v125
	v_mul_f32_e32 v232, 0xbfb8aa3b, v109
	v_exp_f32_e32 v231, v231
	v_exp_f32_e32 v232, v232
	v_add_f32_e32 v231, 1.0, v231
	v_add_f32_e32 v232, 1.0, v232
	v_rcp_f32_e32 v231, v231
	v_rcp_f32_e32 v232, v232
	v_mul_f32_e32 v231, v125, v231
	v_mul_f32_e32 v232, v109, v232
	v_cvt_pk_bf16_f32 v231, v231, v232
	ds_write_b16 v224, v231 offset:3600
	ds_write_b16_d16_hi v224, v231 offset:3664
	v_mul_f32_e32 v229, 0xbfb8aa3b, v126
	v_mul_f32_e32 v230, 0xbfb8aa3b, v110
	v_exp_f32_e32 v229, v229
	v_exp_f32_e32 v230, v230
	v_add_f32_e32 v229, 1.0, v229
	v_add_f32_e32 v230, 1.0, v230
	v_rcp_f32_e32 v229, v229
	v_rcp_f32_e32 v230, v230
	v_mul_f32_e32 v229, v126, v229
	v_mul_f32_e32 v230, v110, v230
	v_cvt_pk_bf16_f32 v229, v229, v230
	ds_write_b16 v224, v229 offset:3744
	ds_write_b16_d16_hi v224, v229 offset:3808
	v_mul_f32_e32 v231, 0xbfb8aa3b, v127
	v_mul_f32_e32 v232, 0xbfb8aa3b, v111
	v_exp_f32_e32 v231, v231
	v_exp_f32_e32 v232, v232
	v_add_f32_e32 v231, 1.0, v231
	v_add_f32_e32 v232, 1.0, v232
	v_rcp_f32_e32 v231, v231
	v_rcp_f32_e32 v232, v232
	v_mul_f32_e32 v231, v127, v231
	v_mul_f32_e32 v232, v111, v232
	v_cvt_pk_bf16_f32 v231, v231, v232
	ds_write_b16 v224, v231 offset:3888
	ds_write_b16_d16_hi v224, v231 offset:3952
	s_branch .Lep0_00_st
.Lep0_00_stq:
	v_add_u32_e32 v233, s94, v227
	s_waitcnt lgkmcnt(0)
	ds_read_b128 v[206:209], v225
	ds_read_b128 v[212:215], v225 offset:1152
	ds_read_b128 v[216:219], v225 offset:2304
	ds_read_b128 v[220:223], v225 offset:3456
	v_add_u32_e32 v229, 0, v233
	v_mul_lo_u32 v229, v229, s89
	v_add3_u32 v229, v229, v228, s91
	v_add_u32_e32 v230, 8, v233
	v_mul_lo_u32 v230, v230, s89
	v_add3_u32 v230, v230, v228, s91
	v_add_u32_e32 v231, 16, v233
	v_mul_lo_u32 v231, v231, s89
	v_add3_u32 v231, v231, v228, s91
	v_add_u32_e32 v232, 24, v233
	v_mul_lo_u32 v232, v232, s89
	v_add3_u32 v232, v232, v228, s91
	s_waitcnt lgkmcnt(3)
	global_store_dwordx4 v229, v[206:209], s[96:97]
	s_waitcnt lgkmcnt(2)
	global_store_dwordx4 v230, v[212:215], s[96:97]
	s_waitcnt lgkmcnt(1)
	global_store_dwordx4 v231, v[216:219], s[96:97]
	s_waitcnt lgkmcnt(0)
	global_store_dwordx4 v232, v[220:223], s[96:97]
	v_lshlrev_b32_e32 v132, 16, v206
	v_and_b32_e32 v133, 0xffff0000, v206
	v_mul_f32_e32 v128, v132, v132
	v_fma_f32 v128, v133, v133, v128
	v_lshlrev_b32_e32 v132, 16, v207
	v_and_b32_e32 v133, 0xffff0000, v207
	v_fma_f32 v128, v132, v132, v128
	v_fma_f32 v128, v133, v133, v128
	v_lshlrev_b32_e32 v132, 16, v208
	v_and_b32_e32 v133, 0xffff0000, v208
	v_fma_f32 v128, v132, v132, v128
	v_fma_f32 v128, v133, v133, v128
	v_lshlrev_b32_e32 v132, 16, v209
	v_and_b32_e32 v133, 0xffff0000, v209
	v_fma_f32 v128, v132, v132, v128
	v_fma_f32 v128, v133, v133, v128
	v_lshlrev_b32_e32 v132, 16, v212
	v_and_b32_e32 v133, 0xffff0000, v212
	v_mul_f32_e32 v129, v132, v132
	v_fma_f32 v129, v133, v133, v129
	v_lshlrev_b32_e32 v132, 16, v213
	v_and_b32_e32 v133, 0xffff0000, v213
	v_fma_f32 v129, v132, v132, v129
	v_fma_f32 v129, v133, v133, v129
	v_lshlrev_b32_e32 v132, 16, v214
	v_and_b32_e32 v133, 0xffff0000, v214
	v_fma_f32 v129, v132, v132, v129
	v_fma_f32 v129, v133, v133, v129
	v_lshlrev_b32_e32 v132, 16, v215
	v_and_b32_e32 v133, 0xffff0000, v215
	v_fma_f32 v129, v132, v132, v129
	v_fma_f32 v129, v133, v133, v129
	v_lshlrev_b32_e32 v132, 16, v216
	v_and_b32_e32 v133, 0xffff0000, v216
	v_mul_f32_e32 v130, v132, v132
	v_fma_f32 v130, v133, v133, v130
	v_lshlrev_b32_e32 v132, 16, v217
	v_and_b32_e32 v133, 0xffff0000, v217
	v_fma_f32 v130, v132, v132, v130
	v_fma_f32 v130, v133, v133, v130
	v_lshlrev_b32_e32 v132, 16, v218
	v_and_b32_e32 v133, 0xffff0000, v218
	v_fma_f32 v130, v132, v132, v130
	v_fma_f32 v130, v133, v133, v130
	v_lshlrev_b32_e32 v132, 16, v219
	v_and_b32_e32 v133, 0xffff0000, v219
	v_fma_f32 v130, v132, v132, v130
	v_fma_f32 v130, v133, v133, v130
	v_lshlrev_b32_e32 v132, 16, v220
	v_and_b32_e32 v133, 0xffff0000, v220
	v_mul_f32_e32 v131, v132, v132
	v_fma_f32 v131, v133, v133, v131
	v_lshlrev_b32_e32 v132, 16, v221
	v_and_b32_e32 v133, 0xffff0000, v221
	v_fma_f32 v131, v132, v132, v131
	v_fma_f32 v131, v133, v133, v131
	v_lshlrev_b32_e32 v132, 16, v222
	v_and_b32_e32 v133, 0xffff0000, v222
	v_fma_f32 v131, v132, v132, v131
	v_fma_f32 v131, v133, v133, v131
	v_lshlrev_b32_e32 v132, 16, v223
	v_and_b32_e32 v133, 0xffff0000, v223
	v_fma_f32 v131, v132, v132, v131
	v_fma_f32 v131, v133, v133, v131
	s_nop 1
	v_add_f32_dpp v136, v128, v128 quad_perm:[1,0,3,2] row_mask:0xf bank_mask:0xf
	v_add_f32_dpp v137, v129, v129 quad_perm:[1,0,3,2] row_mask:0xf bank_mask:0xf
	v_add_f32_dpp v138, v130, v130 quad_perm:[1,0,3,2] row_mask:0xf bank_mask:0xf
	v_add_f32_dpp v139, v131, v131 quad_perm:[1,0,3,2] row_mask:0xf bank_mask:0xf
	v_add_f32_dpp v128, v136, v136 quad_perm:[2,3,0,1] row_mask:0xf bank_mask:0xf
	v_add_f32_dpp v129, v137, v137 quad_perm:[2,3,0,1] row_mask:0xf bank_mask:0xf
	v_add_f32_dpp v130, v138, v138 quad_perm:[2,3,0,1] row_mask:0xf bank_mask:0xf
	v_add_f32_dpp v131, v139, v139 quad_perm:[2,3,0,1] row_mask:0xf bank_mask:0xf
	v_add_f32_dpp v236, v128, v128 row_half_mirror row_mask:0xf bank_mask:0xf
	v_add_f32_dpp v237, v129, v129 row_half_mirror row_mask:0xf bank_mask:0xf
	v_add_f32_dpp v238, v130, v130 row_half_mirror row_mask:0xf bank_mask:0xf
	v_add_f32_dpp v239, v131, v131 row_half_mirror row_mask:0xf bank_mask:0xf
	s_branch .Lep0_00_end
.Lep0_00_stb:
	v_add_u32_e32 v233, s94, v227
	s_waitcnt lgkmcnt(0)
	ds_read_b128 v[206:209], v225
	ds_read_b128 v[212:215], v225 offset:1152
	ds_read_b128 v[216:219], v225 offset:2304
	ds_read_b128 v[220:223], v225 offset:3456
	s_mov_b32 s88, 0xc00000
	s_mov_b32 s89, 0x180
	v_add_u32_e32 v229, 0, v233
	v_lshrrev_b32_e32 v128, 12, v229
	v_and_b32_e32 v229, 0xfff, v229
	v_mul_lo_u32 v128, v128, s88
	v_mul_lo_u32 v229, v229, s89
	v_add3_u32 v229, v229, v128, v228
	v_add_u32_e32 v230, 8, v233
	v_lshrrev_b32_e32 v129, 12, v230
	v_and_b32_e32 v230, 0xfff, v230
	v_mul_lo_u32 v129, v129, s88
	v_mul_lo_u32 v230, v230, s89
	v_add3_u32 v230, v230, v129, v228
	v_add_u32_e32 v231, 16, v233
	v_lshrrev_b32_e32 v130, 12, v231
	v_and_b32_e32 v231, 0xfff, v231
	v_mul_lo_u32 v130, v130, s88
	v_mul_lo_u32 v231, v231, s89
	v_add3_u32 v231, v231, v130, v228
	v_add_u32_e32 v232, 24, v233
	v_lshrrev_b32_e32 v131, 12, v232
	v_and_b32_e32 v232, 0xfff, v232
	v_mul_lo_u32 v131, v131, s88
	v_mul_lo_u32 v232, v232, s89
	v_add3_u32 v232, v232, v131, v228
	s_waitcnt lgkmcnt(3)
	global_store_dwordx4 v229, v[206:209], s[96:97] offset:256
	v_add_u32_e32 v229, 0x180000, v229
	s_waitcnt lgkmcnt(2)
	global_store_dwordx4 v230, v[212:215], s[96:97] offset:256
	v_add_u32_e32 v230, 0x180000, v230
	s_waitcnt lgkmcnt(1)
	global_store_dwordx4 v231, v[216:219], s[96:97] offset:256
	v_add_u32_e32 v231, 0x180000, v231
	s_waitcnt lgkmcnt(0)
	global_store_dwordx4 v232, v[220:223], s[96:97] offset:256
	v_add_u32_e32 v232, 0x180000, v232
	global_store_dwordx4 v229, v[206:209], s[96:97] offset:256
	v_add_u32_e32 v229, 0x180000, v229
	global_store_dwordx4 v230, v[212:215], s[96:97] offset:256
	v_add_u32_e32 v230, 0x180000, v230
	global_store_dwordx4 v231, v[216:219], s[96:97] offset:256
	v_add_u32_e32 v231, 0x180000, v231
	global_store_dwordx4 v232, v[220:223], s[96:97] offset:256
	v_add_u32_e32 v232, 0x180000, v232
	global_store_dwordx4 v229, v[206:209], s[96:97] offset:256
	v_add_u32_e32 v229, 0x180000, v229
	global_store_dwordx4 v230, v[212:215], s[96:97] offset:256
	v_add_u32_e32 v230, 0x180000, v230
	global_store_dwordx4 v231, v[216:219], s[96:97] offset:256
	v_add_u32_e32 v231, 0x180000, v231
	global_store_dwordx4 v232, v[220:223], s[96:97] offset:256
	v_add_u32_e32 v232, 0x180000, v232
	global_store_dwordx4 v229, v[206:209], s[96:97] offset:256
	v_add_u32_e32 v229, 0x180000, v229
	global_store_dwordx4 v230, v[212:215], s[96:97] offset:256
	v_add_u32_e32 v230, 0x180000, v230
	global_store_dwordx4 v231, v[216:219], s[96:97] offset:256
	v_add_u32_e32 v231, 0x180000, v231
	global_store_dwordx4 v232, v[220:223], s[96:97] offset:256
	v_add_u32_e32 v232, 0x180000, v232
	global_store_dwordx4 v229, v[206:209], s[96:97] offset:256
	v_add_u32_e32 v229, 0x180000, v229
	global_store_dwordx4 v230, v[212:215], s[96:97] offset:256
	v_add_u32_e32 v230, 0x180000, v230
	global_store_dwordx4 v231, v[216:219], s[96:97] offset:256
	v_add_u32_e32 v231, 0x180000, v231
	global_store_dwordx4 v232, v[220:223], s[96:97] offset:256
	v_add_u32_e32 v232, 0x180000, v232
	global_store_dwordx4 v229, v[206:209], s[96:97] offset:256
	v_add_u32_e32 v229, 0x180000, v229
	global_store_dwordx4 v230, v[212:215], s[96:97] offset:256
	v_add_u32_e32 v230, 0x180000, v230
	global_store_dwordx4 v231, v[216:219], s[96:97] offset:256
	v_add_u32_e32 v231, 0x180000, v231
	global_store_dwordx4 v232, v[220:223], s[96:97] offset:256
	v_add_u32_e32 v232, 0x180000, v232
	global_store_dwordx4 v229, v[206:209], s[96:97] offset:256
	v_add_u32_e32 v229, 0x180000, v229
	global_store_dwordx4 v230, v[212:215], s[96:97] offset:256
	v_add_u32_e32 v230, 0x180000, v230
	global_store_dwordx4 v231, v[216:219], s[96:97] offset:256
	v_add_u32_e32 v231, 0x180000, v231
	global_store_dwordx4 v232, v[220:223], s[96:97] offset:256
	v_add_u32_e32 v232, 0x180000, v232
	global_store_dwordx4 v229, v[206:209], s[96:97] offset:256
	global_store_dwordx4 v230, v[212:215], s[96:97] offset:256
	global_store_dwordx4 v231, v[216:219], s[96:97] offset:256
	global_store_dwordx4 v232, v[220:223], s[96:97] offset:256
	s_branch .Lep0_00_end
.Lep0_00_st:
	v_add_u32_e32 v233, s94, v227
	s_waitcnt lgkmcnt(0)
	ds_read_b128 v[206:209], v225
	ds_read_b128 v[212:215], v225 offset:1152
	ds_read_b128 v[216:219], v225 offset:2304
	ds_read_b128 v[220:223], v225 offset:3456
	v_add_u32_e32 v229, 0, v233
	v_mul_lo_u32 v229, v229, s89
	v_add3_u32 v229, v229, v228, s91
	v_add_u32_e32 v230, 8, v233
	v_mul_lo_u32 v230, v230, s89
	v_add3_u32 v230, v230, v228, s91
	v_add_u32_e32 v231, 16, v233
	v_mul_lo_u32 v231, v231, s89
	v_add3_u32 v231, v231, v228, s91
	v_add_u32_e32 v232, 24, v233
	v_mul_lo_u32 v232, v232, s89
	v_add3_u32 v232, v232, v228, s91
	s_waitcnt lgkmcnt(3)
	global_store_dwordx4 v229, v[206:209], s[96:97]
	s_waitcnt lgkmcnt(2)
	global_store_dwordx4 v230, v[212:215], s[96:97]
	s_waitcnt lgkmcnt(1)
	global_store_dwordx4 v231, v[216:219], s[96:97]
	s_waitcnt lgkmcnt(0)
	global_store_dwordx4 v232, v[220:223], s[96:97]

.Lep0_01_mP:
	v_cvt_pk_bf16_f32 v229, v80, v64
	ds_write_b16 v224, v229
	ds_write_b16_d16_hi v224, v229 offset:64
	v_cvt_pk_bf16_f32 v230, v81, v65
	ds_write_b16 v224, v230 offset:144
	ds_write_b16_d16_hi v224, v230 offset:208
	v_cvt_pk_bf16_f32 v231, v82, v66
	ds_write_b16 v224, v231 offset:288
	ds_write_b16_d16_hi v224, v231 offset:352
	v_cvt_pk_bf16_f32 v232, v83, v67
	ds_write_b16 v224, v232 offset:432
	ds_write_b16_d16_hi v224, v232 offset:496
	v_cvt_pk_bf16_f32 v229, v84, v68
	ds_write_b16 v224, v229 offset:1152
	ds_write_b16_d16_hi v224, v229 offset:1216
	v_cvt_pk_bf16_f32 v230, v85, v69
	ds_write_b16 v224, v230 offset:1296
	ds_write_b16_d16_hi v224, v230 offset:1360
	v_cvt_pk_bf16_f32 v231, v86, v70
	ds_write_b16 v224, v231 offset:1440
	ds_write_b16_d16_hi v224, v231 offset:1504
	v_cvt_pk_bf16_f32 v232, v87, v71
	ds_write_b16 v224, v232 offset:1584
	ds_write_b16_d16_hi v224, v232 offset:1648
	v_cvt_pk_bf16_f32 v229, v88, v72
	ds_write_b16 v224, v229 offset:2304
	ds_write_b16_d16_hi v224, v229 offset:2368
	v_cvt_pk_bf16_f32 v230, v89, v73
	ds_write_b16 v224, v230 offset:2448
	ds_write_b16_d16_hi v224, v230 offset:2512
	v_cvt_pk_bf16_f32 v231, v90, v74
	ds_write_b16 v224, v231 offset:2592
	ds_write_b16_d16_hi v224, v231 offset:2656
	v_cvt_pk_bf16_f32 v232, v91, v75
	ds_write_b16 v224, v232 offset:2736
	ds_write_b16_d16_hi v224, v232 offset:2800
	v_cvt_pk_bf16_f32 v229, v92, v76
	ds_write_b16 v224, v229 offset:3456
	ds_write_b16_d16_hi v224, v229 offset:3520
	v_cvt_pk_bf16_f32 v230, v93, v77
	ds_write_b16 v224, v230 offset:3600
	ds_write_b16_d16_hi v224, v230 offset:3664
	v_cvt_pk_bf16_f32 v231, v94, v78
	ds_write_b16 v224, v231 offset:3744
	ds_write_b16_d16_hi v224, v231 offset:3808
	v_cvt_pk_bf16_f32 v232, v95, v79
	ds_write_b16 v224, v232 offset:3888
	ds_write_b16_d16_hi v224, v232 offset:3952
	s_branch .Lep0_01_stq
.Lep0_01_mR:
	s_load_dwordx2 s[98:99], s[0:1], 0x148
	v_add_u32_e32 v229, s94, v226
	v_lshlrev_b32_e32 v229, 8, v229
	v_add_u32_e32 v236, v229, v160
	v_mov_b32_e32 v237, 0
	s_waitcnt lgkmcnt(0)
	v_lshl_add_u64 v[236:237], s[98:99], 0, v[236:237]
	global_load_dwordx2 v[128:129], v[236:237], off
	global_load_dwordx2 v[130:131], v[236:237], off offset:256
	global_load_dwordx2 v[132:133], v[236:237], off offset:512
	global_load_dwordx2 v[134:135], v[236:237], off offset:768
	global_load_dwordx2 v[136:137], v[236:237], off offset:2048
	global_load_dwordx2 v[138:139], v[236:237], off offset:2304
	global_load_dwordx2 v[140:141], v[236:237], off offset:2560
	global_load_dwordx2 v[142:143], v[236:237], off offset:2816
	v_add_co_u32_e32 v238, vcc, 0x1000, v236
	s_nop 1
	v_addc_co_u32_e32 v239, vcc, 0, v237, vcc
	global_load_dwordx2 v[144:145], v[238:239], off
	global_load_dwordx2 v[146:147], v[238:239], off offset:256
	global_load_dwordx2 v[148:149], v[238:239], off offset:512
	global_load_dwordx2 v[150:151], v[238:239], off offset:768
	global_load_dwordx2 v[152:153], v[238:239], off offset:2048
	global_load_dwordx2 v[154:155], v[238:239], off offset:2304
	global_load_dwordx2 v[156:157], v[238:239], off offset:2560
	global_load_dwordx2 v[158:159], v[238:239], off offset:2816
	s_waitcnt vmcnt(15)
	v_mul_f32_e32 v229, v64, v129
	v_mul_f32_e32 v230, v80, v129
	v_fma_f32 v229, v80, v128, -v229
	v_fma_f32 v230, v64, v128, v230
	v_mul_f32_e32 v229, s88, v229
	v_mul_f32_e32 v230, s88, v230
	v_cvt_pk_bf16_f32 v229, v229, v230
	ds_write_b16 v224, v229
	ds_write_b16_d16_hi v224, v229 offset:64
	s_waitcnt vmcnt(14)
	v_mul_f32_e32 v229, v65, v131
	v_mul_f32_e32 v230, v81, v131
	v_fma_f32 v229, v81, v130, -v229
	v_fma_f32 v230, v65, v130, v230
	v_mul_f32_e32 v229, s88, v229
	v_mul_f32_e32 v230, s88, v230
	v_cvt_pk_bf16_f32 v229, v229, v230
	ds_write_b16 v224, v229 offset:144
	ds_write_b16_d16_hi v224, v229 offset:208
	s_waitcnt vmcnt(13)
	v_mul_f32_e32 v229, v66, v133
	v_mul_f32_e32 v230, v82, v133
	v_fma_f32 v229, v82, v132, -v229
	v_fma_f32 v230, v66, v132, v230
	v_mul_f32_e32 v229, s88, v229
	v_mul_f32_e32 v230, s88, v230
	v_cvt_pk_bf16_f32 v229, v229, v230
	ds_write_b16 v224, v229 offset:288
	ds_write_b16_d16_hi v224, v229 offset:352
	s_waitcnt vmcnt(12)
	v_mul_f32_e32 v229, v67, v135
	v_mul_f32_e32 v230, v83, v135
	v_fma_f32 v229, v83, v134, -v229
	v_fma_f32 v230, v67, v134, v230
	v_mul_f32_e32 v229, s88, v229
	v_mul_f32_e32 v230, s88, v230
	v_cvt_pk_bf16_f32 v229, v229, v230
	ds_write_b16 v224, v229 offset:432
	ds_write_b16_d16_hi v224, v229 offset:496
	s_waitcnt vmcnt(11)
	v_mul_f32_e32 v229, v68, v137
	v_mul_f32_e32 v230, v84, v137
	v_fma_f32 v229, v84, v136, -v229
	v_fma_f32 v230, v68, v136, v230
	v_mul_f32_e32 v229, s88, v229
	v_mul_f32_e32 v230, s88, v230
	v_cvt_pk_bf16_f32 v229, v229, v230
	ds_write_b16 v224, v229 offset:1152
	ds_write_b16_d16_hi v224, v229 offset:1216
	s_waitcnt vmcnt(10)
	v_mul_f32_e32 v229, v69, v139
	v_mul_f32_e32 v230, v85, v139
	v_fma_f32 v229, v85, v138, -v229
	v_fma_f32 v230, v69, v138, v230
	v_mul_f32_e32 v229, s88, v229
	v_mul_f32_e32 v230, s88, v230
	v_cvt_pk_bf16_f32 v229, v229, v230
	ds_write_b16 v224, v229 offset:1296
	ds_write_b16_d16_hi v224, v229 offset:1360
	s_waitcnt vmcnt(9)
	v_mul_f32_e32 v229, v70, v141
	v_mul_f32_e32 v230, v86, v141
	v_fma_f32 v229, v86, v140, -v229
	v_fma_f32 v230, v70, v140, v230
	v_mul_f32_e32 v229, s88, v229
	v_mul_f32_e32 v230, s88, v230
	v_cvt_pk_bf16_f32 v229, v229, v230
	ds_write_b16 v224, v229 offset:1440
	ds_write_b16_d16_hi v224, v229 offset:1504
	s_waitcnt vmcnt(8)
	v_mul_f32_e32 v229, v71, v143
	v_mul_f32_e32 v230, v87, v143
	v_fma_f32 v229, v87, v142, -v229
	v_fma_f32 v230, v71, v142, v230
	v_mul_f32_e32 v229, s88, v229
	v_mul_f32_e32 v230, s88, v230
	v_cvt_pk_bf16_f32 v229, v229, v230
	ds_write_b16 v224, v229 offset:1584
	ds_write_b16_d16_hi v224, v229 offset:1648
	s_waitcnt vmcnt(7)
	v_mul_f32_e32 v229, v72, v145
	v_mul_f32_e32 v230, v88, v145
	v_fma_f32 v229, v88, v144, -v229
	v_fma_f32 v230, v72, v144, v230
	v_mul_f32_e32 v229, s88, v229
	v_mul_f32_e32 v230, s88, v230
	v_cvt_pk_bf16_f32 v229, v229, v230
	ds_write_b16 v224, v229 offset:2304
	ds_write_b16_d16_hi v224, v229 offset:2368
	s_waitcnt vmcnt(6)
	v_mul_f32_e32 v229, v73, v147
	v_mul_f32_e32 v230, v89, v147
	v_fma_f32 v229, v89, v146, -v229
	v_fma_f32 v230, v73, v146, v230
	v_mul_f32_e32 v229, s88, v229
	v_mul_f32_e32 v230, s88, v230
	v_cvt_pk_bf16_f32 v229, v229, v230
	ds_write_b16 v224, v229 offset:2448
	ds_write_b16_d16_hi v224, v229 offset:2512
	s_waitcnt vmcnt(5)
	v_mul_f32_e32 v229, v74, v149
	v_mul_f32_e32 v230, v90, v149
	v_fma_f32 v229, v90, v148, -v229
	v_fma_f32 v230, v74, v148, v230
	v_mul_f32_e32 v229, s88, v229
	v_mul_f32_e32 v230, s88, v230
	v_cvt_pk_bf16_f32 v229, v229, v230
	ds_write_b16 v224, v229 offset:2592
	ds_write_b16_d16_hi v224, v229 offset:2656
	s_waitcnt vmcnt(4)
	v_mul_f32_e32 v229, v75, v151
	v_mul_f32_e32 v230, v91, v151
	v_fma_f32 v229, v91, v150, -v229
	v_fma_f32 v230, v75, v150, v230
	v_mul_f32_e32 v229, s88, v229
	v_mul_f32_e32 v230, s88, v230
	v_cvt_pk_bf16_f32 v229, v229, v230
	ds_write_b16 v224, v229 offset:2736
	ds_write_b16_d16_hi v224, v229 offset:2800
	s_waitcnt vmcnt(3)
	v_mul_f32_e32 v229, v76, v153
	v_mul_f32_e32 v230, v92, v153
	v_fma_f32 v229, v92, v152, -v229
	v_fma_f32 v230, v76, v152, v230
	v_mul_f32_e32 v229, s88, v229
	v_mul_f32_e32 v230, s88, v230
	v_cvt_pk_bf16_f32 v229, v229, v230
	ds_write_b16 v224, v229 offset:3456
	ds_write_b16_d16_hi v224, v229 offset:3520
	s_waitcnt vmcnt(2)
	v_mul_f32_e32 v229, v77, v155
	v_mul_f32_e32 v230, v93, v155
	v_fma_f32 v229, v93, v154, -v229
	v_fma_f32 v230, v77, v154, v230
	v_mul_f32_e32 v229, s88, v229
	v_mul_f32_e32 v230, s88, v230
	v_cvt_pk_bf16_f32 v229, v229, v230
	ds_write_b16 v224, v229 offset:3600
	ds_write_b16_d16_hi v224, v229 offset:3664
	s_waitcnt vmcnt(1)
	v_mul_f32_e32 v229, v78, v157
	v_mul_f32_e32 v230, v94, v157
	v_fma_f32 v229, v94, v156, -v229
	v_fma_f32 v230, v78, v156, v230
	v_mul_f32_e32 v229, s88, v229
	v_mul_f32_e32 v230, s88, v230
	v_cvt_pk_bf16_f32 v229, v229, v230
	ds_write_b16 v224, v229 offset:3744
	ds_write_b16_d16_hi v224, v229 offset:3808
	s_waitcnt vmcnt(0)
	v_mul_f32_e32 v229, v79, v159
	v_mul_f32_e32 v230, v95, v159
	v_fma_f32 v229, v95, v158, -v229
	v_fma_f32 v230, v79, v158, v230
	v_mul_f32_e32 v229, s88, v229
	v_mul_f32_e32 v230, s88, v230
	v_cvt_pk_bf16_f32 v229, v229, v230
	ds_write_b16 v224, v229 offset:3888
	ds_write_b16_d16_hi v224, v229 offset:3952
	s_branch .Lep0_01_stb
.Lep0_01_mS:
	v_mul_f32_e32 v229, 0xbfb8aa3b, v80
	v_mul_f32_e32 v230, 0xbfb8aa3b, v64
	v_exp_f32_e32 v229, v229
	v_exp_f32_e32 v230, v230
	v_add_f32_e32 v229, 1.0, v229
	v_add_f32_e32 v230, 1.0, v230
	v_rcp_f32_e32 v229, v229
	v_rcp_f32_e32 v230, v230
	v_mul_f32_e32 v229, v80, v229
	v_mul_f32_e32 v230, v64, v230
	v_cvt_pk_bf16_f32 v229, v229, v230
	ds_write_b16 v224, v229
	ds_write_b16_d16_hi v224, v229 offset:64
	v_mul_f32_e32 v231, 0xbfb8aa3b, v81
	v_mul_f32_e32 v232, 0xbfb8aa3b, v65
	v_exp_f32_e32 v231, v231
	v_exp_f32_e32 v232, v232
	v_add_f32_e32 v231, 1.0, v231
	v_add_f32_e32 v232, 1.0, v232
	v_rcp_f32_e32 v231, v231
	v_rcp_f32_e32 v232, v232
	v_mul_f32_e32 v231, v81, v231
	v_mul_f32_e32 v232, v65, v232
	v_cvt_pk_bf16_f32 v231, v231, v232
	ds_write_b16 v224, v231 offset:144
	ds_write_b16_d16_hi v224, v231 offset:208
	v_mul_f32_e32 v229, 0xbfb8aa3b, v82
	v_mul_f32_e32 v230, 0xbfb8aa3b, v66
	v_exp_f32_e32 v229, v229
	v_exp_f32_e32 v230, v230
	v_add_f32_e32 v229, 1.0, v229
	v_add_f32_e32 v230, 1.0, v230
	v_rcp_f32_e32 v229, v229
	v_rcp_f32_e32 v230, v230
	v_mul_f32_e32 v229, v82, v229
	v_mul_f32_e32 v230, v66, v230
	v_cvt_pk_bf16_f32 v229, v229, v230
	ds_write_b16 v224, v229 offset:288
	ds_write_b16_d16_hi v224, v229 offset:352
	v_mul_f32_e32 v231, 0xbfb8aa3b, v83
	v_mul_f32_e32 v232, 0xbfb8aa3b, v67
	v_exp_f32_e32 v231, v231
	v_exp_f32_e32 v232, v232
	v_add_f32_e32 v231, 1.0, v231
	v_add_f32_e32 v232, 1.0, v232
	v_rcp_f32_e32 v231, v231
	v_rcp_f32_e32 v232, v232
	v_mul_f32_e32 v231, v83, v231
	v_mul_f32_e32 v232, v67, v232
	v_cvt_pk_bf16_f32 v231, v231, v232
	ds_write_b16 v224, v231 offset:432
	ds_write_b16_d16_hi v224, v231 offset:496
	v_mul_f32_e32 v229, 0xbfb8aa3b, v84
	v_mul_f32_e32 v230, 0xbfb8aa3b, v68
	v_exp_f32_e32 v229, v229
	v_exp_f32_e32 v230, v230
	v_add_f32_e32 v229, 1.0, v229
	v_add_f32_e32 v230, 1.0, v230
	v_rcp_f32_e32 v229, v229
	v_rcp_f32_e32 v230, v230
	v_mul_f32_e32 v229, v84, v229
	v_mul_f32_e32 v230, v68, v230
	v_cvt_pk_bf16_f32 v229, v229, v230
	ds_write_b16 v224, v229 offset:1152
	ds_write_b16_d16_hi v224, v229 offset:1216
	v_mul_f32_e32 v231, 0xbfb8aa3b, v85
	v_mul_f32_e32 v232, 0xbfb8aa3b, v69
	v_exp_f32_e32 v231, v231
	v_exp_f32_e32 v232, v232
	v_add_f32_e32 v231, 1.0, v231
	v_add_f32_e32 v232, 1.0, v232
	v_rcp_f32_e32 v231, v231
	v_rcp_f32_e32 v232, v232
	v_mul_f32_e32 v231, v85, v231
	v_mul_f32_e32 v232, v69, v232
	v_cvt_pk_bf16_f32 v231, v231, v232
	ds_write_b16 v224, v231 offset:1296
	ds_write_b16_d16_hi v224, v231 offset:1360
	v_mul_f32_e32 v229, 0xbfb8aa3b, v86
	v_mul_f32_e32 v230, 0xbfb8aa3b, v70
	v_exp_f32_e32 v229, v229
	v_exp_f32_e32 v230, v230
	v_add_f32_e32 v229, 1.0, v229
	v_add_f32_e32 v230, 1.0, v230
	v_rcp_f32_e32 v229, v229
	v_rcp_f32_e32 v230, v230
	v_mul_f32_e32 v229, v86, v229
	v_mul_f32_e32 v230, v70, v230
	v_cvt_pk_bf16_f32 v229, v229, v230
	ds_write_b16 v224, v229 offset:1440
	ds_write_b16_d16_hi v224, v229 offset:1504
	v_mul_f32_e32 v231, 0xbfb8aa3b, v87
	v_mul_f32_e32 v232, 0xbfb8aa3b, v71
	v_exp_f32_e32 v231, v231
	v_exp_f32_e32 v232, v232
	v_add_f32_e32 v231, 1.0, v231
	v_add_f32_e32 v232, 1.0, v232
	v_rcp_f32_e32 v231, v231
	v_rcp_f32_e32 v232, v232
	v_mul_f32_e32 v231, v87, v231
	v_mul_f32_e32 v232, v71, v232
	v_cvt_pk_bf16_f32 v231, v231, v232
	ds_write_b16 v224, v231 offset:1584
	ds_write_b16_d16_hi v224, v231 offset:1648
	v_mul_f32_e32 v229, 0xbfb8aa3b, v88
	v_mul_f32_e32 v230, 0xbfb8aa3b, v72
	v_exp_f32_e32 v229, v229
	v_exp_f32_e32 v230, v230
	v_add_f32_e32 v229, 1.0, v229
	v_add_f32_e32 v230, 1.0, v230
	v_rcp_f32_e32 v229, v229
	v_rcp_f32_e32 v230, v230
	v_mul_f32_e32 v229, v88, v229
	v_mul_f32_e32 v230, v72, v230
	v_cvt_pk_bf16_f32 v229, v229, v230
	ds_write_b16 v224, v229 offset:2304
	ds_write_b16_d16_hi v224, v229 offset:2368
	v_mul_f32_e32 v231, 0xbfb8aa3b, v89
	v_mul_f32_e32 v232, 0xbfb8aa3b, v73
	v_exp_f32_e32 v231, v231
	v_exp_f32_e32 v232, v232
	v_add_f32_e32 v231, 1.0, v231
	v_add_f32_e32 v232, 1.0, v232
	v_rcp_f32_e32 v231, v231
	v_rcp_f32_e32 v232, v232
	v_mul_f32_e32 v231, v89, v231
	v_mul_f32_e32 v232, v73, v232
	v_cvt_pk_bf16_f32 v231, v231, v232
	ds_write_b16 v224, v231 offset:2448
	ds_write_b16_d16_hi v224, v231 offset:2512
	v_mul_f32_e32 v229, 0xbfb8aa3b, v90
	v_mul_f32_e32 v230, 0xbfb8aa3b, v74
	v_exp_f32_e32 v229, v229
	v_exp_f32_e32 v230, v230
	v_add_f32_e32 v229, 1.0, v229
	v_add_f32_e32 v230, 1.0, v230
	v_rcp_f32_e32 v229, v229
	v_rcp_f32_e32 v230, v230
	v_mul_f32_e32 v229, v90, v229
	v_mul_f32_e32 v230, v74, v230
	v_cvt_pk_bf16_f32 v229, v229, v230
	ds_write_b16 v224, v229 offset:2592
	ds_write_b16_d16_hi v224, v229 offset:2656
	v_mul_f32_e32 v231, 0xbfb8aa3b, v91
	v_mul_f32_e32 v232, 0xbfb8aa3b, v75
	v_exp_f32_e32 v231, v231
	v_exp_f32_e32 v232, v232
	v_add_f32_e32 v231, 1.0, v231
	v_add_f32_e32 v232, 1.0, v232
	v_rcp_f32_e32 v231, v231
	v_rcp_f32_e32 v232, v232
	v_mul_f32_e32 v231, v91, v231
	v_mul_f32_e32 v232, v75, v232
	v_cvt_pk_bf16_f32 v231, v231, v232
	ds_write_b16 v224, v231 offset:2736
	ds_write_b16_d16_hi v224, v231 offset:2800
	v_mul_f32_e32 v229, 0xbfb8aa3b, v92
	v_mul_f32_e32 v230, 0xbfb8aa3b, v76
	v_exp_f32_e32 v229, v229
	v_exp_f32_e32 v230, v230
	v_add_f32_e32 v229, 1.0, v229
	v_add_f32_e32 v230, 1.0, v230
	v_rcp_f32_e32 v229, v229
	v_rcp_f32_e32 v230, v230
	v_mul_f32_e32 v229, v92, v229
	v_mul_f32_e32 v230, v76, v230
	v_cvt_pk_bf16_f32 v229, v229, v230
	ds_write_b16 v224, v229 offset:3456
	ds_write_b16_d16_hi v224, v229 offset:3520
	v_mul_f32_e32 v231, 0xbfb8aa3b, v93
	v_mul_f32_e32 v232, 0xbfb8aa3b, v77
	v_exp_f32_e32 v231, v231
	v_exp_f32_e32 v232, v232
	v_add_f32_e32 v231, 1.0, v231
	v_add_f32_e32 v232, 1.0, v232
	v_rcp_f32_e32 v231, v231
	v_rcp_f32_e32 v232, v232
	v_mul_f32_e32 v231, v93, v231
	v_mul_f32_e32 v232, v77, v232
	v_cvt_pk_bf16_f32 v231, v231, v232
	ds_write_b16 v224, v231 offset:3600
	ds_write_b16_d16_hi v224, v231 offset:3664
	v_mul_f32_e32 v229, 0xbfb8aa3b, v94
	v_mul_f32_e32 v230, 0xbfb8aa3b, v78
	v_exp_f32_e32 v229, v229
	v_exp_f32_e32 v230, v230
	v_add_f32_e32 v229, 1.0, v229
	v_add_f32_e32 v230, 1.0, v230
	v_rcp_f32_e32 v229, v229
	v_rcp_f32_e32 v230, v230
	v_mul_f32_e32 v229, v94, v229
	v_mul_f32_e32 v230, v78, v230
	v_cvt_pk_bf16_f32 v229, v229, v230
	ds_write_b16 v224, v229 offset:3744
	ds_write_b16_d16_hi v224, v229 offset:3808
	v_mul_f32_e32 v231, 0xbfb8aa3b, v95
	v_mul_f32_e32 v232, 0xbfb8aa3b, v79
	v_exp_f32_e32 v231, v231
	v_exp_f32_e32 v232, v232
	v_add_f32_e32 v231, 1.0, v231
	v_add_f32_e32 v232, 1.0, v232
	v_rcp_f32_e32 v231, v231
	v_rcp_f32_e32 v232, v232
	v_mul_f32_e32 v231, v95, v231
	v_mul_f32_e32 v232, v79, v232
	v_cvt_pk_bf16_f32 v231, v231, v232
	ds_write_b16 v224, v231 offset:3888
	ds_write_b16_d16_hi v224, v231 offset:3952
	s_branch .Lep0_01_st
.Lep0_01_stq:
	v_add_u32_e32 v233, s94, v227
	s_waitcnt lgkmcnt(0)
	ds_read_b128 v[206:209], v225
	ds_read_b128 v[212:215], v225 offset:1152
	ds_read_b128 v[216:219], v225 offset:2304
	ds_read_b128 v[220:223], v225 offset:3456
	v_add_u32_e32 v229, 0, v233
	v_mul_lo_u32 v229, v229, s89
	v_add3_u32 v229, v229, v228, s91
	v_add_u32_e32 v230, 8, v233
	v_mul_lo_u32 v230, v230, s89
	v_add3_u32 v230, v230, v228, s91
	v_add_u32_e32 v231, 16, v233
	v_mul_lo_u32 v231, v231, s89
	v_add3_u32 v231, v231, v228, s91
	v_add_u32_e32 v232, 24, v233
	v_mul_lo_u32 v232, v232, s89
	v_add3_u32 v232, v232, v228, s91
	s_waitcnt lgkmcnt(3)
	global_store_dwordx4 v229, v[206:209], s[96:97]
	s_waitcnt lgkmcnt(2)
	global_store_dwordx4 v230, v[212:215], s[96:97]
	s_waitcnt lgkmcnt(1)
	global_store_dwordx4 v231, v[216:219], s[96:97]
	s_waitcnt lgkmcnt(0)
	global_store_dwordx4 v232, v[220:223], s[96:97]
	v_lshlrev_b32_e32 v132, 16, v206
	v_and_b32_e32 v133, 0xffff0000, v206
	v_mul_f32_e32 v128, v132, v132
	v_fma_f32 v128, v133, v133, v128
	v_lshlrev_b32_e32 v132, 16, v207
	v_and_b32_e32 v133, 0xffff0000, v207
	v_fma_f32 v128, v132, v132, v128
	v_fma_f32 v128, v133, v133, v128
	v_lshlrev_b32_e32 v132, 16, v208
	v_and_b32_e32 v133, 0xffff0000, v208
	v_fma_f32 v128, v132, v132, v128
	v_fma_f32 v128, v133, v133, v128
	v_lshlrev_b32_e32 v132, 16, v209
	v_and_b32_e32 v133, 0xffff0000, v209
	v_fma_f32 v128, v132, v132, v128
	v_fma_f32 v128, v133, v133, v128
	v_lshlrev_b32_e32 v132, 16, v212
	v_and_b32_e32 v133, 0xffff0000, v212
	v_mul_f32_e32 v129, v132, v132
	v_fma_f32 v129, v133, v133, v129
	v_lshlrev_b32_e32 v132, 16, v213
	v_and_b32_e32 v133, 0xffff0000, v213
	v_fma_f32 v129, v132, v132, v129
	v_fma_f32 v129, v133, v133, v129
	v_lshlrev_b32_e32 v132, 16, v214
	v_and_b32_e32 v133, 0xffff0000, v214
	v_fma_f32 v129, v132, v132, v129
	v_fma_f32 v129, v133, v133, v129
	v_lshlrev_b32_e32 v132, 16, v215
	v_and_b32_e32 v133, 0xffff0000, v215
	v_fma_f32 v129, v132, v132, v129
	v_fma_f32 v129, v133, v133, v129
	v_lshlrev_b32_e32 v132, 16, v216
	v_and_b32_e32 v133, 0xffff0000, v216
	v_mul_f32_e32 v130, v132, v132
	v_fma_f32 v130, v133, v133, v130
	v_lshlrev_b32_e32 v132, 16, v217
	v_and_b32_e32 v133, 0xffff0000, v217
	v_fma_f32 v130, v132, v132, v130
	v_fma_f32 v130, v133, v133, v130
	v_lshlrev_b32_e32 v132, 16, v218
	v_and_b32_e32 v133, 0xffff0000, v218
	v_fma_f32 v130, v132, v132, v130
	v_fma_f32 v130, v133, v133, v130
	v_lshlrev_b32_e32 v132, 16, v219
	v_and_b32_e32 v133, 0xffff0000, v219
	v_fma_f32 v130, v132, v132, v130
	v_fma_f32 v130, v133, v133, v130
	v_lshlrev_b32_e32 v132, 16, v220
	v_and_b32_e32 v133, 0xffff0000, v220
	v_mul_f32_e32 v131, v132, v132
	v_fma_f32 v131, v133, v133, v131
	v_lshlrev_b32_e32 v132, 16, v221
	v_and_b32_e32 v133, 0xffff0000, v221
	v_fma_f32 v131, v132, v132, v131
	v_fma_f32 v131, v133, v133, v131
	v_lshlrev_b32_e32 v132, 16, v222
	v_and_b32_e32 v133, 0xffff0000, v222
	v_fma_f32 v131, v132, v132, v131
	v_fma_f32 v131, v133, v133, v131
	v_lshlrev_b32_e32 v132, 16, v223
	v_and_b32_e32 v133, 0xffff0000, v223
	v_fma_f32 v131, v132, v132, v131
	v_fma_f32 v131, v133, v133, v131
	s_nop 1
	v_add_f32_dpp v136, v128, v128 quad_perm:[1,0,3,2] row_mask:0xf bank_mask:0xf
	v_add_f32_dpp v137, v129, v129 quad_perm:[1,0,3,2] row_mask:0xf bank_mask:0xf
	v_add_f32_dpp v138, v130, v130 quad_perm:[1,0,3,2] row_mask:0xf bank_mask:0xf
	v_add_f32_dpp v139, v131, v131 quad_perm:[1,0,3,2] row_mask:0xf bank_mask:0xf
	v_add_f32_dpp v128, v136, v136 quad_perm:[2,3,0,1] row_mask:0xf bank_mask:0xf
	v_add_f32_dpp v129, v137, v137 quad_perm:[2,3,0,1] row_mask:0xf bank_mask:0xf
	v_add_f32_dpp v130, v138, v138 quad_perm:[2,3,0,1] row_mask:0xf bank_mask:0xf
	v_add_f32_dpp v131, v139, v139 quad_perm:[2,3,0,1] row_mask:0xf bank_mask:0xf
	v_add_f32_dpp v136, v128, v128 row_half_mirror row_mask:0xf bank_mask:0xf
	v_add_f32_dpp v137, v129, v129 row_half_mirror row_mask:0xf bank_mask:0xf
	v_add_f32_dpp v138, v130, v130 row_half_mirror row_mask:0xf bank_mask:0xf
	v_add_f32_dpp v139, v131, v131 row_half_mirror row_mask:0xf bank_mask:0xf
	v_add_f32_e32 v136, v236, v136
	v_add_f32_e32 v137, v237, v137
	v_add_f32_e32 v138, v238, v138
	v_add_f32_e32 v139, v239, v139
	v_cmp_eq_u32_e32 vcc, 0, v228
	v_add_u32_e32 v229, 0, v233
	v_lshlrev_b32_e32 v229, 2, v229
	v_add_u32_e32 v230, 8, v233
	v_lshlrev_b32_e32 v230, 2, v230
	v_add_u32_e32 v231, 16, v233
	v_lshlrev_b32_e32 v231, 2, v231
	v_add_u32_e32 v232, 24, v233
	v_lshlrev_b32_e32 v232, 2, v232
	s_and_b64 exec, exec, vcc
	global_atomic_add_f32 v229, v136, s[98:99]
	global_atomic_add_f32 v230, v137, s[98:99]
	global_atomic_add_f32 v231, v138, s[98:99]
	global_atomic_add_f32 v232, v139, s[98:99]
	s_mov_b64 exec, -1
	s_branch .Lep0_01_end

.Lep0_10_mP:
	v_cvt_pk_bf16_f32 v229, v48, v32
	ds_write_b16 v224, v229
	ds_write_b16_d16_hi v224, v229 offset:64
	v_cvt_pk_bf16_f32 v230, v49, v33
	ds_write_b16 v224, v230 offset:144
	ds_write_b16_d16_hi v224, v230 offset:208
	v_cvt_pk_bf16_f32 v231, v50, v34
	ds_write_b16 v224, v231 offset:288
	ds_write_b16_d16_hi v224, v231 offset:352
	v_cvt_pk_bf16_f32 v232, v51, v35
	ds_write_b16 v224, v232 offset:432
	ds_write_b16_d16_hi v224, v232 offset:496
	v_cvt_pk_bf16_f32 v229, v52, v36
	ds_write_b16 v224, v229 offset:1152
	ds_write_b16_d16_hi v224, v229 offset:1216
	v_cvt_pk_bf16_f32 v230, v53, v37
	ds_write_b16 v224, v230 offset:1296
	ds_write_b16_d16_hi v224, v230 offset:1360
	v_cvt_pk_bf16_f32 v231, v54, v38
	ds_write_b16 v224, v231 offset:1440
	ds_write_b16_d16_hi v224, v231 offset:1504
	v_cvt_pk_bf16_f32 v232, v55, v39
	ds_write_b16 v224, v232 offset:1584
	ds_write_b16_d16_hi v224, v232 offset:1648
	v_cvt_pk_bf16_f32 v229, v56, v40
	ds_write_b16 v224, v229 offset:2304
	ds_write_b16_d16_hi v224, v229 offset:2368
	v_cvt_pk_bf16_f32 v230, v57, v41
	ds_write_b16 v224, v230 offset:2448
	ds_write_b16_d16_hi v224, v230 offset:2512
	v_cvt_pk_bf16_f32 v231, v58, v42
	ds_write_b16 v224, v231 offset:2592
	ds_write_b16_d16_hi v224, v231 offset:2656
	v_cvt_pk_bf16_f32 v232, v59, v43
	ds_write_b16 v224, v232 offset:2736
	ds_write_b16_d16_hi v224, v232 offset:2800
	v_cvt_pk_bf16_f32 v229, v60, v44
	ds_write_b16 v224, v229 offset:3456
	ds_write_b16_d16_hi v224, v229 offset:3520
	v_cvt_pk_bf16_f32 v230, v61, v45
	ds_write_b16 v224, v230 offset:3600
	ds_write_b16_d16_hi v224, v230 offset:3664
	v_cvt_pk_bf16_f32 v231, v62, v46
	ds_write_b16 v224, v231 offset:3744
	ds_write_b16_d16_hi v224, v231 offset:3808
	v_cvt_pk_bf16_f32 v232, v63, v47
	ds_write_b16 v224, v232 offset:3888
	ds_write_b16_d16_hi v224, v232 offset:3952
	s_branch .Lep0_10_stq
.Lep0_10_mR:
	s_load_dwordx2 s[98:99], s[0:1], 0x148
	v_add_u32_e32 v229, s94, v226
	v_lshlrev_b32_e32 v229, 8, v229
	v_add_u32_e32 v236, v229, v160
	v_mov_b32_e32 v237, 0
	s_waitcnt lgkmcnt(0)
	v_lshl_add_u64 v[236:237], s[98:99], 0, v[236:237]
	global_load_dwordx2 v[128:129], v[236:237], off
	global_load_dwordx2 v[130:131], v[236:237], off offset:256
	global_load_dwordx2 v[132:133], v[236:237], off offset:512
	global_load_dwordx2 v[134:135], v[236:237], off offset:768
	global_load_dwordx2 v[136:137], v[236:237], off offset:2048
	global_load_dwordx2 v[138:139], v[236:237], off offset:2304
	global_load_dwordx2 v[140:141], v[236:237], off offset:2560
	global_load_dwordx2 v[142:143], v[236:237], off offset:2816
	v_add_co_u32_e32 v238, vcc, 0x1000, v236
	s_nop 1
	v_addc_co_u32_e32 v239, vcc, 0, v237, vcc
	global_load_dwordx2 v[144:145], v[238:239], off
	global_load_dwordx2 v[146:147], v[238:239], off offset:256
	global_load_dwordx2 v[148:149], v[238:239], off offset:512
	global_load_dwordx2 v[150:151], v[238:239], off offset:768
	global_load_dwordx2 v[152:153], v[238:239], off offset:2048
	global_load_dwordx2 v[154:155], v[238:239], off offset:2304
	global_load_dwordx2 v[156:157], v[238:239], off offset:2560
	global_load_dwordx2 v[158:159], v[238:239], off offset:2816
	s_waitcnt vmcnt(15)
	v_mul_f32_e32 v229, v32, v129
	v_mul_f32_e32 v230, v48, v129
	v_fma_f32 v229, v48, v128, -v229
	v_fma_f32 v230, v32, v128, v230
	v_mul_f32_e32 v229, s88, v229
	v_mul_f32_e32 v230, s88, v230
	v_cvt_pk_bf16_f32 v229, v229, v230
	ds_write_b16 v224, v229
	ds_write_b16_d16_hi v224, v229 offset:64
	s_waitcnt vmcnt(14)
	v_mul_f32_e32 v229, v33, v131
	v_mul_f32_e32 v230, v49, v131
	v_fma_f32 v229, v49, v130, -v229
	v_fma_f32 v230, v33, v130, v230
	v_mul_f32_e32 v229, s88, v229
	v_mul_f32_e32 v230, s88, v230
	v_cvt_pk_bf16_f32 v229, v229, v230
	ds_write_b16 v224, v229 offset:144
	ds_write_b16_d16_hi v224, v229 offset:208
	s_waitcnt vmcnt(13)
	v_mul_f32_e32 v229, v34, v133
	v_mul_f32_e32 v230, v50, v133
	v_fma_f32 v229, v50, v132, -v229
	v_fma_f32 v230, v34, v132, v230
	v_mul_f32_e32 v229, s88, v229
	v_mul_f32_e32 v230, s88, v230
	v_cvt_pk_bf16_f32 v229, v229, v230
	ds_write_b16 v224, v229 offset:288
	ds_write_b16_d16_hi v224, v229 offset:352
	s_waitcnt vmcnt(12)
	v_mul_f32_e32 v229, v35, v135
	v_mul_f32_e32 v230, v51, v135
	v_fma_f32 v229, v51, v134, -v229
	v_fma_f32 v230, v35, v134, v230
	v_mul_f32_e32 v229, s88, v229
	v_mul_f32_e32 v230, s88, v230
	v_cvt_pk_bf16_f32 v229, v229, v230
	ds_write_b16 v224, v229 offset:432
	ds_write_b16_d16_hi v224, v229 offset:496
	s_waitcnt vmcnt(11)
	v_mul_f32_e32 v229, v36, v137
	v_mul_f32_e32 v230, v52, v137
	v_fma_f32 v229, v52, v136, -v229
	v_fma_f32 v230, v36, v136, v230
	v_mul_f32_e32 v229, s88, v229
	v_mul_f32_e32 v230, s88, v230
	v_cvt_pk_bf16_f32 v229, v229, v230
	ds_write_b16 v224, v229 offset:1152
	ds_write_b16_d16_hi v224, v229 offset:1216
	s_waitcnt vmcnt(10)
	v_mul_f32_e32 v229, v37, v139
	v_mul_f32_e32 v230, v53, v139
	v_fma_f32 v229, v53, v138, -v229
	v_fma_f32 v230, v37, v138, v230
	v_mul_f32_e32 v229, s88, v229
	v_mul_f32_e32 v230, s88, v230
	v_cvt_pk_bf16_f32 v229, v229, v230
	ds_write_b16 v224, v229 offset:1296
	ds_write_b16_d16_hi v224, v229 offset:1360
	s_waitcnt vmcnt(9)
	v_mul_f32_e32 v229, v38, v141
	v_mul_f32_e32 v230, v54, v141
	v_fma_f32 v229, v54, v140, -v229
	v_fma_f32 v230, v38, v140, v230
	v_mul_f32_e32 v229, s88, v229
	v_mul_f32_e32 v230, s88, v230
	v_cvt_pk_bf16_f32 v229, v229, v230
	ds_write_b16 v224, v229 offset:1440
	ds_write_b16_d16_hi v224, v229 offset:1504
	s_waitcnt vmcnt(8)
	v_mul_f32_e32 v229, v39, v143
	v_mul_f32_e32 v230, v55, v143
	v_fma_f32 v229, v55, v142, -v229
	v_fma_f32 v230, v39, v142, v230
	v_mul_f32_e32 v229, s88, v229
	v_mul_f32_e32 v230, s88, v230
	v_cvt_pk_bf16_f32 v229, v229, v230
	ds_write_b16 v224, v229 offset:1584
	ds_write_b16_d16_hi v224, v229 offset:1648
	s_waitcnt vmcnt(7)
	v_mul_f32_e32 v229, v40, v145
	v_mul_f32_e32 v230, v56, v145
	v_fma_f32 v229, v56, v144, -v229
	v_fma_f32 v230, v40, v144, v230
	v_mul_f32_e32 v229, s88, v229
	v_mul_f32_e32 v230, s88, v230
	v_cvt_pk_bf16_f32 v229, v229, v230
	ds_write_b16 v224, v229 offset:2304
	ds_write_b16_d16_hi v224, v229 offset:2368
	s_waitcnt vmcnt(6)
	v_mul_f32_e32 v229, v41, v147
	v_mul_f32_e32 v230, v57, v147
	v_fma_f32 v229, v57, v146, -v229
	v_fma_f32 v230, v41, v146, v230
	v_mul_f32_e32 v229, s88, v229
	v_mul_f32_e32 v230, s88, v230
	v_cvt_pk_bf16_f32 v229, v229, v230
	ds_write_b16 v224, v229 offset:2448
	ds_write_b16_d16_hi v224, v229 offset:2512
	s_waitcnt vmcnt(5)
	v_mul_f32_e32 v229, v42, v149
	v_mul_f32_e32 v230, v58, v149
	v_fma_f32 v229, v58, v148, -v229
	v_fma_f32 v230, v42, v148, v230
	v_mul_f32_e32 v229, s88, v229
	v_mul_f32_e32 v230, s88, v230
	v_cvt_pk_bf16_f32 v229, v229, v230
	ds_write_b16 v224, v229 offset:2592
	ds_write_b16_d16_hi v224, v229 offset:2656
	s_waitcnt vmcnt(4)
	v_mul_f32_e32 v229, v43, v151
	v_mul_f32_e32 v230, v59, v151
	v_fma_f32 v229, v59, v150, -v229
	v_fma_f32 v230, v43, v150, v230
	v_mul_f32_e32 v229, s88, v229
	v_mul_f32_e32 v230, s88, v230
	v_cvt_pk_bf16_f32 v229, v229, v230
	ds_write_b16 v224, v229 offset:2736
	ds_write_b16_d16_hi v224, v229 offset:2800
	s_waitcnt vmcnt(3)
	v_mul_f32_e32 v229, v44, v153
	v_mul_f32_e32 v230, v60, v153
	v_fma_f32 v229, v60, v152, -v229
	v_fma_f32 v230, v44, v152, v230
	v_mul_f32_e32 v229, s88, v229
	v_mul_f32_e32 v230, s88, v230
	v_cvt_pk_bf16_f32 v229, v229, v230
	ds_write_b16 v224, v229 offset:3456
	ds_write_b16_d16_hi v224, v229 offset:3520
	s_waitcnt vmcnt(2)
	v_mul_f32_e32 v229, v45, v155
	v_mul_f32_e32 v230, v61, v155
	v_fma_f32 v229, v61, v154, -v229
	v_fma_f32 v230, v45, v154, v230
	v_mul_f32_e32 v229, s88, v229
	v_mul_f32_e32 v230, s88, v230
	v_cvt_pk_bf16_f32 v229, v229, v230
	ds_write_b16 v224, v229 offset:3600
	ds_write_b16_d16_hi v224, v229 offset:3664
	s_waitcnt vmcnt(1)
	v_mul_f32_e32 v229, v46, v157
	v_mul_f32_e32 v230, v62, v157
	v_fma_f32 v229, v62, v156, -v229
	v_fma_f32 v230, v46, v156, v230
	v_mul_f32_e32 v229, s88, v229
	v_mul_f32_e32 v230, s88, v230
	v_cvt_pk_bf16_f32 v229, v229, v230
	ds_write_b16 v224, v229 offset:3744
	ds_write_b16_d16_hi v224, v229 offset:3808
	s_waitcnt vmcnt(0)
	v_mul_f32_e32 v229, v47, v159
	v_mul_f32_e32 v230, v63, v159
	v_fma_f32 v229, v63, v158, -v229
	v_fma_f32 v230, v47, v158, v230
	v_mul_f32_e32 v229, s88, v229
	v_mul_f32_e32 v230, s88, v230
	v_cvt_pk_bf16_f32 v229, v229, v230
	ds_write_b16 v224, v229 offset:3888
	ds_write_b16_d16_hi v224, v229 offset:3952
	s_branch .Lep0_10_stb
.Lep0_10_mS:
	v_mul_f32_e32 v229, 0xbfb8aa3b, v48
	v_mul_f32_e32 v230, 0xbfb8aa3b, v32
	v_exp_f32_e32 v229, v229
	v_exp_f32_e32 v230, v230
	v_add_f32_e32 v229, 1.0, v229
	v_add_f32_e32 v230, 1.0, v230
	v_rcp_f32_e32 v229, v229
	v_rcp_f32_e32 v230, v230
	v_mul_f32_e32 v229, v48, v229
	v_mul_f32_e32 v230, v32, v230
	v_cvt_pk_bf16_f32 v229, v229, v230
	ds_write_b16 v224, v229
	ds_write_b16_d16_hi v224, v229 offset:64
	v_mul_f32_e32 v231, 0xbfb8aa3b, v49
	v_mul_f32_e32 v232, 0xbfb8aa3b, v33
	v_exp_f32_e32 v231, v231
	v_exp_f32_e32 v232, v232
	v_add_f32_e32 v231, 1.0, v231
	v_add_f32_e32 v232, 1.0, v232
	v_rcp_f32_e32 v231, v231
	v_rcp_f32_e32 v232, v232
	v_mul_f32_e32 v231, v49, v231
	v_mul_f32_e32 v232, v33, v232
	v_cvt_pk_bf16_f32 v231, v231, v232
	ds_write_b16 v224, v231 offset:144
	ds_write_b16_d16_hi v224, v231 offset:208
	v_mul_f32_e32 v229, 0xbfb8aa3b, v50
	v_mul_f32_e32 v230, 0xbfb8aa3b, v34
	v_exp_f32_e32 v229, v229
	v_exp_f32_e32 v230, v230
	v_add_f32_e32 v229, 1.0, v229
	v_add_f32_e32 v230, 1.0, v230
	v_rcp_f32_e32 v229, v229
	v_rcp_f32_e32 v230, v230
	v_mul_f32_e32 v229, v50, v229
	v_mul_f32_e32 v230, v34, v230
	v_cvt_pk_bf16_f32 v229, v229, v230
	ds_write_b16 v224, v229 offset:288
	ds_write_b16_d16_hi v224, v229 offset:352
	v_mul_f32_e32 v231, 0xbfb8aa3b, v51
	v_mul_f32_e32 v232, 0xbfb8aa3b, v35
	v_exp_f32_e32 v231, v231
	v_exp_f32_e32 v232, v232
	v_add_f32_e32 v231, 1.0, v231
	v_add_f32_e32 v232, 1.0, v232
	v_rcp_f32_e32 v231, v231
	v_rcp_f32_e32 v232, v232
	v_mul_f32_e32 v231, v51, v231
	v_mul_f32_e32 v232, v35, v232
	v_cvt_pk_bf16_f32 v231, v231, v232
	ds_write_b16 v224, v231 offset:432
	ds_write_b16_d16_hi v224, v231 offset:496
	v_mul_f32_e32 v229, 0xbfb8aa3b, v52
	v_mul_f32_e32 v230, 0xbfb8aa3b, v36
	v_exp_f32_e32 v229, v229
	v_exp_f32_e32 v230, v230
	v_add_f32_e32 v229, 1.0, v229
	v_add_f32_e32 v230, 1.0, v230
	v_rcp_f32_e32 v229, v229
	v_rcp_f32_e32 v230, v230
	v_mul_f32_e32 v229, v52, v229
	v_mul_f32_e32 v230, v36, v230
	v_cvt_pk_bf16_f32 v229, v229, v230
	ds_write_b16 v224, v229 offset:1152
	ds_write_b16_d16_hi v224, v229 offset:1216
	v_mul_f32_e32 v231, 0xbfb8aa3b, v53
	v_mul_f32_e32 v232, 0xbfb8aa3b, v37
	v_exp_f32_e32 v231, v231
	v_exp_f32_e32 v232, v232
	v_add_f32_e32 v231, 1.0, v231
	v_add_f32_e32 v232, 1.0, v232
	v_rcp_f32_e32 v231, v231
	v_rcp_f32_e32 v232, v232
	v_mul_f32_e32 v231, v53, v231
	v_mul_f32_e32 v232, v37, v232
	v_cvt_pk_bf16_f32 v231, v231, v232
	ds_write_b16 v224, v231 offset:1296
	ds_write_b16_d16_hi v224, v231 offset:1360
	v_mul_f32_e32 v229, 0xbfb8aa3b, v54
	v_mul_f32_e32 v230, 0xbfb8aa3b, v38
	v_exp_f32_e32 v229, v229
	v_exp_f32_e32 v230, v230
	v_add_f32_e32 v229, 1.0, v229
	v_add_f32_e32 v230, 1.0, v230
	v_rcp_f32_e32 v229, v229
	v_rcp_f32_e32 v230, v230
	v_mul_f32_e32 v229, v54, v229
	v_mul_f32_e32 v230, v38, v230
	v_cvt_pk_bf16_f32 v229, v229, v230
	ds_write_b16 v224, v229 offset:1440
	ds_write_b16_d16_hi v224, v229 offset:1504
	v_mul_f32_e32 v231, 0xbfb8aa3b, v55
	v_mul_f32_e32 v232, 0xbfb8aa3b, v39
	v_exp_f32_e32 v231, v231
	v_exp_f32_e32 v232, v232
	v_add_f32_e32 v231, 1.0, v231
	v_add_f32_e32 v232, 1.0, v232
	v_rcp_f32_e32 v231, v231
	v_rcp_f32_e32 v232, v232
	v_mul_f32_e32 v231, v55, v231
	v_mul_f32_e32 v232, v39, v232
	v_cvt_pk_bf16_f32 v231, v231, v232
	ds_write_b16 v224, v231 offset:1584
	ds_write_b16_d16_hi v224, v231 offset:1648
	v_mul_f32_e32 v229, 0xbfb8aa3b, v56
	v_mul_f32_e32 v230, 0xbfb8aa3b, v40
	v_exp_f32_e32 v229, v229
	v_exp_f32_e32 v230, v230
	v_add_f32_e32 v229, 1.0, v229
	v_add_f32_e32 v230, 1.0, v230
	v_rcp_f32_e32 v229, v229
	v_rcp_f32_e32 v230, v230
	v_mul_f32_e32 v229, v56, v229
	v_mul_f32_e32 v230, v40, v230
	v_cvt_pk_bf16_f32 v229, v229, v230
	ds_write_b16 v224, v229 offset:2304
	ds_write_b16_d16_hi v224, v229 offset:2368
	v_mul_f32_e32 v231, 0xbfb8aa3b, v57
	v_mul_f32_e32 v232, 0xbfb8aa3b, v41
	v_exp_f32_e32 v231, v231
	v_exp_f32_e32 v232, v232
	v_add_f32_e32 v231, 1.0, v231
	v_add_f32_e32 v232, 1.0, v232
	v_rcp_f32_e32 v231, v231
	v_rcp_f32_e32 v232, v232
	v_mul_f32_e32 v231, v57, v231
	v_mul_f32_e32 v232, v41, v232
	v_cvt_pk_bf16_f32 v231, v231, v232
	ds_write_b16 v224, v231 offset:2448
	ds_write_b16_d16_hi v224, v231 offset:2512
	v_mul_f32_e32 v229, 0xbfb8aa3b, v58
	v_mul_f32_e32 v230, 0xbfb8aa3b, v42
	v_exp_f32_e32 v229, v229
	v_exp_f32_e32 v230, v230
	v_add_f32_e32 v229, 1.0, v229
	v_add_f32_e32 v230, 1.0, v230
	v_rcp_f32_e32 v229, v229
	v_rcp_f32_e32 v230, v230
	v_mul_f32_e32 v229, v58, v229
	v_mul_f32_e32 v230, v42, v230
	v_cvt_pk_bf16_f32 v229, v229, v230
	ds_write_b16 v224, v229 offset:2592
	ds_write_b16_d16_hi v224, v229 offset:2656
	v_mul_f32_e32 v231, 0xbfb8aa3b, v59
	v_mul_f32_e32 v232, 0xbfb8aa3b, v43
	v_exp_f32_e32 v231, v231
	v_exp_f32_e32 v232, v232
	v_add_f32_e32 v231, 1.0, v231
	v_add_f32_e32 v232, 1.0, v232
	v_rcp_f32_e32 v231, v231
	v_rcp_f32_e32 v232, v232
	v_mul_f32_e32 v231, v59, v231
	v_mul_f32_e32 v232, v43, v232
	v_cvt_pk_bf16_f32 v231, v231, v232
	ds_write_b16 v224, v231 offset:2736
	ds_write_b16_d16_hi v224, v231 offset:2800
	v_mul_f32_e32 v229, 0xbfb8aa3b, v60
	v_mul_f32_e32 v230, 0xbfb8aa3b, v44
	v_exp_f32_e32 v229, v229
	v_exp_f32_e32 v230, v230
	v_add_f32_e32 v229, 1.0, v229
	v_add_f32_e32 v230, 1.0, v230
	v_rcp_f32_e32 v229, v229
	v_rcp_f32_e32 v230, v230
	v_mul_f32_e32 v229, v60, v229
	v_mul_f32_e32 v230, v44, v230
	v_cvt_pk_bf16_f32 v229, v229, v230
	ds_write_b16 v224, v229 offset:3456
	ds_write_b16_d16_hi v224, v229 offset:3520
	v_mul_f32_e32 v231, 0xbfb8aa3b, v61
	v_mul_f32_e32 v232, 0xbfb8aa3b, v45
	v_exp_f32_e32 v231, v231
	v_exp_f32_e32 v232, v232
	v_add_f32_e32 v231, 1.0, v231
	v_add_f32_e32 v232, 1.0, v232
	v_rcp_f32_e32 v231, v231
	v_rcp_f32_e32 v232, v232
	v_mul_f32_e32 v231, v61, v231
	v_mul_f32_e32 v232, v45, v232
	v_cvt_pk_bf16_f32 v231, v231, v232
	ds_write_b16 v224, v231 offset:3600
	ds_write_b16_d16_hi v224, v231 offset:3664
	v_mul_f32_e32 v229, 0xbfb8aa3b, v62
	v_mul_f32_e32 v230, 0xbfb8aa3b, v46
	v_exp_f32_e32 v229, v229
	v_exp_f32_e32 v230, v230
	v_add_f32_e32 v229, 1.0, v229
	v_add_f32_e32 v230, 1.0, v230
	v_rcp_f32_e32 v229, v229
	v_rcp_f32_e32 v230, v230
	v_mul_f32_e32 v229, v62, v229
	v_mul_f32_e32 v230, v46, v230
	v_cvt_pk_bf16_f32 v229, v229, v230
	ds_write_b16 v224, v229 offset:3744
	ds_write_b16_d16_hi v224, v229 offset:3808
	v_mul_f32_e32 v231, 0xbfb8aa3b, v63
	v_mul_f32_e32 v232, 0xbfb8aa3b, v47
	v_exp_f32_e32 v231, v231
	v_exp_f32_e32 v232, v232
	v_add_f32_e32 v231, 1.0, v231
	v_add_f32_e32 v232, 1.0, v232
	v_rcp_f32_e32 v231, v231
	v_rcp_f32_e32 v232, v232
	v_mul_f32_e32 v231, v63, v231
	v_mul_f32_e32 v232, v47, v232
	v_cvt_pk_bf16_f32 v231, v231, v232
	ds_write_b16 v224, v231 offset:3888
	ds_write_b16_d16_hi v224, v231 offset:3952
	s_branch .Lep0_10_st

.Lep0_11_mP:
	v_cvt_pk_bf16_f32 v229, v16, v0
	ds_write_b16 v224, v229
	ds_write_b16_d16_hi v224, v229 offset:64
	v_cvt_pk_bf16_f32 v230, v17, v1
	ds_write_b16 v224, v230 offset:144
	ds_write_b16_d16_hi v224, v230 offset:208
	v_cvt_pk_bf16_f32 v231, v18, v2
	ds_write_b16 v224, v231 offset:288
	ds_write_b16_d16_hi v224, v231 offset:352
	v_cvt_pk_bf16_f32 v232, v19, v3
	ds_write_b16 v224, v232 offset:432
	ds_write_b16_d16_hi v224, v232 offset:496
	v_cvt_pk_bf16_f32 v229, v20, v4
	ds_write_b16 v224, v229 offset:1152
	ds_write_b16_d16_hi v224, v229 offset:1216
	v_cvt_pk_bf16_f32 v230, v21, v5
	ds_write_b16 v224, v230 offset:1296
	ds_write_b16_d16_hi v224, v230 offset:1360
	v_cvt_pk_bf16_f32 v231, v22, v6
	ds_write_b16 v224, v231 offset:1440
	ds_write_b16_d16_hi v224, v231 offset:1504
	v_cvt_pk_bf16_f32 v232, v23, v7
	ds_write_b16 v224, v232 offset:1584
	ds_write_b16_d16_hi v224, v232 offset:1648
	v_cvt_pk_bf16_f32 v229, v24, v8
	ds_write_b16 v224, v229 offset:2304
	ds_write_b16_d16_hi v224, v229 offset:2368
	v_cvt_pk_bf16_f32 v230, v25, v9
	ds_write_b16 v224, v230 offset:2448
	ds_write_b16_d16_hi v224, v230 offset:2512
	v_cvt_pk_bf16_f32 v231, v26, v10
	ds_write_b16 v224, v231 offset:2592
	ds_write_b16_d16_hi v224, v231 offset:2656
	v_cvt_pk_bf16_f32 v232, v27, v11
	ds_write_b16 v224, v232 offset:2736
	ds_write_b16_d16_hi v224, v232 offset:2800
	v_cvt_pk_bf16_f32 v229, v28, v12
	ds_write_b16 v224, v229 offset:3456
	ds_write_b16_d16_hi v224, v229 offset:3520
	v_cvt_pk_bf16_f32 v230, v29, v13
	ds_write_b16 v224, v230 offset:3600
	ds_write_b16_d16_hi v224, v230 offset:3664
	v_cvt_pk_bf16_f32 v231, v30, v14
	ds_write_b16 v224, v231 offset:3744
	ds_write_b16_d16_hi v224, v231 offset:3808
	v_cvt_pk_bf16_f32 v232, v31, v15
	ds_write_b16 v224, v232 offset:3888
	ds_write_b16_d16_hi v224, v232 offset:3952
	s_branch .Lep0_11_stq
.Lep0_11_mR:
	s_load_dwordx2 s[98:99], s[0:1], 0x148
	v_add_u32_e32 v229, s94, v226
	v_lshlrev_b32_e32 v229, 8, v229
	v_add_u32_e32 v236, v229, v160
	v_mov_b32_e32 v237, 0
	s_waitcnt lgkmcnt(0)
	v_lshl_add_u64 v[236:237], s[98:99], 0, v[236:237]
	global_load_dwordx2 v[128:129], v[236:237], off
	global_load_dwordx2 v[130:131], v[236:237], off offset:256
	global_load_dwordx2 v[132:133], v[236:237], off offset:512
	global_load_dwordx2 v[134:135], v[236:237], off offset:768
	global_load_dwordx2 v[136:137], v[236:237], off offset:2048
	global_load_dwordx2 v[138:139], v[236:237], off offset:2304
	global_load_dwordx2 v[140:141], v[236:237], off offset:2560
	global_load_dwordx2 v[142:143], v[236:237], off offset:2816
	v_add_co_u32_e32 v238, vcc, 0x1000, v236
	s_nop 1
	v_addc_co_u32_e32 v239, vcc, 0, v237, vcc
	global_load_dwordx2 v[144:145], v[238:239], off
	global_load_dwordx2 v[146:147], v[238:239], off offset:256
	global_load_dwordx2 v[148:149], v[238:239], off offset:512
	global_load_dwordx2 v[150:151], v[238:239], off offset:768
	global_load_dwordx2 v[152:153], v[238:239], off offset:2048
	global_load_dwordx2 v[154:155], v[238:239], off offset:2304
	global_load_dwordx2 v[156:157], v[238:239], off offset:2560
	global_load_dwordx2 v[158:159], v[238:239], off offset:2816
	s_waitcnt vmcnt(15)
	v_mul_f32_e32 v229, v0, v129
	v_mul_f32_e32 v230, v16, v129
	v_fma_f32 v229, v16, v128, -v229
	v_fma_f32 v230, v0, v128, v230
	v_mul_f32_e32 v229, s88, v229
	v_mul_f32_e32 v230, s88, v230
	v_cvt_pk_bf16_f32 v229, v229, v230
	ds_write_b16 v224, v229
	ds_write_b16_d16_hi v224, v229 offset:64
	s_waitcnt vmcnt(14)
	v_mul_f32_e32 v229, v1, v131
	v_mul_f32_e32 v230, v17, v131
	v_fma_f32 v229, v17, v130, -v229
	v_fma_f32 v230, v1, v130, v230
	v_mul_f32_e32 v229, s88, v229
	v_mul_f32_e32 v230, s88, v230
	v_cvt_pk_bf16_f32 v229, v229, v230
	ds_write_b16 v224, v229 offset:144
	ds_write_b16_d16_hi v224, v229 offset:208
	s_waitcnt vmcnt(13)
	v_mul_f32_e32 v229, v2, v133
	v_mul_f32_e32 v230, v18, v133
	v_fma_f32 v229, v18, v132, -v229
	v_fma_f32 v230, v2, v132, v230
	v_mul_f32_e32 v229, s88, v229
	v_mul_f32_e32 v230, s88, v230
	v_cvt_pk_bf16_f32 v229, v229, v230
	ds_write_b16 v224, v229 offset:288
	ds_write_b16_d16_hi v224, v229 offset:352
	s_waitcnt vmcnt(12)
	v_mul_f32_e32 v229, v3, v135
	v_mul_f32_e32 v230, v19, v135
	v_fma_f32 v229, v19, v134, -v229
	v_fma_f32 v230, v3, v134, v230
	v_mul_f32_e32 v229, s88, v229
	v_mul_f32_e32 v230, s88, v230
	v_cvt_pk_bf16_f32 v229, v229, v230
	ds_write_b16 v224, v229 offset:432
	ds_write_b16_d16_hi v224, v229 offset:496
	s_waitcnt vmcnt(11)
	v_mul_f32_e32 v229, v4, v137
	v_mul_f32_e32 v230, v20, v137
	v_fma_f32 v229, v20, v136, -v229
	v_fma_f32 v230, v4, v136, v230
	v_mul_f32_e32 v229, s88, v229
	v_mul_f32_e32 v230, s88, v230
	v_cvt_pk_bf16_f32 v229, v229, v230
	ds_write_b16 v224, v229 offset:1152
	ds_write_b16_d16_hi v224, v229 offset:1216
	s_waitcnt vmcnt(10)
	v_mul_f32_e32 v229, v5, v139
	v_mul_f32_e32 v230, v21, v139
	v_fma_f32 v229, v21, v138, -v229
	v_fma_f32 v230, v5, v138, v230
	v_mul_f32_e32 v229, s88, v229
	v_mul_f32_e32 v230, s88, v230
	v_cvt_pk_bf16_f32 v229, v229, v230
	ds_write_b16 v224, v229 offset:1296
	ds_write_b16_d16_hi v224, v229 offset:1360
	s_waitcnt vmcnt(9)
	v_mul_f32_e32 v229, v6, v141
	v_mul_f32_e32 v230, v22, v141
	v_fma_f32 v229, v22, v140, -v229
	v_fma_f32 v230, v6, v140, v230
	v_mul_f32_e32 v229, s88, v229
	v_mul_f32_e32 v230, s88, v230
	v_cvt_pk_bf16_f32 v229, v229, v230
	ds_write_b16 v224, v229 offset:1440
	ds_write_b16_d16_hi v224, v229 offset:1504
	s_waitcnt vmcnt(8)
	v_mul_f32_e32 v229, v7, v143
	v_mul_f32_e32 v230, v23, v143
	v_fma_f32 v229, v23, v142, -v229
	v_fma_f32 v230, v7, v142, v230
	v_mul_f32_e32 v229, s88, v229
	v_mul_f32_e32 v230, s88, v230
	v_cvt_pk_bf16_f32 v229, v229, v230
	ds_write_b16 v224, v229 offset:1584
	ds_write_b16_d16_hi v224, v229 offset:1648
	s_waitcnt vmcnt(7)
	v_mul_f32_e32 v229, v8, v145
	v_mul_f32_e32 v230, v24, v145
	v_fma_f32 v229, v24, v144, -v229
	v_fma_f32 v230, v8, v144, v230
	v_mul_f32_e32 v229, s88, v229
	v_mul_f32_e32 v230, s88, v230
	v_cvt_pk_bf16_f32 v229, v229, v230
	ds_write_b16 v224, v229 offset:2304
	ds_write_b16_d16_hi v224, v229 offset:2368
	s_waitcnt vmcnt(6)
	v_mul_f32_e32 v229, v9, v147
	v_mul_f32_e32 v230, v25, v147
	v_fma_f32 v229, v25, v146, -v229
	v_fma_f32 v230, v9, v146, v230
	v_mul_f32_e32 v229, s88, v229
	v_mul_f32_e32 v230, s88, v230
	v_cvt_pk_bf16_f32 v229, v229, v230
	ds_write_b16 v224, v229 offset:2448
	ds_write_b16_d16_hi v224, v229 offset:2512
	s_waitcnt vmcnt(5)
	v_mul_f32_e32 v229, v10, v149
	v_mul_f32_e32 v230, v26, v149
	v_fma_f32 v229, v26, v148, -v229
	v_fma_f32 v230, v10, v148, v230
	v_mul_f32_e32 v229, s88, v229
	v_mul_f32_e32 v230, s88, v230
	v_cvt_pk_bf16_f32 v229, v229, v230
	ds_write_b16 v224, v229 offset:2592
	ds_write_b16_d16_hi v224, v229 offset:2656
	s_waitcnt vmcnt(4)
	v_mul_f32_e32 v229, v11, v151
	v_mul_f32_e32 v230, v27, v151
	v_fma_f32 v229, v27, v150, -v229
	v_fma_f32 v230, v11, v150, v230
	v_mul_f32_e32 v229, s88, v229
	v_mul_f32_e32 v230, s88, v230
	v_cvt_pk_bf16_f32 v229, v229, v230
	ds_write_b16 v224, v229 offset:2736
	ds_write_b16_d16_hi v224, v229 offset:2800
	s_waitcnt vmcnt(3)
	v_mul_f32_e32 v229, v12, v153
	v_mul_f32_e32 v230, v28, v153
	v_fma_f32 v229, v28, v152, -v229
	v_fma_f32 v230, v12, v152, v230
	v_mul_f32_e32 v229, s88, v229
	v_mul_f32_e32 v230, s88, v230
	v_cvt_pk_bf16_f32 v229, v229, v230
	ds_write_b16 v224, v229 offset:3456
	ds_write_b16_d16_hi v224, v229 offset:3520
	s_waitcnt vmcnt(2)
	v_mul_f32_e32 v229, v13, v155
	v_mul_f32_e32 v230, v29, v155
	v_fma_f32 v229, v29, v154, -v229
	v_fma_f32 v230, v13, v154, v230
	v_mul_f32_e32 v229, s88, v229
	v_mul_f32_e32 v230, s88, v230
	v_cvt_pk_bf16_f32 v229, v229, v230
	ds_write_b16 v224, v229 offset:3600
	ds_write_b16_d16_hi v224, v229 offset:3664
	s_waitcnt vmcnt(1)
	v_mul_f32_e32 v229, v14, v157
	v_mul_f32_e32 v230, v30, v157
	v_fma_f32 v229, v30, v156, -v229
	v_fma_f32 v230, v14, v156, v230
	v_mul_f32_e32 v229, s88, v229
	v_mul_f32_e32 v230, s88, v230
	v_cvt_pk_bf16_f32 v229, v229, v230
	ds_write_b16 v224, v229 offset:3744
	ds_write_b16_d16_hi v224, v229 offset:3808
	s_waitcnt vmcnt(0)
	v_mul_f32_e32 v229, v15, v159
	v_mul_f32_e32 v230, v31, v159
	v_fma_f32 v229, v31, v158, -v229
	v_fma_f32 v230, v15, v158, v230
	v_mul_f32_e32 v229, s88, v229
	v_mul_f32_e32 v230, s88, v230
	v_cvt_pk_bf16_f32 v229, v229, v230
	ds_write_b16 v224, v229 offset:3888
	ds_write_b16_d16_hi v224, v229 offset:3952
	s_branch .Lep0_11_stb
.Lep0_11_mS:
	v_mul_f32_e32 v229, 0xbfb8aa3b, v16
	v_mul_f32_e32 v230, 0xbfb8aa3b, v0
	v_exp_f32_e32 v229, v229
	v_exp_f32_e32 v230, v230
	v_add_f32_e32 v229, 1.0, v229
	v_add_f32_e32 v230, 1.0, v230
	v_rcp_f32_e32 v229, v229
	v_rcp_f32_e32 v230, v230
	v_mul_f32_e32 v229, v16, v229
	v_mul_f32_e32 v230, v0, v230
	v_cvt_pk_bf16_f32 v229, v229, v230
	ds_write_b16 v224, v229
	ds_write_b16_d16_hi v224, v229 offset:64
	v_mul_f32_e32 v231, 0xbfb8aa3b, v17
	v_mul_f32_e32 v232, 0xbfb8aa3b, v1
	v_exp_f32_e32 v231, v231
	v_exp_f32_e32 v232, v232
	v_add_f32_e32 v231, 1.0, v231
	v_add_f32_e32 v232, 1.0, v232
	v_rcp_f32_e32 v231, v231
	v_rcp_f32_e32 v232, v232
	v_mul_f32_e32 v231, v17, v231
	v_mul_f32_e32 v232, v1, v232
	v_cvt_pk_bf16_f32 v231, v231, v232
	ds_write_b16 v224, v231 offset:144
	ds_write_b16_d16_hi v224, v231 offset:208
	v_mul_f32_e32 v229, 0xbfb8aa3b, v18
	v_mul_f32_e32 v230, 0xbfb8aa3b, v2
	v_exp_f32_e32 v229, v229
	v_exp_f32_e32 v230, v230
	v_add_f32_e32 v229, 1.0, v229
	v_add_f32_e32 v230, 1.0, v230
	v_rcp_f32_e32 v229, v229
	v_rcp_f32_e32 v230, v230
	v_mul_f32_e32 v229, v18, v229
	v_mul_f32_e32 v230, v2, v230
	v_cvt_pk_bf16_f32 v229, v229, v230
	ds_write_b16 v224, v229 offset:288
	ds_write_b16_d16_hi v224, v229 offset:352
	v_mul_f32_e32 v231, 0xbfb8aa3b, v19
	v_mul_f32_e32 v232, 0xbfb8aa3b, v3
	v_exp_f32_e32 v231, v231
	v_exp_f32_e32 v232, v232
	v_add_f32_e32 v231, 1.0, v231
	v_add_f32_e32 v232, 1.0, v232
	v_rcp_f32_e32 v231, v231
	v_rcp_f32_e32 v232, v232
	v_mul_f32_e32 v231, v19, v231
	v_mul_f32_e32 v232, v3, v232
	v_cvt_pk_bf16_f32 v231, v231, v232
	ds_write_b16 v224, v231 offset:432
	ds_write_b16_d16_hi v224, v231 offset:496
	v_mul_f32_e32 v229, 0xbfb8aa3b, v20
	v_mul_f32_e32 v230, 0xbfb8aa3b, v4
	v_exp_f32_e32 v229, v229
	v_exp_f32_e32 v230, v230
	v_add_f32_e32 v229, 1.0, v229
	v_add_f32_e32 v230, 1.0, v230
	v_rcp_f32_e32 v229, v229
	v_rcp_f32_e32 v230, v230
	v_mul_f32_e32 v229, v20, v229
	v_mul_f32_e32 v230, v4, v230
	v_cvt_pk_bf16_f32 v229, v229, v230
	ds_write_b16 v224, v229 offset:1152
	ds_write_b16_d16_hi v224, v229 offset:1216
	v_mul_f32_e32 v231, 0xbfb8aa3b, v21
	v_mul_f32_e32 v232, 0xbfb8aa3b, v5
	v_exp_f32_e32 v231, v231
	v_exp_f32_e32 v232, v232
	v_add_f32_e32 v231, 1.0, v231
	v_add_f32_e32 v232, 1.0, v232
	v_rcp_f32_e32 v231, v231
	v_rcp_f32_e32 v232, v232
	v_mul_f32_e32 v231, v21, v231
	v_mul_f32_e32 v232, v5, v232
	v_cvt_pk_bf16_f32 v231, v231, v232
	ds_write_b16 v224, v231 offset:1296
	ds_write_b16_d16_hi v224, v231 offset:1360
	v_mul_f32_e32 v229, 0xbfb8aa3b, v22
	v_mul_f32_e32 v230, 0xbfb8aa3b, v6
	v_exp_f32_e32 v229, v229
	v_exp_f32_e32 v230, v230
	v_add_f32_e32 v229, 1.0, v229
	v_add_f32_e32 v230, 1.0, v230
	v_rcp_f32_e32 v229, v229
	v_rcp_f32_e32 v230, v230
	v_mul_f32_e32 v229, v22, v229
	v_mul_f32_e32 v230, v6, v230
	v_cvt_pk_bf16_f32 v229, v229, v230
	ds_write_b16 v224, v229 offset:1440
	ds_write_b16_d16_hi v224, v229 offset:1504
	v_mul_f32_e32 v231, 0xbfb8aa3b, v23
	v_mul_f32_e32 v232, 0xbfb8aa3b, v7
	v_exp_f32_e32 v231, v231
	v_exp_f32_e32 v232, v232
	v_add_f32_e32 v231, 1.0, v231
	v_add_f32_e32 v232, 1.0, v232
	v_rcp_f32_e32 v231, v231
	v_rcp_f32_e32 v232, v232
	v_mul_f32_e32 v231, v23, v231
	v_mul_f32_e32 v232, v7, v232
	v_cvt_pk_bf16_f32 v231, v231, v232
	ds_write_b16 v224, v231 offset:1584
	ds_write_b16_d16_hi v224, v231 offset:1648
	v_mul_f32_e32 v229, 0xbfb8aa3b, v24
	v_mul_f32_e32 v230, 0xbfb8aa3b, v8
	v_exp_f32_e32 v229, v229
	v_exp_f32_e32 v230, v230
	v_add_f32_e32 v229, 1.0, v229
	v_add_f32_e32 v230, 1.0, v230
	v_rcp_f32_e32 v229, v229
	v_rcp_f32_e32 v230, v230
	v_mul_f32_e32 v229, v24, v229
	v_mul_f32_e32 v230, v8, v230
	v_cvt_pk_bf16_f32 v229, v229, v230
	ds_write_b16 v224, v229 offset:2304
	ds_write_b16_d16_hi v224, v229 offset:2368
	v_mul_f32_e32 v231, 0xbfb8aa3b, v25
	v_mul_f32_e32 v232, 0xbfb8aa3b, v9
	v_exp_f32_e32 v231, v231
	v_exp_f32_e32 v232, v232
	v_add_f32_e32 v231, 1.0, v231
	v_add_f32_e32 v232, 1.0, v232
	v_rcp_f32_e32 v231, v231
	v_rcp_f32_e32 v232, v232
	v_mul_f32_e32 v231, v25, v231
	v_mul_f32_e32 v232, v9, v232
	v_cvt_pk_bf16_f32 v231, v231, v232
	ds_write_b16 v224, v231 offset:2448
	ds_write_b16_d16_hi v224, v231 offset:2512
	v_mul_f32_e32 v229, 0xbfb8aa3b, v26
	v_mul_f32_e32 v230, 0xbfb8aa3b, v10
	v_exp_f32_e32 v229, v229
	v_exp_f32_e32 v230, v230
	v_add_f32_e32 v229, 1.0, v229
	v_add_f32_e32 v230, 1.0, v230
	v_rcp_f32_e32 v229, v229
	v_rcp_f32_e32 v230, v230
	v_mul_f32_e32 v229, v26, v229
	v_mul_f32_e32 v230, v10, v230
	v_cvt_pk_bf16_f32 v229, v229, v230
	ds_write_b16 v224, v229 offset:2592
	ds_write_b16_d16_hi v224, v229 offset:2656
	v_mul_f32_e32 v231, 0xbfb8aa3b, v27
	v_mul_f32_e32 v232, 0xbfb8aa3b, v11
	v_exp_f32_e32 v231, v231
	v_exp_f32_e32 v232, v232
	v_add_f32_e32 v231, 1.0, v231
	v_add_f32_e32 v232, 1.0, v232
	v_rcp_f32_e32 v231, v231
	v_rcp_f32_e32 v232, v232
	v_mul_f32_e32 v231, v27, v231
	v_mul_f32_e32 v232, v11, v232
	v_cvt_pk_bf16_f32 v231, v231, v232
	ds_write_b16 v224, v231 offset:2736
	ds_write_b16_d16_hi v224, v231 offset:2800
	v_mul_f32_e32 v229, 0xbfb8aa3b, v28
	v_mul_f32_e32 v230, 0xbfb8aa3b, v12
	v_exp_f32_e32 v229, v229
	v_exp_f32_e32 v230, v230
	v_add_f32_e32 v229, 1.0, v229
	v_add_f32_e32 v230, 1.0, v230
	v_rcp_f32_e32 v229, v229
	v_rcp_f32_e32 v230, v230
	v_mul_f32_e32 v229, v28, v229
	v_mul_f32_e32 v230, v12, v230
	v_cvt_pk_bf16_f32 v229, v229, v230
	ds_write_b16 v224, v229 offset:3456
	ds_write_b16_d16_hi v224, v229 offset:3520
	v_mul_f32_e32 v231, 0xbfb8aa3b, v29
	v_mul_f32_e32 v232, 0xbfb8aa3b, v13
	v_exp_f32_e32 v231, v231
	v_exp_f32_e32 v232, v232
	v_add_f32_e32 v231, 1.0, v231
	v_add_f32_e32 v232, 1.0, v232
	v_rcp_f32_e32 v231, v231
	v_rcp_f32_e32 v232, v232
	v_mul_f32_e32 v231, v29, v231
	v_mul_f32_e32 v232, v13, v232
	v_cvt_pk_bf16_f32 v231, v231, v232
	ds_write_b16 v224, v231 offset:3600
	ds_write_b16_d16_hi v224, v231 offset:3664
	v_mul_f32_e32 v229, 0xbfb8aa3b, v30
	v_mul_f32_e32 v230, 0xbfb8aa3b, v14
	v_exp_f32_e32 v229, v229
	v_exp_f32_e32 v230, v230
	v_add_f32_e32 v229, 1.0, v229
	v_add_f32_e32 v230, 1.0, v230
	v_rcp_f32_e32 v229, v229
	v_rcp_f32_e32 v230, v230
	v_mul_f32_e32 v229, v30, v229
	v_mul_f32_e32 v230, v14, v230
	v_cvt_pk_bf16_f32 v229, v229, v230
	ds_write_b16 v224, v229 offset:3744
	ds_write_b16_d16_hi v224, v229 offset:3808
	v_mul_f32_e32 v231, 0xbfb8aa3b, v31
	v_mul_f32_e32 v232, 0xbfb8aa3b, v15
	v_exp_f32_e32 v231, v231
	v_exp_f32_e32 v232, v232
	v_add_f32_e32 v231, 1.0, v231
	v_add_f32_e32 v232, 1.0, v232
	v_rcp_f32_e32 v231, v231
	v_rcp_f32_e32 v232, v232
	v_mul_f32_e32 v231, v31, v231
	v_mul_f32_e32 v232, v15, v232
	v_cvt_pk_bf16_f32 v231, v231, v232
	ds_write_b16 v224, v231 offset:3888
	ds_write_b16_d16_hi v224, v231 offset:3952
	s_branch .Lep0_11_st

.LBB0_1275:
	s_ashr_i32 s2, s54, 31
	s_lshr_b32 s2, s2, 30
	s_add_i32 s2, s54, s2
	s_ashr_i32 s2, s2, 2
	s_lshl_b32 s4, s2, 8
	v_add_u32_e32 v0, s4, v212
	v_min_i32_e32 v0, 0x7fff, v0
	v_ashrrev_i32_e32 v1, 31, v0
	s_lshl_b32 s6, s2, 10
	v_lshlrev_b64 v[0:1], 11, v[0:1]
	v_lshl_add_u64 v[160:161], v[176:177], 0, v[0:1]
	v_subrev_u32_e32 v0, s6, v220
	v_ashrrev_i32_e32 v1, 31, v0
	v_lshlrev_b64 v[0:1], 11, v[0:1]
	v_lshl_add_u64 v[180:181], v[178:179], 0, v[0:1]
	v_subrev_u32_e32 v0, s6, v221
	v_ashrrev_i32_e32 v1, 31, v0
	v_lshlrev_b64 v[0:1], 11, v[0:1]
	v_lshl_add_u64 v[182:183], v[178:179], 0, v[0:1]
	v_subrev_u32_e32 v0, s6, v222
	v_ashrrev_i32_e32 v1, 31, v0
	v_add_u32_e32 v2, s4, v213
	v_add_u32_e32 v4, s4, v171
	v_add_u32_e32 v6, s4, v215
	v_lshlrev_b64 v[0:1], 11, v[0:1]
	v_min_i32_e32 v2, 0x7fff, v2
	v_min_i32_e32 v4, 0x7fff, v4
	v_min_i32_e32 v6, 0x7fff, v6
	v_lshl_add_u64 v[184:185], v[178:179], 0, v[0:1]
	v_subrev_u32_e32 v0, s6, v223
	v_ashrrev_i32_e32 v3, 31, v2
	v_ashrrev_i32_e32 v5, 31, v4
	v_ashrrev_i32_e32 v7, 31, v6
	v_ashrrev_i32_e32 v1, 31, v0
	v_lshlrev_b64 v[2:3], 11, v[2:3]
	v_lshlrev_b64 v[4:5], 11, v[4:5]
	v_lshlrev_b64 v[6:7], 11, v[6:7]
	v_lshlrev_b64 v[0:1], 11, v[0:1]
	s_mov_b32 s5, s54
	v_lshl_add_u64 v[162:163], v[176:177], 0, v[2:3]
	v_lshl_add_u64 v[164:165], v[176:177], 0, v[4:5]
	v_lshl_add_u64 v[166:167], v[176:177], 0, v[6:7]
	v_lshl_add_u64 v[186:187], v[178:179], 0, v[0:1]
	s_mov_b64 s[2:3], 0
	s_mov_b32 s7, 0
	v_mov_b32_e32 v0, 0
	v_mov_b32_e32 v1, v169
	v_mov_b32_e32 v2, v169
	v_mov_b32_e32 v3, v169
	v_mov_b32_e32 v4, v169
	v_mov_b32_e32 v5, v169
	v_mov_b32_e32 v6, v169
	v_mov_b32_e32 v7, v169
	v_mov_b32_e32 v8, v169
	v_mov_b32_e32 v9, v169
	v_mov_b32_e32 v10, v169
	v_mov_b32_e32 v11, v169
	v_mov_b32_e32 v12, v169
	v_mov_b32_e32 v13, v169
	v_mov_b32_e32 v14, v169
	v_mov_b32_e32 v15, v169
	v_mov_b32_e32 v16, 0
	v_mov_b32_e32 v17, v169
	v_mov_b32_e32 v18, v169
	v_mov_b32_e32 v19, v169
	v_mov_b32_e32 v20, v169
	v_mov_b32_e32 v21, v169
	v_mov_b32_e32 v22, v169
	v_mov_b32_e32 v23, v169
	v_mov_b32_e32 v24, v169
	v_mov_b32_e32 v25, v169
	v_mov_b32_e32 v26, v169
	v_mov_b32_e32 v27, v169
	v_mov_b32_e32 v28, v169
	v_mov_b32_e32 v29, v169
	v_mov_b32_e32 v30, v169
	v_mov_b32_e32 v31, v169
	v_mov_b32_e32 v32, 0
	v_mov_b32_e32 v33, v169
	v_mov_b32_e32 v34, v169
	v_mov_b32_e32 v35, v169
	v_mov_b32_e32 v36, v169
	v_mov_b32_e32 v37, v169
	v_mov_b32_e32 v38, v169
	v_mov_b32_e32 v39, v169
	v_mov_b32_e32 v40, v169
	v_mov_b32_e32 v41, v169
	v_mov_b32_e32 v42, v169
	v_mov_b32_e32 v43, v169
	v_mov_b32_e32 v44, v169
	v_mov_b32_e32 v45, v169
	v_mov_b32_e32 v46, v169
	v_mov_b32_e32 v47, v169
	v_mov_b32_e32 v48, 0
	v_mov_b32_e32 v49, v169
	v_mov_b32_e32 v50, v169
	v_mov_b32_e32 v51, v169
	v_mov_b32_e32 v52, v169
	v_mov_b32_e32 v53, v169
	v_mov_b32_e32 v54, v169
	v_mov_b32_e32 v55, v169
	v_mov_b32_e32 v56, v169
	v_mov_b32_e32 v57, v169
	v_mov_b32_e32 v58, v169
	v_mov_b32_e32 v59, v169
	v_mov_b32_e32 v60, v169
	v_mov_b32_e32 v61, v169
	v_mov_b32_e32 v62, v169
	v_mov_b32_e32 v63, v169
	v_mov_b32_e32 v64, 0
	v_mov_b32_e32 v65, v169
	v_mov_b32_e32 v66, v169
	v_mov_b32_e32 v67, v169
	v_mov_b32_e32 v68, v169
	v_mov_b32_e32 v69, v169
	v_mov_b32_e32 v70, v169
	v_mov_b32_e32 v71, v169
	v_mov_b32_e32 v72, v169
	v_mov_b32_e32 v73, v169
	v_mov_b32_e32 v74, v169
	v_mov_b32_e32 v75, v169
	v_mov_b32_e32 v76, v169
	v_mov_b32_e32 v77, v169
	v_mov_b32_e32 v78, v169
	v_mov_b32_e32 v79, v169
	v_mov_b32_e32 v80, 0
	v_mov_b32_e32 v81, v169
	v_mov_b32_e32 v82, v169
	v_mov_b32_e32 v83, v169
	v_mov_b32_e32 v84, v169
	v_mov_b32_e32 v85, v169
	v_mov_b32_e32 v86, v169
	v_mov_b32_e32 v87, v169
	v_mov_b32_e32 v88, v169
	v_mov_b32_e32 v89, v169
	v_mov_b32_e32 v90, v169
	v_mov_b32_e32 v91, v169
	v_mov_b32_e32 v92, v169
	v_mov_b32_e32 v93, v169
	v_mov_b32_e32 v94, v169
	v_mov_b32_e32 v95, v169
	v_mov_b32_e32 v96, 0
	v_mov_b32_e32 v97, v169
	v_mov_b32_e32 v98, v169
	v_mov_b32_e32 v99, v169
	v_mov_b32_e32 v100, v169
	v_mov_b32_e32 v101, v169
	v_mov_b32_e32 v102, v169
	v_mov_b32_e32 v103, v169
	v_mov_b32_e32 v104, v169
	v_mov_b32_e32 v105, v169
	v_mov_b32_e32 v106, v169
	v_mov_b32_e32 v107, v169
	v_mov_b32_e32 v108, v169
	v_mov_b32_e32 v109, v169
	v_mov_b32_e32 v110, v169
	v_mov_b32_e32 v111, v169
	v_mov_b32_e32 v112, 0
	v_mov_b32_e32 v113, v169
	v_mov_b32_e32 v114, v169
	v_mov_b32_e32 v115, v169
	v_mov_b32_e32 v116, v169
	v_mov_b32_e32 v117, v169
	v_mov_b32_e32 v118, v169
	v_mov_b32_e32 v119, v169
	v_mov_b32_e32 v120, v169
	v_mov_b32_e32 v121, v169
	v_mov_b32_e32 v122, v169
	v_mov_b32_e32 v123, v169
	v_mov_b32_e32 v124, v169
	v_mov_b32_e32 v125, v169
	v_mov_b32_e32 v126, v169
	v_mov_b32_e32 v127, v169
	v_mbcnt_hi_u32_b32 v128, -1, v210
	s_and_b32 s90, s70, 0x40
	v_and_b32_e32 v159, 48, v128
	v_or_b32_e32 v159, s90, v159
	v_and_b32_e32 v129, 31, v128
	v_lshrrev_b32_e32 v130, 5, v128
	v_bfe_u32 v131, v128, 1, 3
	v_lshlrev_b32_e32 v132, 7, v129
	s_lshr_b32 s91, s70, 7
	s_lshl_b32 s91, s91, 13
	s_lshl_b32 s90, s90, 8
	s_add_u32 s90, s90, 0x8000
	s_lshl_b32 s88, s70, 4
	s_mov_b32 s89, 0x10000
	s_lshl_b32 s92, s22, 4
	s_and_b32 s92, s92, 0x780
	s_mov_b32 s93, 0
	s_load_dwordx2 s[96:97], s[0:1], 0x158
	s_load_dwordx2 s[98:99], s[0:1], 0xf0
	s_waitcnt lgkmcnt(0)
	v_subrev_u32_e32 v152, s96, v160
	v_xor_b32_e32 v152, v159, v152
	v_subrev_u32_e32 v153, s98, v180
	v_xor_b32_e32 v153, v159, v153
	v_subrev_u32_e32 v154, s96, v162
	v_xor_b32_e32 v154, v159, v154
	v_subrev_u32_e32 v155, s98, v182
	v_xor_b32_e32 v155, v159, v155
	v_subrev_u32_e32 v156, s96, v164
	v_xor_b32_e32 v156, v159, v156
	v_subrev_u32_e32 v157, s98, v184
	v_xor_b32_e32 v157, v159, v157
	v_subrev_u32_e32 v158, s96, v166
	v_xor_b32_e32 v158, v159, v158
	v_subrev_u32_e32 v168, s98, v186
	v_xor_b32_e32 v168, v159, v168
	v_xor_b32_e32 v133, v130, v131
	v_lshl_add_u32 v133, v133, 4, v132
	v_add_u32_e32 v230, s91, v133
	v_add_u32_e32 v234, s90, v133
	v_or_b32_e32 v133, 2, v130
	v_xor_b32_e32 v133, v133, v131
	v_lshl_add_u32 v133, v133, 4, v132
	v_add_u32_e32 v231, s91, v133
	v_add_u32_e32 v235, s90, v133
	v_or_b32_e32 v133, 4, v130
	v_xor_b32_e32 v133, v133, v131
	v_lshl_add_u32 v133, v133, 4, v132
	v_add_u32_e32 v232, s91, v133
	v_add_u32_e32 v236, s90, v133
	v_or_b32_e32 v133, 6, v130
	v_xor_b32_e32 v133, v133, v131
	v_lshl_add_u32 v133, v133, 4, v132
	v_add_u32_e32 v233, s91, v133
	v_add_u32_e32 v237, s90, v133
	s_barrier
	ds_read_b128 v[188:191], v230
	ds_read_b128 v[196:199], v234
	ds_read_b128 v[192:195], v230 offset:4096
	ds_read_b128 v[200:203], v234 offset:4096
	ds_read_b128 v[204:207], v234 offset:8192
	ds_read_b128 v[226:229], v234 offset:12288
	s_add_u32 s94, s2, s92
	s_add_u32 s94, s94, 0x80
	s_and_b32 s94, s94, 0x780
	s_sub_u32 s94, s94, 0x80
	s_subb_u32 s95, 0, 0
	s_add_u32 s100, s96, s94
	s_addc_u32 s101, s97, s95
	s_add_u32 s94, s98, s94
	s_addc_u32 s95, s99, s95
	s_add_u32 s90, s88, s89
	s_add_u32 m0, s90, 0
	s_nop 0
	global_load_lds_dwordx4 v152, s[100:101]
	s_add_u32 m0, s90, 32768
	s_nop 0
	global_load_lds_dwordx4 v153, s[94:95]
	s_add_u32 m0, s90, 8192
	s_nop 0
	global_load_lds_dwordx4 v154, s[100:101]
	s_add_u32 m0, s90, 40960
	s_nop 0
	global_load_lds_dwordx4 v155, s[94:95]
	s_add_u32 m0, s90, 16384
	s_nop 0
	global_load_lds_dwordx4 v156, s[100:101]
	s_add_u32 m0, s90, 49152
	s_nop 0
	global_load_lds_dwordx4 v157, s[94:95]
	s_add_u32 m0, s90, 24576
	s_nop 0
	global_load_lds_dwordx4 v158, s[100:101]
	s_add_u32 m0, s90, 57344
	s_nop 0
	global_load_lds_dwordx4 v168, s[94:95]
	s_xor_b32 s89, s89, 0x10000
.Lgk1_loop:
	ds_read_b128 v[128:131], v231
	ds_read_b128 v[136:139], v235
	ds_read_b128 v[132:135], v231 offset:4096
	ds_read_b128 v[140:143], v235 offset:4096
	ds_read_b128 v[144:147], v235 offset:8192
	ds_read_b128 v[148:151], v235 offset:12288
	s_waitcnt lgkmcnt(6)
	v_mfma_f32_32x32x16_bf16 v[112:127], v[188:191], v[196:199], v[112:127]
	v_mfma_f32_32x32x16_bf16 v[48:63], v[192:195], v[196:199], v[48:63]
	v_mfma_f32_32x32x16_bf16 v[96:111], v[188:191], v[200:203], v[96:111]
	v_mfma_f32_32x32x16_bf16 v[32:47], v[192:195], v[200:203], v[32:47]
	v_mfma_f32_32x32x16_bf16 v[80:95], v[188:191], v[204:207], v[80:95]
	v_mfma_f32_32x32x16_bf16 v[16:31], v[192:195], v[204:207], v[16:31]
	v_mfma_f32_32x32x16_bf16 v[64:79], v[188:191], v[226:229], v[64:79]
	v_mfma_f32_32x32x16_bf16 v[0:15], v[192:195], v[226:229], v[0:15]
	ds_read_b128 v[188:191], v232
	ds_read_b128 v[196:199], v236
	ds_read_b128 v[192:195], v232 offset:4096
	ds_read_b128 v[200:203], v236 offset:4096
	ds_read_b128 v[204:207], v236 offset:8192
	ds_read_b128 v[226:229], v236 offset:12288
	s_waitcnt lgkmcnt(6)
	v_mfma_f32_32x32x16_bf16 v[112:127], v[128:131], v[136:139], v[112:127]
	v_mfma_f32_32x32x16_bf16 v[48:63], v[132:135], v[136:139], v[48:63]
	v_mfma_f32_32x32x16_bf16 v[96:111], v[128:131], v[140:143], v[96:111]
	v_mfma_f32_32x32x16_bf16 v[32:47], v[132:135], v[140:143], v[32:47]
	v_mfma_f32_32x32x16_bf16 v[80:95], v[128:131], v[144:147], v[80:95]
	v_mfma_f32_32x32x16_bf16 v[16:31], v[132:135], v[144:147], v[16:31]
	v_mfma_f32_32x32x16_bf16 v[64:79], v[128:131], v[148:151], v[64:79]
	v_mfma_f32_32x32x16_bf16 v[0:15], v[132:135], v[148:151], v[0:15]
	ds_read_b128 v[128:131], v233
	ds_read_b128 v[136:139], v237
	ds_read_b128 v[132:135], v233 offset:4096
	ds_read_b128 v[140:143], v237 offset:4096
	ds_read_b128 v[144:147], v237 offset:8192
	ds_read_b128 v[148:151], v237 offset:12288
	s_waitcnt lgkmcnt(6)
	v_mfma_f32_32x32x16_bf16 v[112:127], v[188:191], v[196:199], v[112:127]
	v_mfma_f32_32x32x16_bf16 v[48:63], v[192:195], v[196:199], v[48:63]
	v_mfma_f32_32x32x16_bf16 v[96:111], v[188:191], v[200:203], v[96:111]
	v_mfma_f32_32x32x16_bf16 v[32:47], v[192:195], v[200:203], v[32:47]
	v_mfma_f32_32x32x16_bf16 v[80:95], v[188:191], v[204:207], v[80:95]
	v_mfma_f32_32x32x16_bf16 v[16:31], v[192:195], v[204:207], v[16:31]
	v_mfma_f32_32x32x16_bf16 v[64:79], v[188:191], v[226:229], v[64:79]
	v_mfma_f32_32x32x16_bf16 v[0:15], v[192:195], v[226:229], v[0:15]
	s_waitcnt vmcnt(0) lgkmcnt(0)
	s_barrier
	v_xor_b32_e32 v230, 0x10000, v230
	v_xor_b32_e32 v234, 0x10000, v234
	ds_read_b128 v[188:191], v230
	ds_read_b128 v[196:199], v234
	ds_read_b128 v[192:195], v230 offset:4096
	ds_read_b128 v[200:203], v234 offset:4096
	ds_read_b128 v[204:207], v234 offset:8192
	ds_read_b128 v[226:229], v234 offset:12288
	s_cmpk_eq_i32 s2, 0x700
	s_cbranch_scc1 .Lgk1_nodma
	s_add_u32 s94, s2, s92
	s_add_u32 s94, s94, 0x100
	s_and_b32 s94, s94, 0x780
	s_sub_u32 s94, s94, 0x80
	s_subb_u32 s95, 0, 0
	s_add_u32 s100, s96, s94
	s_addc_u32 s101, s97, s95
	s_add_u32 s94, s98, s94
	s_addc_u32 s95, s99, s95
	s_add_u32 s90, s88, s89
	v_mfma_f32_32x32x16_bf16 v[112:127], v[128:131], v[136:139], v[112:127]
	v_xor_b32_e32 v231, 0x10000, v231
	v_xor_b32_e32 v235, 0x10000, v235
	s_add_u32 m0, s90, 0
	s_nop 0
	global_load_lds_dwordx4 v152, s[100:101]
	v_mfma_f32_32x32x16_bf16 v[48:63], v[132:135], v[136:139], v[48:63]
	v_xor_b32_e32 v232, 0x10000, v232
	v_xor_b32_e32 v236, 0x10000, v236
	s_add_u32 m0, s90, 32768
	s_nop 0
	global_load_lds_dwordx4 v153, s[94:95]
	v_mfma_f32_32x32x16_bf16 v[96:111], v[128:131], v[140:143], v[96:111]
	v_xor_b32_e32 v233, 0x10000, v233
	v_xor_b32_e32 v237, 0x10000, v237
	s_add_u32 m0, s90, 8192
	s_nop 0
	global_load_lds_dwordx4 v154, s[100:101]
	v_mfma_f32_32x32x16_bf16 v[32:47], v[132:135], v[140:143], v[32:47]
	s_add_u32 m0, s90, 40960
	s_nop 0
	global_load_lds_dwordx4 v155, s[94:95]
	v_mfma_f32_32x32x16_bf16 v[80:95], v[128:131], v[144:147], v[80:95]
	s_add_u32 m0, s90, 16384
	s_nop 0
	global_load_lds_dwordx4 v156, s[100:101]
	v_mfma_f32_32x32x16_bf16 v[16:31], v[132:135], v[144:147], v[16:31]
	s_add_u32 m0, s90, 49152
	s_nop 0
	global_load_lds_dwordx4 v157, s[94:95]
	v_mfma_f32_32x32x16_bf16 v[64:79], v[128:131], v[148:151], v[64:79]
	s_add_u32 m0, s90, 24576
	s_nop 0
	global_load_lds_dwordx4 v158, s[100:101]
	v_mfma_f32_32x32x16_bf16 v[0:15], v[132:135], v[148:151], v[0:15]
	s_add_u32 m0, s90, 57344
	s_nop 0
	global_load_lds_dwordx4 v168, s[94:95]
	s_branch .Lgk1_join

.LBB0_1466:
	s_mul_hi_i32 s2, s8, 0x38e38e39
	s_lshr_b32 s3, s2, 31
	s_ashr_i32 s4, s2, 1
	s_add_i32 s4, s4, s3
	s_lshl_b32 s77, s4, 8
	v_add_u32_e32 v0, s77, v193
	v_min_i32_e32 v0, 0x7fff, v0
	v_ashrrev_i32_e32 v1, 31, v0
	v_lshlrev_b64 v[0:1], 11, v[0:1]
	s_mul_i32 s2, s4, 0x900
	v_lshl_add_u64 v[172:173], v[168:169], 0, v[0:1]
	v_subrev_u32_e32 v0, s2, v201
	v_ashrrev_i32_e32 v1, 31, v0
	v_lshlrev_b64 v[0:1], 11, v[0:1]
	v_lshl_add_u64 v[180:181], v[170:171], 0, v[0:1]
	v_subrev_u32_e32 v0, s2, v202
	v_ashrrev_i32_e32 v1, 31, v0
	v_lshlrev_b64 v[0:1], 11, v[0:1]
	v_lshl_add_u64 v[182:183], v[170:171], 0, v[0:1]
	v_subrev_u32_e32 v0, s2, v203
	v_ashrrev_i32_e32 v1, 31, v0
	v_add_u32_e32 v2, s77, v194
	v_add_u32_e32 v4, s77, v163
	v_add_u32_e32 v6, s77, v196
	v_lshlrev_b64 v[0:1], 11, v[0:1]
	v_min_i32_e32 v2, 0x7fff, v2
	v_min_i32_e32 v4, 0x7fff, v4
	v_min_i32_e32 v6, 0x7fff, v6
	v_lshl_add_u64 v[184:185], v[170:171], 0, v[0:1]
	v_subrev_u32_e32 v0, s2, v204
	v_ashrrev_i32_e32 v3, 31, v2
	v_ashrrev_i32_e32 v5, 31, v4
	v_ashrrev_i32_e32 v7, 31, v6
	v_ashrrev_i32_e32 v1, 31, v0
	v_lshlrev_b64 v[2:3], 11, v[2:3]
	v_lshlrev_b64 v[4:5], 11, v[4:5]
	v_lshlrev_b64 v[6:7], 11, v[6:7]
	v_lshlrev_b64 v[0:1], 11, v[0:1]
	v_lshl_add_u64 v[174:175], v[168:169], 0, v[2:3]
	v_lshl_add_u64 v[176:177], v[168:169], 0, v[4:5]
	v_lshl_add_u64 v[178:179], v[168:169], 0, v[6:7]
	v_lshl_add_u64 v[186:187], v[170:171], 0, v[0:1]
	s_mov_b64 s[2:3], 0
	s_mov_b32 s5, s25
	v_mov_b32_e32 v0, 0
	v_mov_b32_e32 v1, v161
	v_mov_b32_e32 v2, v161
	v_mov_b32_e32 v3, v161
	v_mov_b32_e32 v4, v161
	v_mov_b32_e32 v5, v161
	v_mov_b32_e32 v6, v161
	v_mov_b32_e32 v7, v161
	v_mov_b32_e32 v8, v161
	v_mov_b32_e32 v9, v161
	v_mov_b32_e32 v10, v161
	v_mov_b32_e32 v11, v161
	v_mov_b32_e32 v12, v161
	v_mov_b32_e32 v13, v161
	v_mov_b32_e32 v14, v161
	v_mov_b32_e32 v15, v161
	v_mov_b32_e32 v16, 0
	v_mov_b32_e32 v17, v161
	v_mov_b32_e32 v18, v161
	v_mov_b32_e32 v19, v161
	v_mov_b32_e32 v20, v161
	v_mov_b32_e32 v21, v161
	v_mov_b32_e32 v22, v161
	v_mov_b32_e32 v23, v161
	v_mov_b32_e32 v24, v161
	v_mov_b32_e32 v25, v161
	v_mov_b32_e32 v26, v161
	v_mov_b32_e32 v27, v161
	v_mov_b32_e32 v28, v161
	v_mov_b32_e32 v29, v161
	v_mov_b32_e32 v30, v161
	v_mov_b32_e32 v31, v161
	v_mov_b32_e32 v32, 0
	v_mov_b32_e32 v33, v161
	v_mov_b32_e32 v34, v161
	v_mov_b32_e32 v35, v161
	v_mov_b32_e32 v36, v161
	v_mov_b32_e32 v37, v161
	v_mov_b32_e32 v38, v161
	v_mov_b32_e32 v39, v161
	v_mov_b32_e32 v40, v161
	v_mov_b32_e32 v41, v161
	v_mov_b32_e32 v42, v161
	v_mov_b32_e32 v43, v161
	v_mov_b32_e32 v44, v161
	v_mov_b32_e32 v45, v161
	v_mov_b32_e32 v46, v161
	v_mov_b32_e32 v47, v161
	v_mov_b32_e32 v48, 0
	v_mov_b32_e32 v49, v161
	v_mov_b32_e32 v50, v161
	v_mov_b32_e32 v51, v161
	v_mov_b32_e32 v52, v161
	v_mov_b32_e32 v53, v161
	v_mov_b32_e32 v54, v161
	v_mov_b32_e32 v55, v161
	v_mov_b32_e32 v56, v161
	v_mov_b32_e32 v57, v161
	v_mov_b32_e32 v58, v161
	v_mov_b32_e32 v59, v161
	v_mov_b32_e32 v60, v161
	v_mov_b32_e32 v61, v161
	v_mov_b32_e32 v62, v161
	v_mov_b32_e32 v63, v161
	v_mov_b32_e32 v64, 0
	v_mov_b32_e32 v65, v161
	v_mov_b32_e32 v66, v161
	v_mov_b32_e32 v67, v161
	v_mov_b32_e32 v68, v161
	v_mov_b32_e32 v69, v161
	v_mov_b32_e32 v70, v161
	v_mov_b32_e32 v71, v161
	v_mov_b32_e32 v72, v161
	v_mov_b32_e32 v73, v161
	v_mov_b32_e32 v74, v161
	v_mov_b32_e32 v75, v161
	v_mov_b32_e32 v76, v161
	v_mov_b32_e32 v77, v161
	v_mov_b32_e32 v78, v161
	v_mov_b32_e32 v79, v161
	v_mov_b32_e32 v80, 0
	v_mov_b32_e32 v81, v161
	v_mov_b32_e32 v82, v161
	v_mov_b32_e32 v83, v161
	v_mov_b32_e32 v84, v161
	v_mov_b32_e32 v85, v161
	v_mov_b32_e32 v86, v161
	v_mov_b32_e32 v87, v161
	v_mov_b32_e32 v88, v161
	v_mov_b32_e32 v89, v161
	v_mov_b32_e32 v90, v161
	v_mov_b32_e32 v91, v161
	v_mov_b32_e32 v92, v161
	v_mov_b32_e32 v93, v161
	v_mov_b32_e32 v94, v161
	v_mov_b32_e32 v95, v161
	v_mov_b32_e32 v96, 0
	v_mov_b32_e32 v97, v161
	v_mov_b32_e32 v98, v161
	v_mov_b32_e32 v99, v161
	v_mov_b32_e32 v100, v161
	v_mov_b32_e32 v101, v161
	v_mov_b32_e32 v102, v161
	v_mov_b32_e32 v103, v161
	v_mov_b32_e32 v104, v161
	v_mov_b32_e32 v105, v161
	v_mov_b32_e32 v106, v161
	v_mov_b32_e32 v107, v161
	v_mov_b32_e32 v108, v161
	v_mov_b32_e32 v109, v161
	v_mov_b32_e32 v110, v161
	v_mov_b32_e32 v111, v161
	v_mov_b32_e32 v112, 0
	v_mov_b32_e32 v113, v161
	v_mov_b32_e32 v114, v161
	v_mov_b32_e32 v115, v161
	v_mov_b32_e32 v116, v161
	v_mov_b32_e32 v117, v161
	v_mov_b32_e32 v118, v161
	v_mov_b32_e32 v119, v161
	v_mov_b32_e32 v120, v161
	v_mov_b32_e32 v121, v161
	v_mov_b32_e32 v122, v161
	v_mov_b32_e32 v123, v161
	v_mov_b32_e32 v124, v161
	v_mov_b32_e32 v125, v161
	v_mov_b32_e32 v126, v161
	v_mov_b32_e32 v127, v161
	v_mbcnt_hi_u32_b32 v128, -1, v210
	s_and_b32 s90, s70, 0x40
	v_and_b32_e32 v159, 48, v128
	v_or_b32_e32 v159, s90, v159
	v_and_b32_e32 v129, 31, v128
	v_lshrrev_b32_e32 v130, 5, v128
	v_bfe_u32 v131, v128, 1, 3
	v_lshlrev_b32_e32 v132, 7, v129
	s_lshr_b32 s91, s70, 7
	s_lshl_b32 s91, s91, 13
	s_lshl_b32 s90, s90, 8
	s_add_u32 s90, s90, 0x8000
	s_lshl_b32 s88, s70, 4
	s_mov_b32 s89, 0x10000
	s_lshl_b32 s92, s22, 4
	s_and_b32 s92, s92, 0x780
	s_mov_b32 s93, 0
	s_load_dwordx2 s[96:97], s[0:1], 0x158
	s_load_dwordx2 s[98:99], s[0:1], 0x100
	s_waitcnt lgkmcnt(0)
	v_subrev_u32_e32 v152, s96, v172
	v_xor_b32_e32 v152, v159, v152
	v_subrev_u32_e32 v153, s98, v180
	v_xor_b32_e32 v153, v159, v153
	v_subrev_u32_e32 v154, s96, v174
	v_xor_b32_e32 v154, v159, v154
	v_subrev_u32_e32 v155, s98, v182
	v_xor_b32_e32 v155, v159, v155
	v_subrev_u32_e32 v156, s96, v176
	v_xor_b32_e32 v156, v159, v156
	v_subrev_u32_e32 v157, s98, v184
	v_xor_b32_e32 v157, v159, v157
	v_subrev_u32_e32 v158, s96, v178
	v_xor_b32_e32 v158, v159, v158
	v_subrev_u32_e32 v160, s98, v186
	v_xor_b32_e32 v160, v159, v160
	v_xor_b32_e32 v133, v130, v131
	v_lshl_add_u32 v133, v133, 4, v132
	v_add_u32_e32 v232, s91, v133
	v_add_u32_e32 v236, s90, v133
	v_or_b32_e32 v133, 2, v130
	v_xor_b32_e32 v133, v133, v131
	v_lshl_add_u32 v133, v133, 4, v132
	v_add_u32_e32 v233, s91, v133
	v_add_u32_e32 v237, s90, v133
	v_or_b32_e32 v133, 4, v130
	v_xor_b32_e32 v133, v133, v131
	v_lshl_add_u32 v133, v133, 4, v132
	v_add_u32_e32 v234, s91, v133
	v_add_u32_e32 v238, s90, v133
	v_or_b32_e32 v133, 6, v130
	v_xor_b32_e32 v133, v133, v131
	v_lshl_add_u32 v133, v133, 4, v132
	v_add_u32_e32 v235, s91, v133
	v_add_u32_e32 v239, s90, v133
	s_barrier
	ds_read_b128 v[188:191], v232
	ds_read_b128 v[216:219], v236
	ds_read_b128 v[212:215], v232 offset:4096
	ds_read_b128 v[220:223], v236 offset:4096
	ds_read_b128 v[224:227], v236 offset:8192
	ds_read_b128 v[228:231], v236 offset:12288
	s_add_u32 s94, s2, s92
	s_add_u32 s94, s94, 0x80
	s_and_b32 s94, s94, 0x780
	s_sub_u32 s94, s94, 0x80
	s_subb_u32 s95, 0, 0
	s_add_u32 s100, s96, s94
	s_addc_u32 s101, s97, s95
	s_add_u32 s94, s98, s94
	s_addc_u32 s95, s99, s95
	s_add_u32 s90, s88, s89
	s_add_u32 m0, s90, 0
	s_nop 0
	global_load_lds_dwordx4 v152, s[100:101]
	s_add_u32 m0, s90, 32768
	s_nop 0
	global_load_lds_dwordx4 v153, s[94:95]
	s_add_u32 m0, s90, 8192
	s_nop 0
	global_load_lds_dwordx4 v154, s[100:101]
	s_add_u32 m0, s90, 40960
	s_nop 0
	global_load_lds_dwordx4 v155, s[94:95]
	s_add_u32 m0, s90, 16384
	s_nop 0
	global_load_lds_dwordx4 v156, s[100:101]
	s_add_u32 m0, s90, 49152
	s_nop 0
	global_load_lds_dwordx4 v157, s[94:95]
	s_add_u32 m0, s90, 24576
	s_nop 0
	global_load_lds_dwordx4 v158, s[100:101]
	s_add_u32 m0, s90, 57344
	s_nop 0
	global_load_lds_dwordx4 v160, s[94:95]
	s_xor_b32 s89, s89, 0x10000
.Lgk2_loop:
	ds_read_b128 v[128:131], v233
	ds_read_b128 v[136:139], v237
	ds_read_b128 v[132:135], v233 offset:4096
	ds_read_b128 v[140:143], v237 offset:4096
	ds_read_b128 v[144:147], v237 offset:8192
	ds_read_b128 v[148:151], v237 offset:12288
	s_waitcnt lgkmcnt(6)
	v_mfma_f32_32x32x16_bf16 v[112:127], v[188:191], v[216:219], v[112:127]
	v_mfma_f32_32x32x16_bf16 v[48:63], v[212:215], v[216:219], v[48:63]
	v_mfma_f32_32x32x16_bf16 v[96:111], v[188:191], v[220:223], v[96:111]
	v_mfma_f32_32x32x16_bf16 v[32:47], v[212:215], v[220:223], v[32:47]
	v_mfma_f32_32x32x16_bf16 v[80:95], v[188:191], v[224:227], v[80:95]
	v_mfma_f32_32x32x16_bf16 v[16:31], v[212:215], v[224:227], v[16:31]
	v_mfma_f32_32x32x16_bf16 v[64:79], v[188:191], v[228:231], v[64:79]
	v_mfma_f32_32x32x16_bf16 v[0:15], v[212:215], v[228:231], v[0:15]
	ds_read_b128 v[188:191], v234
	ds_read_b128 v[216:219], v238
	ds_read_b128 v[212:215], v234 offset:4096
	ds_read_b128 v[220:223], v238 offset:4096
	ds_read_b128 v[224:227], v238 offset:8192
	ds_read_b128 v[228:231], v238 offset:12288
	s_waitcnt lgkmcnt(6)
	v_mfma_f32_32x32x16_bf16 v[112:127], v[128:131], v[136:139], v[112:127]
	v_mfma_f32_32x32x16_bf16 v[48:63], v[132:135], v[136:139], v[48:63]
	v_mfma_f32_32x32x16_bf16 v[96:111], v[128:131], v[140:143], v[96:111]
	v_mfma_f32_32x32x16_bf16 v[32:47], v[132:135], v[140:143], v[32:47]
	v_mfma_f32_32x32x16_bf16 v[80:95], v[128:131], v[144:147], v[80:95]
	v_mfma_f32_32x32x16_bf16 v[16:31], v[132:135], v[144:147], v[16:31]
	v_mfma_f32_32x32x16_bf16 v[64:79], v[128:131], v[148:151], v[64:79]
	v_mfma_f32_32x32x16_bf16 v[0:15], v[132:135], v[148:151], v[0:15]
	ds_read_b128 v[128:131], v235
	ds_read_b128 v[136:139], v239
	ds_read_b128 v[132:135], v235 offset:4096
	ds_read_b128 v[140:143], v239 offset:4096
	ds_read_b128 v[144:147], v239 offset:8192
	ds_read_b128 v[148:151], v239 offset:12288
	s_waitcnt lgkmcnt(6)
	v_mfma_f32_32x32x16_bf16 v[112:127], v[188:191], v[216:219], v[112:127]
	v_mfma_f32_32x32x16_bf16 v[48:63], v[212:215], v[216:219], v[48:63]
	v_mfma_f32_32x32x16_bf16 v[96:111], v[188:191], v[220:223], v[96:111]
	v_mfma_f32_32x32x16_bf16 v[32:47], v[212:215], v[220:223], v[32:47]
	v_mfma_f32_32x32x16_bf16 v[80:95], v[188:191], v[224:227], v[80:95]
	v_mfma_f32_32x32x16_bf16 v[16:31], v[212:215], v[224:227], v[16:31]
	v_mfma_f32_32x32x16_bf16 v[64:79], v[188:191], v[228:231], v[64:79]
	v_mfma_f32_32x32x16_bf16 v[0:15], v[212:215], v[228:231], v[0:15]
	s_waitcnt vmcnt(0) lgkmcnt(0)
	s_barrier
	v_xor_b32_e32 v232, 0x10000, v232
	v_xor_b32_e32 v236, 0x10000, v236
	ds_read_b128 v[188:191], v232
	ds_read_b128 v[216:219], v236
	ds_read_b128 v[212:215], v232 offset:4096
	ds_read_b128 v[220:223], v236 offset:4096
	ds_read_b128 v[224:227], v236 offset:8192
	ds_read_b128 v[228:231], v236 offset:12288
	s_cmpk_eq_i32 s2, 0x700
	s_cbranch_scc1 .Lgk2_nodma
	s_add_u32 s94, s2, s92
	s_add_u32 s94, s94, 0x100
	s_and_b32 s94, s94, 0x780
	s_sub_u32 s94, s94, 0x80
	s_subb_u32 s95, 0, 0
	s_add_u32 s100, s96, s94
	s_addc_u32 s101, s97, s95
	s_add_u32 s94, s98, s94
	s_addc_u32 s95, s99, s95
	s_add_u32 s90, s88, s89
	v_mfma_f32_32x32x16_bf16 v[112:127], v[128:131], v[136:139], v[112:127]
	v_xor_b32_e32 v233, 0x10000, v233
	v_xor_b32_e32 v237, 0x10000, v237
	s_add_u32 m0, s90, 0
	s_nop 0
	global_load_lds_dwordx4 v152, s[100:101]
	v_mfma_f32_32x32x16_bf16 v[48:63], v[132:135], v[136:139], v[48:63]
	v_xor_b32_e32 v234, 0x10000, v234
	v_xor_b32_e32 v238, 0x10000, v238
	s_add_u32 m0, s90, 32768
	s_nop 0
	global_load_lds_dwordx4 v153, s[94:95]
	v_mfma_f32_32x32x16_bf16 v[96:111], v[128:131], v[140:143], v[96:111]
	v_xor_b32_e32 v235, 0x10000, v235
	v_xor_b32_e32 v239, 0x10000, v239
	s_add_u32 m0, s90, 8192
	s_nop 0
	global_load_lds_dwordx4 v154, s[100:101]
	v_mfma_f32_32x32x16_bf16 v[32:47], v[132:135], v[140:143], v[32:47]
	s_add_u32 m0, s90, 40960
	s_nop 0
	global_load_lds_dwordx4 v155, s[94:95]
	v_mfma_f32_32x32x16_bf16 v[80:95], v[128:131], v[144:147], v[80:95]
	s_add_u32 m0, s90, 16384
	s_nop 0
	global_load_lds_dwordx4 v156, s[100:101]
	v_mfma_f32_32x32x16_bf16 v[16:31], v[132:135], v[144:147], v[16:31]
	s_add_u32 m0, s90, 49152
	s_nop 0
	global_load_lds_dwordx4 v157, s[94:95]
	v_mfma_f32_32x32x16_bf16 v[64:79], v[128:131], v[148:151], v[64:79]
	s_add_u32 m0, s90, 24576
	s_nop 0
	global_load_lds_dwordx4 v158, s[100:101]
	v_mfma_f32_32x32x16_bf16 v[0:15], v[132:135], v[148:151], v[0:15]
	s_add_u32 m0, s90, 57344
	s_nop 0
	global_load_lds_dwordx4 v160, s[94:95]
	s_branch .Lgk2_join

.LBB0_1470:
	ds_read_b128 v[128:131], v233
	ds_read_b128 v[136:139], v237
	ds_read_b128 v[132:135], v233 offset:4096
	ds_read_b128 v[140:143], v237 offset:4096
	ds_read_b128 v[144:147], v237 offset:8192
	ds_read_b128 v[148:151], v237 offset:12288
	s_waitcnt lgkmcnt(6)
	v_mfma_f32_32x32x16_bf16 v[112:127], v[188:191], v[216:219], v[112:127]
	v_mfma_f32_32x32x16_bf16 v[48:63], v[212:215], v[216:219], v[48:63]
	v_mfma_f32_32x32x16_bf16 v[96:111], v[188:191], v[220:223], v[96:111]
	v_mfma_f32_32x32x16_bf16 v[32:47], v[212:215], v[220:223], v[32:47]
	v_mfma_f32_32x32x16_bf16 v[80:95], v[188:191], v[224:227], v[80:95]
	v_mfma_f32_32x32x16_bf16 v[16:31], v[212:215], v[224:227], v[16:31]
	v_mfma_f32_32x32x16_bf16 v[64:79], v[188:191], v[228:231], v[64:79]
	v_mfma_f32_32x32x16_bf16 v[0:15], v[212:215], v[228:231], v[0:15]
	ds_read_b128 v[188:191], v234
	ds_read_b128 v[216:219], v238
	ds_read_b128 v[212:215], v234 offset:4096
	ds_read_b128 v[220:223], v238 offset:4096
	ds_read_b128 v[224:227], v238 offset:8192
	ds_read_b128 v[228:231], v238 offset:12288
	s_waitcnt lgkmcnt(6)
	v_mfma_f32_32x32x16_bf16 v[112:127], v[128:131], v[136:139], v[112:127]
	v_mfma_f32_32x32x16_bf16 v[48:63], v[132:135], v[136:139], v[48:63]
	v_mfma_f32_32x32x16_bf16 v[96:111], v[128:131], v[140:143], v[96:111]
	v_mfma_f32_32x32x16_bf16 v[32:47], v[132:135], v[140:143], v[32:47]
	v_mfma_f32_32x32x16_bf16 v[80:95], v[128:131], v[144:147], v[80:95]
	v_mfma_f32_32x32x16_bf16 v[16:31], v[132:135], v[144:147], v[16:31]
	v_mfma_f32_32x32x16_bf16 v[64:79], v[128:131], v[148:151], v[64:79]
	v_mfma_f32_32x32x16_bf16 v[0:15], v[132:135], v[148:151], v[0:15]
	ds_read_b128 v[128:131], v235
	ds_read_b128 v[136:139], v239
	ds_read_b128 v[132:135], v235 offset:4096
	ds_read_b128 v[140:143], v239 offset:4096
	ds_read_b128 v[144:147], v239 offset:8192
	ds_read_b128 v[148:151], v239 offset:12288
	s_waitcnt lgkmcnt(6)
	v_mfma_f32_32x32x16_bf16 v[112:127], v[188:191], v[216:219], v[112:127]
	v_mfma_f32_32x32x16_bf16 v[48:63], v[212:215], v[216:219], v[48:63]
	v_mfma_f32_32x32x16_bf16 v[96:111], v[188:191], v[220:223], v[96:111]
	v_mfma_f32_32x32x16_bf16 v[32:47], v[212:215], v[220:223], v[32:47]
	v_mfma_f32_32x32x16_bf16 v[80:95], v[188:191], v[224:227], v[80:95]
	v_mfma_f32_32x32x16_bf16 v[16:31], v[212:215], v[224:227], v[16:31]
	v_mfma_f32_32x32x16_bf16 v[64:79], v[188:191], v[228:231], v[64:79]
	v_mfma_f32_32x32x16_bf16 v[0:15], v[212:215], v[228:231], v[0:15]
	s_waitcnt vmcnt(0) lgkmcnt(0)
	s_barrier
	v_xor_b32_e32 v232, 0x10000, v232
	v_xor_b32_e32 v236, 0x10000, v236
	v_mfma_f32_32x32x16_bf16 v[112:127], v[128:131], v[136:139], v[112:127]
	v_xor_b32_e32 v233, 0x10000, v233
	v_xor_b32_e32 v237, 0x10000, v237
	v_mfma_f32_32x32x16_bf16 v[48:63], v[132:135], v[136:139], v[48:63]
	v_xor_b32_e32 v234, 0x10000, v234
	v_xor_b32_e32 v238, 0x10000, v238
	v_mfma_f32_32x32x16_bf16 v[96:111], v[128:131], v[140:143], v[96:111]
	v_xor_b32_e32 v235, 0x10000, v235
	v_xor_b32_e32 v239, 0x10000, v239
	v_mfma_f32_32x32x16_bf16 v[32:47], v[132:135], v[140:143], v[32:47]
	v_mfma_f32_32x32x16_bf16 v[80:95], v[128:131], v[144:147], v[80:95]
	v_mfma_f32_32x32x16_bf16 v[16:31], v[132:135], v[144:147], v[16:31]
	v_mfma_f32_32x32x16_bf16 v[64:79], v[128:131], v[148:151], v[64:79]
	v_mfma_f32_32x32x16_bf16 v[0:15], v[132:135], v[148:151], v[0:15]
	v_mbcnt_hi_u32_b32 v229, -1, v210
	v_and_b32_e32 v230, 31, v229
	v_lshrrev_b32_e32 v231, 5, v229
	v_lshlrev_b32_e32 v160, 3, v230
	v_lshlrev_b32_e32 v226, 2, v231
	s_lshr_b32 s90, s70, 6
	s_mul_i32 s91, s90, 0x1200
	s_add_u32 s91, s91, 0x12000
	v_mul_u32_u24_e32 v232, 0x240, v231
	v_lshl_add_u32 v232, v230, 1, v232
	v_add_u32_e32 v224, s91, v232
	v_lshrrev_b32_e32 v227, 3, v229
	v_and_b32_e32 v233, 7, v229
	v_lshlrev_b32_e32 v228, 4, v233
	v_mul_u32_u24_e32 v232, 0x90, v227
	v_add3_u32 v225, v232, v228, s91
	s_mul_i32 s92, s4, 9
	s_sub_u32 s93, s8, s92
	s_lshl_b32 s93, s93, 8
	s_lshl_b32 s92, s4, 8
	s_lshr_b32 s94, s90, 1
	s_lshl_b32 s94, s94, 6
	s_add_u32 s92, s92, s94
	s_and_b32 s94, s90, 1
	s_lshl_b32 s94, s94, 7
	s_add_u32 s93, s93, s94

.Lep2_00_st:
	v_add_u32_e32 v233, s94, v227
	s_waitcnt lgkmcnt(0)
	ds_read_b128 v[188:191], v225
	ds_read_b128 v[212:215], v225 offset:1152
	ds_read_b128 v[216:219], v225 offset:2304
	ds_read_b128 v[220:223], v225 offset:3456
	v_add_u32_e32 v229, 0, v233
	v_mul_lo_u32 v229, v229, s89
	v_add3_u32 v229, v229, v228, s91
	v_add_u32_e32 v230, 8, v233
	v_mul_lo_u32 v230, v230, s89
	v_add3_u32 v230, v230, v228, s91
	v_add_u32_e32 v231, 16, v233
	v_mul_lo_u32 v231, v231, s89
	v_add3_u32 v231, v231, v228, s91
	v_add_u32_e32 v232, 24, v233
	v_mul_lo_u32 v232, v232, s89
	v_add3_u32 v232, v232, v228, s91
	s_waitcnt lgkmcnt(3)
	global_store_dwordx4 v229, v[188:191], s[96:97]
	s_waitcnt lgkmcnt(2)
	global_store_dwordx4 v230, v[212:215], s[96:97]
	s_waitcnt lgkmcnt(1)
	global_store_dwordx4 v231, v[216:219], s[96:97]
	s_waitcnt lgkmcnt(0)
	global_store_dwordx4 v232, v[220:223], s[96:97]

.LBB0_2219:
	s_ashr_i32 s2, s54, 31
	s_lshr_b32 s2, s2, 30
	s_add_i32 s2, s54, s2
	s_ashr_i32 s2, s2, 2
	s_lshl_b32 s4, s2, 8
	v_add_u32_e32 v0, s4, v212
	v_min_i32_e32 v0, 0x7fff, v0
	v_ashrrev_i32_e32 v1, 31, v0
	s_lshl_b32 s6, s2, 10
	v_lshlrev_b64 v[0:1], 11, v[0:1]
	v_lshl_add_u64 v[160:161], v[176:177], 0, v[0:1]
	v_subrev_u32_e32 v0, s6, v220
	v_ashrrev_i32_e32 v1, 31, v0
	v_lshlrev_b64 v[0:1], 11, v[0:1]
	v_lshl_add_u64 v[180:181], v[178:179], 0, v[0:1]
	v_subrev_u32_e32 v0, s6, v221
	v_ashrrev_i32_e32 v1, 31, v0
	v_lshlrev_b64 v[0:1], 11, v[0:1]
	v_lshl_add_u64 v[182:183], v[178:179], 0, v[0:1]
	v_subrev_u32_e32 v0, s6, v222
	v_ashrrev_i32_e32 v1, 31, v0
	v_add_u32_e32 v2, s4, v213
	v_add_u32_e32 v4, s4, v171
	v_add_u32_e32 v6, s4, v215
	v_lshlrev_b64 v[0:1], 11, v[0:1]
	v_min_i32_e32 v2, 0x7fff, v2
	v_min_i32_e32 v4, 0x7fff, v4
	v_min_i32_e32 v6, 0x7fff, v6
	v_lshl_add_u64 v[184:185], v[178:179], 0, v[0:1]
	v_subrev_u32_e32 v0, s6, v223
	v_ashrrev_i32_e32 v3, 31, v2
	v_ashrrev_i32_e32 v5, 31, v4
	v_ashrrev_i32_e32 v7, 31, v6
	v_ashrrev_i32_e32 v1, 31, v0
	v_lshlrev_b64 v[2:3], 11, v[2:3]
	v_lshlrev_b64 v[4:5], 11, v[4:5]
	v_lshlrev_b64 v[6:7], 11, v[6:7]
	v_lshlrev_b64 v[0:1], 11, v[0:1]
	s_mov_b32 s5, s54
	v_lshl_add_u64 v[162:163], v[176:177], 0, v[2:3]
	v_lshl_add_u64 v[164:165], v[176:177], 0, v[4:5]
	v_lshl_add_u64 v[166:167], v[176:177], 0, v[6:7]
	v_lshl_add_u64 v[186:187], v[178:179], 0, v[0:1]
	s_mov_b64 s[2:3], 0
	s_mov_b32 s7, 0
	v_mov_b32_e32 v0, 0
	v_mov_b32_e32 v1, v169
	v_mov_b32_e32 v2, v169
	v_mov_b32_e32 v3, v169
	v_mov_b32_e32 v4, v169
	v_mov_b32_e32 v5, v169
	v_mov_b32_e32 v6, v169
	v_mov_b32_e32 v7, v169
	v_mov_b32_e32 v8, v169
	v_mov_b32_e32 v9, v169
	v_mov_b32_e32 v10, v169
	v_mov_b32_e32 v11, v169
	v_mov_b32_e32 v12, v169
	v_mov_b32_e32 v13, v169
	v_mov_b32_e32 v14, v169
	v_mov_b32_e32 v15, v169
	v_mov_b32_e32 v16, 0
	v_mov_b32_e32 v17, v169
	v_mov_b32_e32 v18, v169
	v_mov_b32_e32 v19, v169
	v_mov_b32_e32 v20, v169
	v_mov_b32_e32 v21, v169
	v_mov_b32_e32 v22, v169
	v_mov_b32_e32 v23, v169
	v_mov_b32_e32 v24, v169
	v_mov_b32_e32 v25, v169
	v_mov_b32_e32 v26, v169
	v_mov_b32_e32 v27, v169
	v_mov_b32_e32 v28, v169
	v_mov_b32_e32 v29, v169
	v_mov_b32_e32 v30, v169
	v_mov_b32_e32 v31, v169
	v_mov_b32_e32 v32, 0
	v_mov_b32_e32 v33, v169
	v_mov_b32_e32 v34, v169
	v_mov_b32_e32 v35, v169
	v_mov_b32_e32 v36, v169
	v_mov_b32_e32 v37, v169
	v_mov_b32_e32 v38, v169
	v_mov_b32_e32 v39, v169
	v_mov_b32_e32 v40, v169
	v_mov_b32_e32 v41, v169
	v_mov_b32_e32 v42, v169
	v_mov_b32_e32 v43, v169
	v_mov_b32_e32 v44, v169
	v_mov_b32_e32 v45, v169
	v_mov_b32_e32 v46, v169
	v_mov_b32_e32 v47, v169
	v_mov_b32_e32 v48, 0
	v_mov_b32_e32 v49, v169
	v_mov_b32_e32 v50, v169
	v_mov_b32_e32 v51, v169
	v_mov_b32_e32 v52, v169
	v_mov_b32_e32 v53, v169
	v_mov_b32_e32 v54, v169
	v_mov_b32_e32 v55, v169
	v_mov_b32_e32 v56, v169
	v_mov_b32_e32 v57, v169
	v_mov_b32_e32 v58, v169
	v_mov_b32_e32 v59, v169
	v_mov_b32_e32 v60, v169
	v_mov_b32_e32 v61, v169
	v_mov_b32_e32 v62, v169
	v_mov_b32_e32 v63, v169
	v_mov_b32_e32 v64, 0
	v_mov_b32_e32 v65, v169
	v_mov_b32_e32 v66, v169
	v_mov_b32_e32 v67, v169
	v_mov_b32_e32 v68, v169
	v_mov_b32_e32 v69, v169
	v_mov_b32_e32 v70, v169
	v_mov_b32_e32 v71, v169
	v_mov_b32_e32 v72, v169
	v_mov_b32_e32 v73, v169
	v_mov_b32_e32 v74, v169
	v_mov_b32_e32 v75, v169
	v_mov_b32_e32 v76, v169
	v_mov_b32_e32 v77, v169
	v_mov_b32_e32 v78, v169
	v_mov_b32_e32 v79, v169
	v_mov_b32_e32 v80, 0
	v_mov_b32_e32 v81, v169
	v_mov_b32_e32 v82, v169
	v_mov_b32_e32 v83, v169
	v_mov_b32_e32 v84, v169
	v_mov_b32_e32 v85, v169
	v_mov_b32_e32 v86, v169
	v_mov_b32_e32 v87, v169
	v_mov_b32_e32 v88, v169
	v_mov_b32_e32 v89, v169
	v_mov_b32_e32 v90, v169
	v_mov_b32_e32 v91, v169
	v_mov_b32_e32 v92, v169
	v_mov_b32_e32 v93, v169
	v_mov_b32_e32 v94, v169
	v_mov_b32_e32 v95, v169
	v_mov_b32_e32 v96, 0
	v_mov_b32_e32 v97, v169
	v_mov_b32_e32 v98, v169
	v_mov_b32_e32 v99, v169
	v_mov_b32_e32 v100, v169
	v_mov_b32_e32 v101, v169
	v_mov_b32_e32 v102, v169
	v_mov_b32_e32 v103, v169
	v_mov_b32_e32 v104, v169
	v_mov_b32_e32 v105, v169
	v_mov_b32_e32 v106, v169
	v_mov_b32_e32 v107, v169
	v_mov_b32_e32 v108, v169
	v_mov_b32_e32 v109, v169
	v_mov_b32_e32 v110, v169
	v_mov_b32_e32 v111, v169
	v_mov_b32_e32 v112, 0
	v_mov_b32_e32 v113, v169
	v_mov_b32_e32 v114, v169
	v_mov_b32_e32 v115, v169
	v_mov_b32_e32 v116, v169
	v_mov_b32_e32 v117, v169
	v_mov_b32_e32 v118, v169
	v_mov_b32_e32 v119, v169
	v_mov_b32_e32 v120, v169
	v_mov_b32_e32 v121, v169
	v_mov_b32_e32 v122, v169
	v_mov_b32_e32 v123, v169
	v_mov_b32_e32 v124, v169
	v_mov_b32_e32 v125, v169
	v_mov_b32_e32 v126, v169
	v_mov_b32_e32 v127, v169
	v_mbcnt_hi_u32_b32 v128, -1, v210
	s_and_b32 s90, s70, 0x40
	v_and_b32_e32 v159, 48, v128
	v_or_b32_e32 v159, s90, v159
	v_and_b32_e32 v129, 31, v128
	v_lshrrev_b32_e32 v130, 5, v128
	v_bfe_u32 v131, v128, 1, 3
	v_lshlrev_b32_e32 v132, 7, v129
	s_lshr_b32 s91, s70, 7
	s_lshl_b32 s91, s91, 13
	s_lshl_b32 s90, s90, 8
	s_add_u32 s90, s90, 0x8000
	s_lshl_b32 s88, s70, 4
	s_mov_b32 s89, 0x10000
	s_lshl_b32 s92, s22, 4
	s_and_b32 s92, s92, 0x780
	s_mov_b32 s93, 0
	s_load_dwordx2 s[96:97], s[0:1], 0x158
	s_load_dwordx2 s[98:99], s[0:1], 0x108
	s_waitcnt lgkmcnt(0)
	v_subrev_u32_e32 v152, s96, v160
	v_xor_b32_e32 v152, v159, v152
	v_subrev_u32_e32 v153, s98, v180
	v_xor_b32_e32 v153, v159, v153
	v_subrev_u32_e32 v154, s96, v162
	v_xor_b32_e32 v154, v159, v154
	v_subrev_u32_e32 v155, s98, v182
	v_xor_b32_e32 v155, v159, v155
	v_subrev_u32_e32 v156, s96, v164
	v_xor_b32_e32 v156, v159, v156
	v_subrev_u32_e32 v157, s98, v184
	v_xor_b32_e32 v157, v159, v157
	v_subrev_u32_e32 v158, s96, v166
	v_xor_b32_e32 v158, v159, v158
	v_subrev_u32_e32 v168, s98, v186
	v_xor_b32_e32 v168, v159, v168
	v_xor_b32_e32 v133, v130, v131
	v_lshl_add_u32 v133, v133, 4, v132
	v_add_u32_e32 v230, s91, v133
	v_add_u32_e32 v234, s90, v133
	v_or_b32_e32 v133, 2, v130
	v_xor_b32_e32 v133, v133, v131
	v_lshl_add_u32 v133, v133, 4, v132
	v_add_u32_e32 v231, s91, v133
	v_add_u32_e32 v235, s90, v133
	v_or_b32_e32 v133, 4, v130
	v_xor_b32_e32 v133, v133, v131
	v_lshl_add_u32 v133, v133, 4, v132
	v_add_u32_e32 v232, s91, v133
	v_add_u32_e32 v236, s90, v133
	v_or_b32_e32 v133, 6, v130
	v_xor_b32_e32 v133, v133, v131
	v_lshl_add_u32 v133, v133, 4, v132
	v_add_u32_e32 v233, s91, v133
	v_add_u32_e32 v237, s90, v133
	s_barrier
	ds_read_b128 v[188:191], v230
	ds_read_b128 v[196:199], v234
	ds_read_b128 v[192:195], v230 offset:4096
	ds_read_b128 v[200:203], v234 offset:4096
	ds_read_b128 v[204:207], v234 offset:8192
	ds_read_b128 v[226:229], v234 offset:12288
	s_add_u32 s94, s2, s92
	s_add_u32 s94, s94, 0x80
	s_and_b32 s94, s94, 0x780
	s_sub_u32 s94, s94, 0x80
	s_subb_u32 s95, 0, 0
	s_add_u32 s100, s96, s94
	s_addc_u32 s101, s97, s95
	s_add_u32 s94, s98, s94
	s_addc_u32 s95, s99, s95
	s_add_u32 s90, s88, s89
	s_add_u32 m0, s90, 0
	s_nop 0
	global_load_lds_dwordx4 v152, s[100:101]
	s_add_u32 m0, s90, 32768
	s_nop 0
	global_load_lds_dwordx4 v153, s[94:95]
	s_add_u32 m0, s90, 8192
	s_nop 0
	global_load_lds_dwordx4 v154, s[100:101]
	s_add_u32 m0, s90, 40960
	s_nop 0
	global_load_lds_dwordx4 v155, s[94:95]
	s_add_u32 m0, s90, 16384
	s_nop 0
	global_load_lds_dwordx4 v156, s[100:101]
	s_add_u32 m0, s90, 49152
	s_nop 0
	global_load_lds_dwordx4 v157, s[94:95]
	s_add_u32 m0, s90, 24576
	s_nop 0
	global_load_lds_dwordx4 v158, s[100:101]
	s_add_u32 m0, s90, 57344
	s_nop 0
	global_load_lds_dwordx4 v168, s[94:95]
	s_xor_b32 s89, s89, 0x10000

.LBB0_4478:
	s_ashr_i32 s2, s54, 31
	s_lshr_b32 s2, s2, 30
	s_add_i32 s2, s54, s2
	s_ashr_i32 s2, s2, 2
	s_lshl_b32 s4, s2, 8
	v_add_u32_e32 v0, s4, v212
	v_min_i32_e32 v0, 0x7fff, v0
	v_ashrrev_i32_e32 v1, 31, v0
	s_lshl_b32 s6, s2, 10
	v_lshlrev_b64 v[0:1], 11, v[0:1]
	v_lshl_add_u64 v[160:161], v[176:177], 0, v[0:1]
	v_subrev_u32_e32 v0, s6, v220
	v_ashrrev_i32_e32 v1, 31, v0
	v_lshlrev_b64 v[0:1], 11, v[0:1]
	v_lshl_add_u64 v[180:181], v[178:179], 0, v[0:1]
	v_subrev_u32_e32 v0, s6, v221
	v_ashrrev_i32_e32 v1, 31, v0
	v_lshlrev_b64 v[0:1], 11, v[0:1]
	v_lshl_add_u64 v[182:183], v[178:179], 0, v[0:1]
	v_subrev_u32_e32 v0, s6, v222
	v_ashrrev_i32_e32 v1, 31, v0
	v_add_u32_e32 v2, s4, v213
	v_add_u32_e32 v4, s4, v171
	v_add_u32_e32 v6, s4, v215
	v_lshlrev_b64 v[0:1], 11, v[0:1]
	v_min_i32_e32 v2, 0x7fff, v2
	v_min_i32_e32 v4, 0x7fff, v4
	v_min_i32_e32 v6, 0x7fff, v6
	v_lshl_add_u64 v[184:185], v[178:179], 0, v[0:1]
	v_subrev_u32_e32 v0, s6, v223
	v_ashrrev_i32_e32 v3, 31, v2
	v_ashrrev_i32_e32 v5, 31, v4
	v_ashrrev_i32_e32 v7, 31, v6
	v_ashrrev_i32_e32 v1, 31, v0
	v_lshlrev_b64 v[2:3], 11, v[2:3]
	v_lshlrev_b64 v[4:5], 11, v[4:5]
	v_lshlrev_b64 v[6:7], 11, v[6:7]
	v_lshlrev_b64 v[0:1], 11, v[0:1]
	s_mov_b32 s5, s54
	v_lshl_add_u64 v[162:163], v[176:177], 0, v[2:3]
	v_lshl_add_u64 v[164:165], v[176:177], 0, v[4:5]
	v_lshl_add_u64 v[166:167], v[176:177], 0, v[6:7]
	v_lshl_add_u64 v[186:187], v[178:179], 0, v[0:1]
	s_mov_b64 s[2:3], 0
	s_mov_b32 s7, 0
	v_mov_b32_e32 v0, 0
	v_mov_b32_e32 v1, v169
	v_mov_b32_e32 v2, v169
	v_mov_b32_e32 v3, v169
	v_mov_b32_e32 v4, v169
	v_mov_b32_e32 v5, v169
	v_mov_b32_e32 v6, v169
	v_mov_b32_e32 v7, v169
	v_mov_b32_e32 v8, v169
	v_mov_b32_e32 v9, v169
	v_mov_b32_e32 v10, v169
	v_mov_b32_e32 v11, v169
	v_mov_b32_e32 v12, v169
	v_mov_b32_e32 v13, v169
	v_mov_b32_e32 v14, v169
	v_mov_b32_e32 v15, v169
	v_mov_b32_e32 v16, 0
	v_mov_b32_e32 v17, v169
	v_mov_b32_e32 v18, v169
	v_mov_b32_e32 v19, v169
	v_mov_b32_e32 v20, v169
	v_mov_b32_e32 v21, v169
	v_mov_b32_e32 v22, v169
	v_mov_b32_e32 v23, v169
	v_mov_b32_e32 v24, v169
	v_mov_b32_e32 v25, v169
	v_mov_b32_e32 v26, v169
	v_mov_b32_e32 v27, v169
	v_mov_b32_e32 v28, v169
	v_mov_b32_e32 v29, v169
	v_mov_b32_e32 v30, v169
	v_mov_b32_e32 v31, v169
	v_mov_b32_e32 v32, 0
	v_mov_b32_e32 v33, v169
	v_mov_b32_e32 v34, v169
	v_mov_b32_e32 v35, v169
	v_mov_b32_e32 v36, v169
	v_mov_b32_e32 v37, v169
	v_mov_b32_e32 v38, v169
	v_mov_b32_e32 v39, v169
	v_mov_b32_e32 v40, v169
	v_mov_b32_e32 v41, v169
	v_mov_b32_e32 v42, v169
	v_mov_b32_e32 v43, v169
	v_mov_b32_e32 v44, v169
	v_mov_b32_e32 v45, v169
	v_mov_b32_e32 v46, v169
	v_mov_b32_e32 v47, v169
	v_mov_b32_e32 v48, 0
	v_mov_b32_e32 v49, v169
	v_mov_b32_e32 v50, v169
	v_mov_b32_e32 v51, v169
	v_mov_b32_e32 v52, v169
	v_mov_b32_e32 v53, v169
	v_mov_b32_e32 v54, v169
	v_mov_b32_e32 v55, v169
	v_mov_b32_e32 v56, v169
	v_mov_b32_e32 v57, v169
	v_mov_b32_e32 v58, v169
	v_mov_b32_e32 v59, v169
	v_mov_b32_e32 v60, v169
	v_mov_b32_e32 v61, v169
	v_mov_b32_e32 v62, v169
	v_mov_b32_e32 v63, v169
	v_mov_b32_e32 v64, 0
	v_mov_b32_e32 v65, v169
	v_mov_b32_e32 v66, v169
	v_mov_b32_e32 v67, v169
	v_mov_b32_e32 v68, v169
	v_mov_b32_e32 v69, v169
	v_mov_b32_e32 v70, v169
	v_mov_b32_e32 v71, v169
	v_mov_b32_e32 v72, v169
	v_mov_b32_e32 v73, v169
	v_mov_b32_e32 v74, v169
	v_mov_b32_e32 v75, v169
	v_mov_b32_e32 v76, v169
	v_mov_b32_e32 v77, v169
	v_mov_b32_e32 v78, v169
	v_mov_b32_e32 v79, v169
	v_mov_b32_e32 v80, 0
	v_mov_b32_e32 v81, v169
	v_mov_b32_e32 v82, v169
	v_mov_b32_e32 v83, v169
	v_mov_b32_e32 v84, v169
	v_mov_b32_e32 v85, v169
	v_mov_b32_e32 v86, v169
	v_mov_b32_e32 v87, v169
	v_mov_b32_e32 v88, v169
	v_mov_b32_e32 v89, v169
	v_mov_b32_e32 v90, v169
	v_mov_b32_e32 v91, v169
	v_mov_b32_e32 v92, v169
	v_mov_b32_e32 v93, v169
	v_mov_b32_e32 v94, v169
	v_mov_b32_e32 v95, v169
	s_waitcnt vmcnt(7)
	v_mov_b32_e32 v96, 0
	v_mov_b32_e32 v97, v169
	v_mov_b32_e32 v98, v169
	v_mov_b32_e32 v99, v169
	s_waitcnt vmcnt(6)
	v_mov_b32_e32 v100, v169
	v_mov_b32_e32 v101, v169
	v_mov_b32_e32 v102, v169
	v_mov_b32_e32 v103, v169
	s_waitcnt vmcnt(5)
	v_mov_b32_e32 v104, v169
	v_mov_b32_e32 v105, v169
	v_mov_b32_e32 v106, v169
	v_mov_b32_e32 v107, v169
	s_waitcnt vmcnt(4)
	v_mov_b32_e32 v108, v169
	v_mov_b32_e32 v109, v169
	v_mov_b32_e32 v110, v169
	v_mov_b32_e32 v111, v169
	s_waitcnt vmcnt(3)
	v_mov_b32_e32 v112, 0
	v_mov_b32_e32 v113, v169
	v_mov_b32_e32 v114, v169
	v_mov_b32_e32 v115, v169
	s_waitcnt vmcnt(2)
	v_mov_b32_e32 v116, v169
	v_mov_b32_e32 v117, v169
	v_mov_b32_e32 v118, v169
	v_mov_b32_e32 v119, v169
	s_waitcnt vmcnt(1)
	v_mov_b32_e32 v120, v169
	v_mov_b32_e32 v121, v169
	v_mov_b32_e32 v122, v169
	v_mov_b32_e32 v123, v169
	s_waitcnt vmcnt(0)
	v_mov_b32_e32 v124, v169
	v_mov_b32_e32 v125, v169
	v_mov_b32_e32 v126, v169
	v_mov_b32_e32 v127, v169
	v_mbcnt_hi_u32_b32 v128, -1, v210
	s_and_b32 s90, s70, 0x40
	v_and_b32_e32 v159, 48, v128
	v_or_b32_e32 v159, s90, v159
	v_and_b32_e32 v129, 31, v128
	v_lshrrev_b32_e32 v130, 5, v128
	v_bfe_u32 v131, v128, 1, 3
	v_lshlrev_b32_e32 v132, 7, v129
	s_lshr_b32 s91, s70, 7
	s_lshl_b32 s91, s91, 13
	s_lshl_b32 s90, s90, 8
	s_add_u32 s90, s90, 0x8000
	s_lshl_b32 s88, s70, 4
	s_mov_b32 s89, 0x10000
	s_lshl_b32 s92, s22, 4
	s_and_b32 s92, s92, 0x780
	s_mov_b32 s93, 0
	s_load_dwordx2 s[96:97], s[0:1], 0x158
	s_load_dwordx2 s[98:99], s[0:1], 0x138
	s_waitcnt lgkmcnt(0)
	v_subrev_u32_e32 v152, s96, v160
	v_xor_b32_e32 v152, v159, v152
	v_subrev_u32_e32 v153, s98, v180
	v_xor_b32_e32 v153, v159, v153
	v_subrev_u32_e32 v154, s96, v162
	v_xor_b32_e32 v154, v159, v154
	v_subrev_u32_e32 v155, s98, v182
	v_xor_b32_e32 v155, v159, v155
	v_subrev_u32_e32 v156, s96, v164
	v_xor_b32_e32 v156, v159, v156
	v_subrev_u32_e32 v157, s98, v184
	v_xor_b32_e32 v157, v159, v157
	v_subrev_u32_e32 v158, s96, v166
	v_xor_b32_e32 v158, v159, v158
	v_subrev_u32_e32 v168, s98, v186
	v_xor_b32_e32 v168, v159, v168
	v_xor_b32_e32 v133, v130, v131
	v_lshl_add_u32 v133, v133, 4, v132
	v_add_u32_e32 v230, s91, v133
	v_add_u32_e32 v234, s90, v133
	v_or_b32_e32 v133, 2, v130
	v_xor_b32_e32 v133, v133, v131
	v_lshl_add_u32 v133, v133, 4, v132
	v_add_u32_e32 v231, s91, v133
	v_add_u32_e32 v235, s90, v133
	v_or_b32_e32 v133, 4, v130
	v_xor_b32_e32 v133, v133, v131
	v_lshl_add_u32 v133, v133, 4, v132
	v_add_u32_e32 v232, s91, v133
	v_add_u32_e32 v236, s90, v133
	v_or_b32_e32 v133, 6, v130
	v_xor_b32_e32 v133, v133, v131
	v_lshl_add_u32 v133, v133, 4, v132
	v_add_u32_e32 v233, s91, v133
	v_add_u32_e32 v237, s90, v133
	s_barrier
	ds_read_b128 v[188:191], v230
	ds_read_b128 v[196:199], v234
	ds_read_b128 v[192:195], v230 offset:4096
	ds_read_b128 v[200:203], v234 offset:4096
	ds_read_b128 v[204:207], v234 offset:8192
	ds_read_b128 v[226:229], v234 offset:12288
	s_add_u32 s94, s2, s92
	s_add_u32 s94, s94, 0x80
	s_and_b32 s94, s94, 0x780
	s_sub_u32 s94, s94, 0x80
	s_subb_u32 s95, 0, 0
	s_add_u32 s100, s96, s94
	s_addc_u32 s101, s97, s95
	s_add_u32 s94, s98, s94
	s_addc_u32 s95, s99, s95
	s_add_u32 s90, s88, s89
	s_add_u32 m0, s90, 0
	s_nop 0
	global_load_lds_dwordx4 v152, s[100:101]
	s_add_u32 m0, s90, 32768
	s_nop 0
	global_load_lds_dwordx4 v153, s[94:95]
	s_add_u32 m0, s90, 8192
	s_nop 0
	global_load_lds_dwordx4 v154, s[100:101]
	s_add_u32 m0, s90, 40960
	s_nop 0
	global_load_lds_dwordx4 v155, s[94:95]
	s_add_u32 m0, s90, 16384
	s_nop 0
	global_load_lds_dwordx4 v156, s[100:101]
	s_add_u32 m0, s90, 49152
	s_nop 0
	global_load_lds_dwordx4 v157, s[94:95]
	s_add_u32 m0, s90, 24576
	s_nop 0
	global_load_lds_dwordx4 v158, s[100:101]
	s_add_u32 m0, s90, 57344
	s_nop 0
	global_load_lds_dwordx4 v168, s[94:95]
	s_xor_b32 s89, s89, 0x10000

.LBB0_4668:
	s_mul_hi_i32 s5, s68, 0x2aaaaaab
	s_lshr_b32 s2, s5, 31
	s_add_i32 s5, s5, s2
	s_lshl_b32 s69, s5, 8
	s_waitcnt lgkmcnt(0)
	v_add_u32_e32 v0, s69, v189
	v_min_i32_e32 v0, 0x7fff, v0
	v_ashrrev_i32_e32 v1, 31, v0
	v_lshlrev_b64 v[0:1], 11, v[0:1]
	s_mul_i32 s2, s5, 0x600
	v_lshl_add_u64 v[172:173], v[168:169], 0, v[0:1]
	v_subrev_u32_e32 v0, s2, v200
	v_ashrrev_i32_e32 v1, 31, v0
	v_lshlrev_b64 v[0:1], 11, v[0:1]
	v_lshl_add_u64 v[180:181], v[170:171], 0, v[0:1]
	v_subrev_u32_e32 v0, s2, v201
	v_ashrrev_i32_e32 v1, 31, v0
	v_lshlrev_b64 v[0:1], 11, v[0:1]
	v_lshl_add_u64 v[182:183], v[170:171], 0, v[0:1]
	v_subrev_u32_e32 v0, s2, v202
	v_ashrrev_i32_e32 v1, 31, v0
	v_add_u32_e32 v2, s69, v190
	v_add_u32_e32 v4, s69, v163
	v_add_u32_e32 v6, s69, v192
	v_lshlrev_b64 v[0:1], 11, v[0:1]
	v_min_i32_e32 v2, 0x7fff, v2
	v_min_i32_e32 v4, 0x7fff, v4
	v_min_i32_e32 v6, 0x7fff, v6
	v_lshl_add_u64 v[184:185], v[170:171], 0, v[0:1]
	v_subrev_u32_e32 v0, s2, v203
	v_ashrrev_i32_e32 v3, 31, v2
	v_ashrrev_i32_e32 v5, 31, v4
	v_ashrrev_i32_e32 v7, 31, v6
	v_ashrrev_i32_e32 v1, 31, v0
	v_lshlrev_b64 v[2:3], 11, v[2:3]
	v_lshlrev_b64 v[4:5], 11, v[4:5]
	v_lshlrev_b64 v[6:7], 11, v[6:7]
	v_lshlrev_b64 v[0:1], 11, v[0:1]
	s_mov_b32 s4, s68
	v_lshl_add_u64 v[174:175], v[168:169], 0, v[2:3]
	v_lshl_add_u64 v[176:177], v[168:169], 0, v[4:5]
	v_lshl_add_u64 v[178:179], v[168:169], 0, v[6:7]
	v_lshl_add_u64 v[186:187], v[170:171], 0, v[0:1]
	s_mov_b64 s[2:3], 0
	s_mov_b32 s6, s25
	v_mov_b32_e32 v0, v161
	v_mov_b32_e32 v1, v161
	v_mov_b32_e32 v2, v161
	v_mov_b32_e32 v3, v161
	v_mov_b32_e32 v4, v161
	v_mov_b32_e32 v5, v161
	v_mov_b32_e32 v6, v161
	v_mov_b32_e32 v7, v161
	v_mov_b32_e32 v8, v161
	v_mov_b32_e32 v9, v161
	v_mov_b32_e32 v10, v161
	v_mov_b32_e32 v11, v161
	v_mov_b32_e32 v12, v161
	v_mov_b32_e32 v13, v161
	v_mov_b32_e32 v14, v161
	v_mov_b32_e32 v15, v161
	v_mov_b32_e32 v16, v161
	v_mov_b32_e32 v17, v161
	v_mov_b32_e32 v18, v161
	v_mov_b32_e32 v19, v161
	v_mov_b32_e32 v20, v161
	v_mov_b32_e32 v21, v161
	v_mov_b32_e32 v22, v161
	v_mov_b32_e32 v23, v161
	v_mov_b32_e32 v24, v161
	v_mov_b32_e32 v25, v161
	v_mov_b32_e32 v26, v161
	v_mov_b32_e32 v27, v161
	v_mov_b32_e32 v28, v161
	v_mov_b32_e32 v29, v161
	v_mov_b32_e32 v30, v161
	v_mov_b32_e32 v31, v161
	v_mov_b32_e32 v32, v161
	v_mov_b32_e32 v33, v161
	v_mov_b32_e32 v34, v161
	v_mov_b32_e32 v35, v161
	v_mov_b32_e32 v36, v161
	v_mov_b32_e32 v37, v161
	v_mov_b32_e32 v38, v161
	v_mov_b32_e32 v39, v161
	v_mov_b32_e32 v40, v161
	v_mov_b32_e32 v41, v161
	v_mov_b32_e32 v42, v161
	v_mov_b32_e32 v43, v161
	v_mov_b32_e32 v44, v161
	v_mov_b32_e32 v45, v161
	v_mov_b32_e32 v46, v161
	v_mov_b32_e32 v47, v161
	v_mov_b32_e32 v48, v161
	v_mov_b32_e32 v49, v161
	v_mov_b32_e32 v50, v161
	v_mov_b32_e32 v51, v161
	v_mov_b32_e32 v52, v161
	v_mov_b32_e32 v53, v161
	v_mov_b32_e32 v54, v161
	v_mov_b32_e32 v55, v161
	v_mov_b32_e32 v56, v161
	v_mov_b32_e32 v57, v161
	v_mov_b32_e32 v58, v161
	v_mov_b32_e32 v59, v161
	v_mov_b32_e32 v60, v161
	v_mov_b32_e32 v61, v161
	v_mov_b32_e32 v62, v161
	v_mov_b32_e32 v63, v161
	v_mov_b32_e32 v64, v161
	v_mov_b32_e32 v65, v161
	v_mov_b32_e32 v66, v161
	v_mov_b32_e32 v67, v161
	v_mov_b32_e32 v68, v161
	v_mov_b32_e32 v69, v161
	v_mov_b32_e32 v70, v161
	v_mov_b32_e32 v71, v161
	v_mov_b32_e32 v72, v161
	v_mov_b32_e32 v73, v161
	v_mov_b32_e32 v74, v161
	v_mov_b32_e32 v75, v161
	v_mov_b32_e32 v76, v161
	v_mov_b32_e32 v77, v161
	v_mov_b32_e32 v78, v161
	v_mov_b32_e32 v79, v161
	v_mov_b32_e32 v80, v161
	v_mov_b32_e32 v81, v161
	v_mov_b32_e32 v82, v161
	v_mov_b32_e32 v83, v161
	v_mov_b32_e32 v84, v161
	v_mov_b32_e32 v85, v161
	v_mov_b32_e32 v86, v161
	v_mov_b32_e32 v87, v161
	v_mov_b32_e32 v88, v161
	v_mov_b32_e32 v89, v161
	v_mov_b32_e32 v90, v161
	v_mov_b32_e32 v91, v161
	v_mov_b32_e32 v92, v161
	v_mov_b32_e32 v93, v161
	v_mov_b32_e32 v94, v161
	v_mov_b32_e32 v95, v161
	s_waitcnt vmcnt(7)
	v_mov_b32_e32 v96, v161
	v_mov_b32_e32 v97, v161
	v_mov_b32_e32 v98, v161
	v_mov_b32_e32 v99, v161
	s_waitcnt vmcnt(6)
	v_mov_b32_e32 v100, v161
	v_mov_b32_e32 v101, v161
	v_mov_b32_e32 v102, v161
	v_mov_b32_e32 v103, v161
	s_waitcnt vmcnt(5)
	v_mov_b32_e32 v104, v161
	v_mov_b32_e32 v105, v161
	v_mov_b32_e32 v106, v161
	v_mov_b32_e32 v107, v161
	s_waitcnt vmcnt(4)
	v_mov_b32_e32 v108, v161
	v_mov_b32_e32 v109, v161
	v_mov_b32_e32 v110, v161
	v_mov_b32_e32 v111, v161
	s_waitcnt vmcnt(3)
	v_mov_b32_e32 v112, v161
	v_mov_b32_e32 v113, v161
	v_mov_b32_e32 v114, v161
	v_mov_b32_e32 v115, v161
	s_waitcnt vmcnt(2)
	v_mov_b32_e32 v116, v161
	v_mov_b32_e32 v117, v161
	v_mov_b32_e32 v118, v161
	v_mov_b32_e32 v119, v161
	s_waitcnt vmcnt(1)
	v_mov_b32_e32 v120, v161
	v_mov_b32_e32 v121, v161
	v_mov_b32_e32 v122, v161
	v_mov_b32_e32 v123, v161
	s_waitcnt vmcnt(0)
	v_mov_b32_e32 v124, v161
	v_mov_b32_e32 v125, v161
	v_mov_b32_e32 v126, v161
	v_mov_b32_e32 v127, v161
	v_mbcnt_hi_u32_b32 v128, -1, v210
	s_and_b32 s90, s70, 0x40
	v_and_b32_e32 v159, 48, v128
	v_or_b32_e32 v159, s90, v159
	v_and_b32_e32 v129, 31, v128
	v_lshrrev_b32_e32 v130, 5, v128
	v_bfe_u32 v131, v128, 1, 3
	v_lshlrev_b32_e32 v132, 7, v129
	s_lshr_b32 s91, s70, 7
	s_lshl_b32 s91, s91, 13
	s_lshl_b32 s90, s90, 8
	s_add_u32 s90, s90, 0x8000
	s_lshl_b32 s88, s70, 4
	s_mov_b32 s89, 0x10000
	s_lshl_b32 s92, s22, 4
	s_and_b32 s92, s92, 0x780
	s_mov_b32 s93, 0
	s_load_dwordx2 s[96:97], s[0:1], 0x158
	s_load_dwordx2 s[98:99], s[0:1], 0xc8
	s_waitcnt lgkmcnt(0)
	v_subrev_u32_e32 v152, s96, v172
	v_xor_b32_e32 v152, v159, v152
	v_subrev_u32_e32 v153, s98, v180
	v_xor_b32_e32 v153, v159, v153
	v_subrev_u32_e32 v154, s96, v174
	v_xor_b32_e32 v154, v159, v154
	v_subrev_u32_e32 v155, s98, v182
	v_xor_b32_e32 v155, v159, v155
	v_subrev_u32_e32 v156, s96, v176
	v_xor_b32_e32 v156, v159, v156
	v_subrev_u32_e32 v157, s98, v184
	v_xor_b32_e32 v157, v159, v157
	v_subrev_u32_e32 v158, s96, v178
	v_xor_b32_e32 v158, v159, v158
	v_subrev_u32_e32 v160, s98, v186
	v_xor_b32_e32 v160, v159, v160
	v_xor_b32_e32 v133, v130, v131
	v_lshl_add_u32 v133, v133, 4, v132
	v_add_u32_e32 v232, s91, v133
	v_add_u32_e32 v236, s90, v133
	v_or_b32_e32 v133, 2, v130
	v_xor_b32_e32 v133, v133, v131
	v_lshl_add_u32 v133, v133, 4, v132
	v_add_u32_e32 v233, s91, v133
	v_add_u32_e32 v237, s90, v133
	v_or_b32_e32 v133, 4, v130
	v_xor_b32_e32 v133, v133, v131
	v_lshl_add_u32 v133, v133, 4, v132
	v_add_u32_e32 v234, s91, v133
	v_add_u32_e32 v238, s90, v133
	v_or_b32_e32 v133, 6, v130
	v_xor_b32_e32 v133, v133, v131
	v_lshl_add_u32 v133, v133, 4, v132
	v_add_u32_e32 v235, s91, v133
	v_add_u32_e32 v239, s90, v133
	s_barrier
	ds_read_b128 v[206:209], v232
	ds_read_b128 v[216:219], v236
	ds_read_b128 v[212:215], v232 offset:4096
	ds_read_b128 v[220:223], v236 offset:4096
	ds_read_b128 v[224:227], v236 offset:8192
	ds_read_b128 v[228:231], v236 offset:12288
	s_add_u32 s94, s2, s92
	s_add_u32 s94, s94, 0x80
	s_and_b32 s94, s94, 0x780
	s_sub_u32 s94, s94, 0x80
	s_subb_u32 s95, 0, 0
	s_add_u32 s100, s96, s94
	s_addc_u32 s101, s97, s95
	s_add_u32 s94, s98, s94
	s_addc_u32 s95, s99, s95
	s_add_u32 s90, s88, s89
	s_add_u32 m0, s90, 0
	s_nop 0
	global_load_lds_dwordx4 v152, s[100:101]
	s_add_u32 m0, s90, 32768
	s_nop 0
	global_load_lds_dwordx4 v153, s[94:95]
	s_add_u32 m0, s90, 8192
	s_nop 0
	global_load_lds_dwordx4 v154, s[100:101]
	s_add_u32 m0, s90, 40960
	s_nop 0
	global_load_lds_dwordx4 v155, s[94:95]
	s_add_u32 m0, s90, 16384
	s_nop 0
	global_load_lds_dwordx4 v156, s[100:101]
	s_add_u32 m0, s90, 49152
	s_nop 0
	global_load_lds_dwordx4 v157, s[94:95]
	s_add_u32 m0, s90, 24576
	s_nop 0
	global_load_lds_dwordx4 v158, s[100:101]
	s_add_u32 m0, s90, 57344
	s_nop 0
	global_load_lds_dwordx4 v160, s[94:95]
	s_xor_b32 s89, s89, 0x10000

.LBB0_5640:
	s_ashr_i32 s2, s54, 31
	s_lshr_b32 s2, s2, 30
	s_add_i32 s2, s54, s2
	s_ashr_i32 s2, s2, 2
	s_lshl_b32 s4, s2, 8
	v_add_u32_e32 v0, s4, v212
	v_min_i32_e32 v0, 0x7fff, v0
	v_ashrrev_i32_e32 v1, 31, v0
	s_lshl_b32 s6, s2, 10
	v_lshlrev_b64 v[0:1], 11, v[0:1]
	v_lshl_add_u64 v[160:161], v[176:177], 0, v[0:1]
	v_subrev_u32_e32 v0, s6, v220
	v_ashrrev_i32_e32 v1, 31, v0
	v_lshlrev_b64 v[0:1], 11, v[0:1]
	v_lshl_add_u64 v[180:181], v[178:179], 0, v[0:1]
	v_subrev_u32_e32 v0, s6, v221
	v_ashrrev_i32_e32 v1, 31, v0
	v_lshlrev_b64 v[0:1], 11, v[0:1]
	v_lshl_add_u64 v[182:183], v[178:179], 0, v[0:1]
	v_subrev_u32_e32 v0, s6, v222
	v_ashrrev_i32_e32 v1, 31, v0
	v_add_u32_e32 v2, s4, v213
	v_add_u32_e32 v4, s4, v171
	v_add_u32_e32 v6, s4, v215
	v_lshlrev_b64 v[0:1], 11, v[0:1]
	v_min_i32_e32 v2, 0x7fff, v2
	v_min_i32_e32 v4, 0x7fff, v4
	v_min_i32_e32 v6, 0x7fff, v6
	v_lshl_add_u64 v[184:185], v[178:179], 0, v[0:1]
	v_subrev_u32_e32 v0, s6, v223
	v_ashrrev_i32_e32 v3, 31, v2
	v_ashrrev_i32_e32 v5, 31, v4
	v_ashrrev_i32_e32 v7, 31, v6
	v_ashrrev_i32_e32 v1, 31, v0
	v_lshlrev_b64 v[2:3], 11, v[2:3]
	v_lshlrev_b64 v[4:5], 11, v[4:5]
	v_lshlrev_b64 v[6:7], 11, v[6:7]
	v_lshlrev_b64 v[0:1], 11, v[0:1]
	s_mov_b32 s5, s54
	v_lshl_add_u64 v[162:163], v[176:177], 0, v[2:3]
	v_lshl_add_u64 v[164:165], v[176:177], 0, v[4:5]
	v_lshl_add_u64 v[166:167], v[176:177], 0, v[6:7]
	v_lshl_add_u64 v[186:187], v[178:179], 0, v[0:1]
	s_mov_b64 s[2:3], 0
	s_mov_b32 s7, 0
	v_mov_b32_e32 v0, 0
	v_mov_b32_e32 v1, v169
	v_mov_b32_e32 v2, v169
	v_mov_b32_e32 v3, v169
	v_mov_b32_e32 v4, v169
	v_mov_b32_e32 v5, v169
	v_mov_b32_e32 v6, v169
	v_mov_b32_e32 v7, v169
	v_mov_b32_e32 v8, v169
	v_mov_b32_e32 v9, v169
	v_mov_b32_e32 v10, v169
	v_mov_b32_e32 v11, v169
	v_mov_b32_e32 v12, v169
	v_mov_b32_e32 v13, v169
	v_mov_b32_e32 v14, v169
	v_mov_b32_e32 v15, v169
	v_mov_b32_e32 v16, 0
	v_mov_b32_e32 v17, v169
	v_mov_b32_e32 v18, v169
	v_mov_b32_e32 v19, v169
	v_mov_b32_e32 v20, v169
	v_mov_b32_e32 v21, v169
	v_mov_b32_e32 v22, v169
	v_mov_b32_e32 v23, v169
	v_mov_b32_e32 v24, v169
	v_mov_b32_e32 v25, v169
	v_mov_b32_e32 v26, v169
	v_mov_b32_e32 v27, v169
	v_mov_b32_e32 v28, v169
	v_mov_b32_e32 v29, v169
	v_mov_b32_e32 v30, v169
	v_mov_b32_e32 v31, v169
	v_mov_b32_e32 v32, 0
	v_mov_b32_e32 v33, v169
	v_mov_b32_e32 v34, v169
	v_mov_b32_e32 v35, v169
	v_mov_b32_e32 v36, v169
	v_mov_b32_e32 v37, v169
	v_mov_b32_e32 v38, v169
	v_mov_b32_e32 v39, v169
	v_mov_b32_e32 v40, v169
	v_mov_b32_e32 v41, v169
	v_mov_b32_e32 v42, v169
	v_mov_b32_e32 v43, v169
	v_mov_b32_e32 v44, v169
	v_mov_b32_e32 v45, v169
	v_mov_b32_e32 v46, v169
	v_mov_b32_e32 v47, v169
	v_mov_b32_e32 v48, 0
	v_mov_b32_e32 v49, v169
	v_mov_b32_e32 v50, v169
	v_mov_b32_e32 v51, v169
	v_mov_b32_e32 v52, v169
	v_mov_b32_e32 v53, v169
	v_mov_b32_e32 v54, v169
	v_mov_b32_e32 v55, v169
	v_mov_b32_e32 v56, v169
	v_mov_b32_e32 v57, v169
	v_mov_b32_e32 v58, v169
	v_mov_b32_e32 v59, v169
	v_mov_b32_e32 v60, v169
	v_mov_b32_e32 v61, v169
	v_mov_b32_e32 v62, v169
	v_mov_b32_e32 v63, v169
	v_mov_b32_e32 v64, 0
	v_mov_b32_e32 v65, v169
	v_mov_b32_e32 v66, v169
	v_mov_b32_e32 v67, v169
	v_mov_b32_e32 v68, v169
	v_mov_b32_e32 v69, v169
	v_mov_b32_e32 v70, v169
	v_mov_b32_e32 v71, v169
	v_mov_b32_e32 v72, v169
	v_mov_b32_e32 v73, v169
	v_mov_b32_e32 v74, v169
	v_mov_b32_e32 v75, v169
	v_mov_b32_e32 v76, v169
	v_mov_b32_e32 v77, v169
	v_mov_b32_e32 v78, v169
	v_mov_b32_e32 v79, v169
	v_mov_b32_e32 v80, 0
	v_mov_b32_e32 v81, v169
	v_mov_b32_e32 v82, v169
	v_mov_b32_e32 v83, v169
	v_mov_b32_e32 v84, v169
	v_mov_b32_e32 v85, v169
	v_mov_b32_e32 v86, v169
	v_mov_b32_e32 v87, v169
	v_mov_b32_e32 v88, v169
	v_mov_b32_e32 v89, v169
	v_mov_b32_e32 v90, v169
	v_mov_b32_e32 v91, v169
	v_mov_b32_e32 v92, v169
	v_mov_b32_e32 v93, v169
	v_mov_b32_e32 v94, v169
	v_mov_b32_e32 v95, v169
	s_waitcnt vmcnt(7)
	v_mov_b32_e32 v96, 0
	v_mov_b32_e32 v97, v169
	v_mov_b32_e32 v98, v169
	v_mov_b32_e32 v99, v169
	s_waitcnt vmcnt(6)
	v_mov_b32_e32 v100, v169
	v_mov_b32_e32 v101, v169
	v_mov_b32_e32 v102, v169
	v_mov_b32_e32 v103, v169
	s_waitcnt vmcnt(5)
	v_mov_b32_e32 v104, v169
	v_mov_b32_e32 v105, v169
	v_mov_b32_e32 v106, v169
	v_mov_b32_e32 v107, v169
	s_waitcnt vmcnt(4)
	v_mov_b32_e32 v108, v169
	v_mov_b32_e32 v109, v169
	v_mov_b32_e32 v110, v169
	v_mov_b32_e32 v111, v169
	s_waitcnt vmcnt(3)
	v_mov_b32_e32 v112, 0
	v_mov_b32_e32 v113, v169
	v_mov_b32_e32 v114, v169
	v_mov_b32_e32 v115, v169
	s_waitcnt vmcnt(2)
	v_mov_b32_e32 v116, v169
	v_mov_b32_e32 v117, v169
	v_mov_b32_e32 v118, v169
	v_mov_b32_e32 v119, v169
	s_waitcnt vmcnt(1)
	v_mov_b32_e32 v120, v169
	v_mov_b32_e32 v121, v169
	v_mov_b32_e32 v122, v169
	v_mov_b32_e32 v123, v169
	s_waitcnt vmcnt(0)
	v_mov_b32_e32 v124, v169
	v_mov_b32_e32 v125, v169
	v_mov_b32_e32 v126, v169
	v_mov_b32_e32 v127, v169
	v_mbcnt_hi_u32_b32 v128, -1, v210
	s_and_b32 s90, s70, 0x40
	v_and_b32_e32 v159, 48, v128
	v_or_b32_e32 v159, s90, v159
	v_and_b32_e32 v129, 31, v128
	v_lshrrev_b32_e32 v130, 5, v128
	v_bfe_u32 v131, v128, 1, 3
	v_lshlrev_b32_e32 v132, 7, v129
	s_lshr_b32 s91, s70, 7
	s_lshl_b32 s91, s91, 13
	s_lshl_b32 s90, s90, 8
	s_add_u32 s90, s90, 0x8000
	s_lshl_b32 s88, s70, 4
	s_mov_b32 s89, 0x10000
	s_lshl_b32 s92, s22, 4
	s_and_b32 s92, s92, 0x780
	s_mov_b32 s93, 0
	s_load_dwordx2 s[96:97], s[0:1], 0x158
	s_load_dwordx2 s[98:99], s[0:1], 0xf8
	s_waitcnt lgkmcnt(0)
	v_subrev_u32_e32 v152, s96, v160
	v_xor_b32_e32 v152, v159, v152
	v_subrev_u32_e32 v153, s98, v180
	v_xor_b32_e32 v153, v159, v153
	v_subrev_u32_e32 v154, s96, v162
	v_xor_b32_e32 v154, v159, v154
	v_subrev_u32_e32 v155, s98, v182
	v_xor_b32_e32 v155, v159, v155
	v_subrev_u32_e32 v156, s96, v164
	v_xor_b32_e32 v156, v159, v156
	v_subrev_u32_e32 v157, s98, v184
	v_xor_b32_e32 v157, v159, v157
	v_subrev_u32_e32 v158, s96, v166
	v_xor_b32_e32 v158, v159, v158
	v_subrev_u32_e32 v168, s98, v186
	v_xor_b32_e32 v168, v159, v168
	v_xor_b32_e32 v133, v130, v131
	v_lshl_add_u32 v133, v133, 4, v132
	v_add_u32_e32 v230, s91, v133
	v_add_u32_e32 v234, s90, v133
	v_or_b32_e32 v133, 2, v130
	v_xor_b32_e32 v133, v133, v131
	v_lshl_add_u32 v133, v133, 4, v132
	v_add_u32_e32 v231, s91, v133
	v_add_u32_e32 v235, s90, v133
	v_or_b32_e32 v133, 4, v130
	v_xor_b32_e32 v133, v133, v131
	v_lshl_add_u32 v133, v133, 4, v132
	v_add_u32_e32 v232, s91, v133
	v_add_u32_e32 v236, s90, v133
	v_or_b32_e32 v133, 6, v130
	v_xor_b32_e32 v133, v133, v131
	v_lshl_add_u32 v133, v133, 4, v132
	v_add_u32_e32 v233, s91, v133
	v_add_u32_e32 v237, s90, v133
	s_barrier
	ds_read_b128 v[188:191], v230
	ds_read_b128 v[196:199], v234
	ds_read_b128 v[192:195], v230 offset:4096
	ds_read_b128 v[200:203], v234 offset:4096
	ds_read_b128 v[204:207], v234 offset:8192
	ds_read_b128 v[226:229], v234 offset:12288
	s_add_u32 s94, s2, s92
	s_add_u32 s94, s94, 0x80
	s_and_b32 s94, s94, 0x780
	s_sub_u32 s94, s94, 0x80
	s_subb_u32 s95, 0, 0
	s_add_u32 s100, s96, s94
	s_addc_u32 s101, s97, s95
	s_add_u32 s94, s98, s94
	s_addc_u32 s95, s99, s95
	s_add_u32 s90, s88, s89
	s_add_u32 m0, s90, 0
	s_nop 0
	global_load_lds_dwordx4 v152, s[100:101]
	s_add_u32 m0, s90, 32768
	s_nop 0
	global_load_lds_dwordx4 v153, s[94:95]
	s_add_u32 m0, s90, 8192
	s_nop 0
	global_load_lds_dwordx4 v154, s[100:101]
	s_add_u32 m0, s90, 40960
	s_nop 0
	global_load_lds_dwordx4 v155, s[94:95]
	s_add_u32 m0, s90, 16384
	s_nop 0
	global_load_lds_dwordx4 v156, s[100:101]
	s_add_u32 m0, s90, 49152
	s_nop 0
	global_load_lds_dwordx4 v157, s[94:95]
	s_add_u32 m0, s90, 24576
	s_nop 0
	global_load_lds_dwordx4 v158, s[100:101]
	s_add_u32 m0, s90, 57344
	s_nop 0
	global_load_lds_dwordx4 v168, s[94:95]
	s_xor_b32 s89, s89, 0x10000

	.amdhsa_kernel _Z4mega6Paramsii
		.amdhsa_group_segment_fixed_size 148496
		.amdhsa_private_segment_fixed_size 0
		.amdhsa_kernarg_size 808
		.amdhsa_user_sgpr_count 2
		.amdhsa_user_sgpr_dispatch_ptr 0
		.amdhsa_user_sgpr_queue_ptr 0
		.amdhsa_user_sgpr_kernarg_segment_ptr 1
		.amdhsa_user_sgpr_dispatch_id 0
		.amdhsa_user_sgpr_kernarg_preload_length 0
		.amdhsa_user_sgpr_kernarg_preload_offset 0
		.amdhsa_user_sgpr_private_segment_size 0
		.amdhsa_uses_dynamic_stack 0
		.amdhsa_enable_private_segment 0
		.amdhsa_system_sgpr_workgroup_id_x 1
		.amdhsa_system_sgpr_workgroup_id_y 0
		.amdhsa_system_sgpr_workgroup_id_z 0
		.amdhsa_system_sgpr_workgroup_info 0
		.amdhsa_system_vgpr_workitem_id 2
		.amdhsa_next_free_vgpr 256
		.amdhsa_next_free_sgpr 102
		.amdhsa_accum_offset 256
		.amdhsa_reserve_vcc 1
		.amdhsa_float_round_mode_32 0
		.amdhsa_float_round_mode_16_64 0
		.amdhsa_float_denorm_mode_32 3
		.amdhsa_float_denorm_mode_16_64 3
		.amdhsa_dx10_clamp 1
		.amdhsa_ieee_mode 1
		.amdhsa_fp16_overflow 0
		.amdhsa_tg_split 0
		.amdhsa_exception_fp_ieee_invalid_op 0
		.amdhsa_exception_fp_denorm_src 0
		.amdhsa_exception_fp_ieee_div_zero 0
		.amdhsa_exception_fp_ieee_overflow 0
		.amdhsa_exception_fp_ieee_underflow 0
		.amdhsa_exception_fp_ieee_inexact 0
		.amdhsa_exception_int_div_zero 0
	.end_amdhsa_kernel

amdhsa.kernels:
  - .agpr_count:     0
    .args:
      - .offset:         0
        .size:           544
        .value_kind:     by_value
      - .offset:         544
        .size:           4
        .value_kind:     by_value
      - .offset:         548
        .size:           4
        .value_kind:     by_value
      - .offset:         552
        .size:           4
        .value_kind:     hidden_block_count_x
      - .offset:         556
        .size:           4
        .value_kind:     hidden_block_count_y
      - .offset:         560
        .size:           4
        .value_kind:     hidden_block_count_z
      - .offset:         564
        .size:           2
        .value_kind:     hidden_group_size_x
      - .offset:         566
        .size:           2
        .value_kind:     hidden_group_size_y
      - .offset:         568
        .size:           2
        .value_kind:     hidden_group_size_z
      - .offset:         570
        .size:           2
        .value_kind:     hidden_remainder_x
      - .offset:         572
        .size:           2
        .value_kind:     hidden_remainder_y
      - .offset:         574
        .size:           2
        .value_kind:     hidden_remainder_z
      - .offset:         592
        .size:           8
        .value_kind:     hidden_global_offset_x
      - .offset:         600
        .size:           8
        .value_kind:     hidden_global_offset_y
      - .offset:         608
        .size:           8
        .value_kind:     hidden_global_offset_z
      - .offset:         616
        .size:           2
        .value_kind:     hidden_grid_dims
      - .offset:         640
        .size:           8
        .value_kind:     hidden_multigrid_sync_arg
    .group_segment_fixed_size: 148496
    .kernarg_segment_align: 8
    .kernarg_segment_size: 808
    .language:       OpenCL C
    .language_version:
      - 2
      - 0
    .max_flat_workgroup_size: 512
    .name:           _Z4mega6Paramsii
    .private_segment_fixed_size: 0
    .sgpr_count:     108
    .sgpr_spill_count: 0
    .symbol:         _Z4mega6Paramsii.kd
    .uniform_work_group_size: 1
    .uses_dynamic_stack: false
    .vgpr_count:     256
    .vgpr_spill_count: 0
    .wavefront_size: 64
